# v025 + P10 fast path also for the first chunk of each sequence (rows before the sequence start zeroed in registers, 1/min(t+1,w) as correctly rounded constants): no wave runs the serialized original l
# speedup vs baseline: 1.0186x; 1.0077x over previous
; __device__ __forceinline__ void pool_pass(const bf16* __restrict__ U, bf16* __restrict__ Y, int gtid, int gthreads) {
;     for (int task = gtid; task < BATCH * 128 * 128; task += gthreads) {
;         const int chg = task & 127, chunk = (task >> 7) & 127, b = task >> 14;
;         const int w = 2 << (chg >> 5);
;         const bf16* up = U + (size_t)b * SEQ * 1024 + chg * 8; bf16* yp = Y + (size_t)b * SEQ * 1024 + chg * 8;
;         const int t0 = chunk * 32;
;     ...
;             const float rc = 1.0f / (float)((t + 1 < w) ? (t + 1) : w);
.LBB0_931:
	s_cmp_eq_u64 exec, -1
	s_cbranch_scc0 .Lp10_slow
	v_readfirstlane_b32 s15, v155
	s_bfe_u32 s15, s15, 0x70007
	v_ashrrev_i32_e32 v0, 14, v155
	v_ashrrev_i32_e32 v1, 31, v0
	v_lshlrev_b64 v[0:1], 23, v[0:1]
	v_lshl_add_u64 v[22:23], v[18:19], 0, v[0:1]
	s_lshl_b32 s2, s15, 16
	s_mov_b32 s3, 0
	v_lshl_add_u64 v[2:3], v[22:23], 0, s[2:3]
	s_mov_b32 s16, 0x2000
	s_mov_b32 s17, 0
	s_mov_b32 s12, 0
	s_mov_b32 s13, -1
	s_mov_b64 vcc, s[12:13]
	v_ffbl_b32_e32 v4, v32
	v_lshlrev_b32_e32 v4, 23, v4
	v_sub_u32_e32 v24, 0x3f800000, v4
	s_cmp_eq_u32 s15, 0
	s_cselect_b32 s2, 1, 0
	v_readfirstlane_b32 s15, v32
	s_lshl_b32 s2, s2, 8
	s_or_b32 s15, s15, s2
	s_cmp_eq_u32 s15, 2
	s_cbranch_scc1 .Lp10_w2
	s_cmp_eq_u32 s15, 8
	s_cbranch_scc1 .Lp10_w8
	s_cmpk_eq_u32 s15, 0x102
	s_cbranch_scc1 .Lp10_w2f
	s_cmpk_eq_u32 s15, 0x108
	s_cbranch_scc1 .Lp10_w8f
	s_branch .Lp10_slow

; __device__ __forceinline__ unsigned cvtpk(float lo, float hi) { return pg8::cvt_pk_bf16(lo, hi); }
; __device__ __forceinline__ float bflo(unsigned u) { return __uint_as_float(u << 16); }
; __device__ __forceinline__ float bfhi(unsigned u) { return __uint_as_float(u & 0xffff0000u); }
; __device__ __forceinline__ void pool_pass(const bf16* __restrict__ U, bf16* __restrict__ Y, int gtid, int gthreads) {
;     ...
;         const bf16* up = U + (size_t)b * SEQ * 1024 + chg * 8; bf16* yp = Y + (size_t)b * SEQ * 1024 + chg * 8;
;         const int t0 = chunk * 32;
;         float sum[8];
; #pragma unroll
;         for (int j = 0; j < 8; ++j) sum[j] = 0.f;
;         for (int i = 1; i < w; ++i) { const int t = t0 - i; if (t >= 0) { const v4u v = *(const v4u*)(up + (size_t)t * 1024);
; #pragma unroll
;             for (int j = 0; j < 4; ++j) { sum[2 * j] += bflo(v[j]); sum[2 * j + 1] += bfhi(v[j]); } } }
; #pragma unroll 4
;         for (int t = t0; t < t0 + 32; ++t) {
;             const v4u v = *(const v4u*)(up + (size_t)t * 1024);
;             const int tb = t - w; v4u vb = {0u, 0u, 0u, 0u};
;             if (t > t0 && tb >= 0) vb = *(const v4u*)(up + (size_t)tb * 1024);
;             const float rc = 1.0f / (float)((t + 1 < w) ? (t + 1) : w);
;             v4u o;
; #pragma unroll
;             for (int j = 0; j < 4; ++j) { const float c0 = bflo(v[j]), c1 = bfhi(v[j]);
;                 sum[2 * j] += c0 - bflo(vb[j]); sum[2 * j + 1] += c1 - bfhi(vb[j]);
;                 o[j] = cvtpk(sum[2 * j] * rc - c0, sum[2 * j + 1] * rc - c1); }
;             __builtin_nontemporal_store(o, (v4u*)(yp + (size_t)t * 1024));
.Lp10_w2f:
	s_mov_b32 s2, 0xffff9800
	s_mov_b32 s3, -1
	v_lshl_add_u64 v[4:5], v[2:3], 0, s[2:3]
	v_lshl_add_u64 v[4:5], v[4:5], 0, s[16:17]
	v_lshl_add_u64 v[4:5], v[4:5], 0, s[16:17]
	v_lshl_add_u64 v[4:5], v[4:5], 0, s[16:17]
	global_load_dwordx4 v[100:103], v[4:5], off offset:2048
	v_lshl_add_u64 v[4:5], v[4:5], 0, s[16:17]
	global_load_dwordx4 v[104:107], v[4:5], off offset:-4096
	global_load_dwordx4 v[108:111], v[4:5], off offset:-2048
	global_load_dwordx4 v[112:115], v[4:5], off
	global_load_dwordx4 v[116:119], v[4:5], off offset:2048
	v_lshl_add_u64 v[4:5], v[4:5], 0, s[16:17]
	global_load_dwordx4 v[120:123], v[4:5], off offset:-4096
	global_load_dwordx4 v[124:127], v[4:5], off offset:-2048
	global_load_dwordx4 v[128:131], v[4:5], off
	global_load_dwordx4 v[132:135], v[4:5], off offset:2048
	v_lshl_add_u64 v[4:5], v[4:5], 0, s[16:17]
	global_load_dwordx4 v[136:139], v[4:5], off offset:-4096
	global_load_dwordx4 v[140:143], v[4:5], off offset:-2048
	global_load_dwordx4 v[144:147], v[4:5], off
	global_load_dwordx4 v[148:151], v[4:5], off offset:2048
	v_lshl_add_u64 v[4:5], v[4:5], 0, s[16:17]
	global_load_dwordx4 v[156:159], v[4:5], off offset:-4096
	global_load_dwordx4 v[160:163], v[4:5], off offset:-2048
	global_load_dwordx4 v[164:167], v[4:5], off
	global_load_dwordx4 v[168:171], v[4:5], off offset:2048
	v_lshl_add_u64 v[4:5], v[4:5], 0, s[16:17]
	global_load_dwordx4 v[172:175], v[4:5], off offset:-4096
	global_load_dwordx4 v[176:179], v[4:5], off offset:-2048
	global_load_dwordx4 v[180:183], v[4:5], off
	global_load_dwordx4 v[184:187], v[4:5], off offset:2048
	v_lshl_add_u64 v[4:5], v[4:5], 0, s[16:17]
	global_load_dwordx4 v[188:191], v[4:5], off offset:-4096
	global_load_dwordx4 v[192:195], v[4:5], off offset:-2048
	global_load_dwordx4 v[196:199], v[4:5], off
	global_load_dwordx4 v[200:203], v[4:5], off offset:2048
	v_lshl_add_u64 v[4:5], v[4:5], 0, s[16:17]
	global_load_dwordx4 v[204:207], v[4:5], off offset:-4096
	global_load_dwordx4 v[208:211], v[4:5], off offset:-2048
	global_load_dwordx4 v[212:215], v[4:5], off
	global_load_dwordx4 v[216:219], v[4:5], off offset:2048
	v_lshl_add_u64 v[4:5], v[4:5], 0, s[16:17]
	global_load_dwordx4 v[220:223], v[4:5], off offset:-4096
	global_load_dwordx4 v[224:227], v[4:5], off offset:-2048
	global_load_dwordx4 v[228:231], v[4:5], off
	s_mov_b32 s2, 0x8001000
	s_mov_b32 s3, 0
	v_lshl_add_u64 v[6:7], v[2:3], 0, s[2:3]
	v_mov_b32_e32 v26, 0
	v_mov_b32_e32 v27, 0
	v_mov_b32_e32 v28, 0
	v_mov_b32_e32 v29, 0
	v_mov_b32_e32 v30, 0
	v_mov_b32_e32 v31, 0
	v_mov_b32_e32 v8, 0
	v_mov_b32_e32 v9, 0
	v_mov_b32_e32 v96, 0
	v_mov_b32_e32 v97, 0
	v_mov_b32_e32 v98, 0
	v_mov_b32_e32 v99, 0
	v_mov_b32_e32 v92, 0
	v_mov_b32_e32 v93, 0
	v_mov_b32_e32 v94, 0
	v_mov_b32_e32 v95, 0
	v_mov_b32_e32 v88, 0
	v_mov_b32_e32 v89, 0
	v_mov_b32_e32 v90, 0
	v_mov_b32_e32 v91, 0
	s_mov_b64 exec, -1
	s_waitcnt vmcnt(31)
	v_mov_b32_e32 v24, 0x3f800000
	v_lshlrev_b32_e32 v10, 16, v100
	v_and_b32_e32 v11, 0xffff0000, v100
	v_pk_add_f32 v[26:27], v[26:27], v[10:11]
	v_pk_fma_f32 v[0:1], v[24:25], v[26:27], v[10:11] op_sel_hi:[0,1,1] neg_lo:[0,0,1] neg_hi:[0,0,1]
	v_cvt_pk_bf16_f32 v36, v0, v1
	v_lshlrev_b32_e32 v12, 16, v101
	v_and_b32_e32 v13, 0xffff0000, v101
	v_pk_add_f32 v[28:29], v[28:29], v[12:13]
	v_pk_fma_f32 v[0:1], v[24:25], v[28:29], v[12:13] op_sel_hi:[0,1,1] neg_lo:[0,0,1] neg_hi:[0,0,1]
	v_cvt_pk_bf16_f32 v37, v0, v1
	v_lshlrev_b32_e32 v14, 16, v102
	v_and_b32_e32 v15, 0xffff0000, v102
	v_pk_add_f32 v[30:31], v[30:31], v[14:15]
	v_pk_fma_f32 v[0:1], v[24:25], v[30:31], v[14:15] op_sel_hi:[0,1,1] neg_lo:[0,0,1] neg_hi:[0,0,1]
	v_cvt_pk_bf16_f32 v38, v0, v1
	v_lshlrev_b32_e32 v22, 16, v103
	v_and_b32_e32 v23, 0xffff0000, v103
	v_pk_add_f32 v[8:9], v[8:9], v[22:23]
	v_pk_fma_f32 v[0:1], v[24:25], v[8:9], v[22:23] op_sel_hi:[0,1,1] neg_lo:[0,0,1] neg_hi:[0,0,1]
	v_cvt_pk_bf16_f32 v39, v0, v1
	global_store_dwordx4 v[6:7], v[36:39], off offset:-4096 nt
	s_waitcnt vmcnt(31)
	v_mov_b32_e32 v24, 0x3f000000
	v_lshlrev_b32_e32 v10, 16, v104
	v_and_b32_e32 v11, 0xffff0000, v104
	v_cndmask_b32_e32 v35, v96, v88, vcc
	v_lshlrev_b32_e32 v0, 16, v35
	v_and_b32_e32 v1, 0xffff0000, v35
	v_pk_add_f32 v[0:1], v[10:11], v[0:1] neg_lo:[0,1] neg_hi:[0,1]
	v_pk_add_f32 v[26:27], v[26:27], v[0:1]
	v_pk_fma_f32 v[0:1], v[24:25], v[26:27], v[10:11] op_sel_hi:[0,1,1] neg_lo:[0,0,1] neg_hi:[0,0,1]
	v_cvt_pk_bf16_f32 v36, v0, v1
	v_lshlrev_b32_e32 v12, 16, v105
	v_and_b32_e32 v13, 0xffff0000, v105
	v_cndmask_b32_e32 v35, v97, v89, vcc
	v_lshlrev_b32_e32 v0, 16, v35
	v_and_b32_e32 v1, 0xffff0000, v35
	v_pk_add_f32 v[0:1], v[12:13], v[0:1] neg_lo:[0,1] neg_hi:[0,1]
	v_pk_add_f32 v[28:29], v[28:29], v[0:1]
	v_pk_fma_f32 v[0:1], v[24:25], v[28:29], v[12:13] op_sel_hi:[0,1,1] neg_lo:[0,0,1] neg_hi:[0,0,1]
	v_cvt_pk_bf16_f32 v37, v0, v1
	v_lshlrev_b32_e32 v14, 16, v106
	v_and_b32_e32 v15, 0xffff0000, v106
	v_cndmask_b32_e32 v35, v98, v90, vcc
	v_lshlrev_b32_e32 v0, 16, v35
	v_and_b32_e32 v1, 0xffff0000, v35
	v_pk_add_f32 v[0:1], v[14:15], v[0:1] neg_lo:[0,1] neg_hi:[0,1]
	v_pk_add_f32 v[30:31], v[30:31], v[0:1]
	v_pk_fma_f32 v[0:1], v[24:25], v[30:31], v[14:15] op_sel_hi:[0,1,1] neg_lo:[0,0,1] neg_hi:[0,0,1]
	v_cvt_pk_bf16_f32 v38, v0, v1
	v_lshlrev_b32_e32 v22, 16, v107
	v_and_b32_e32 v23, 0xffff0000, v107
	v_cndmask_b32_e32 v35, v99, v91, vcc
	v_lshlrev_b32_e32 v0, 16, v35
	v_and_b32_e32 v1, 0xffff0000, v35
	v_pk_add_f32 v[0:1], v[22:23], v[0:1] neg_lo:[0,1] neg_hi:[0,1]
	v_pk_add_f32 v[8:9], v[8:9], v[0:1]
	v_pk_fma_f32 v[0:1], v[24:25], v[8:9], v[22:23] op_sel_hi:[0,1,1] neg_lo:[0,0,1] neg_hi:[0,0,1]
	v_cvt_pk_bf16_f32 v39, v0, v1
	global_store_dwordx4 v[6:7], v[36:39], off offset:-2048 nt
	s_waitcnt vmcnt(31)
; __device__ __forceinline__ unsigned cvtpk(float lo, float hi) { return pg8::cvt_pk_bf16(lo, hi); }
; __device__ __forceinline__ float bflo(unsigned u) { return __uint_as_float(u << 16); }
; __device__ __forceinline__ float bfhi(unsigned u) { return __uint_as_float(u & 0xffff0000u); }
; __device__ __forceinline__ void pool_pass(const bf16* __restrict__ U, bf16* __restrict__ Y, int gtid, int gthreads) {
;     ...
;         for (int t = t0; t < t0 + 32; ++t) {
;             const v4u v = *(const v4u*)(up + (size_t)t * 1024);
;             const int tb = t - w; v4u vb = {0u, 0u, 0u, 0u};
;             if (t > t0 && tb >= 0) vb = *(const v4u*)(up + (size_t)tb * 1024);
;             const float rc = 1.0f / (float)((t + 1 < w) ? (t + 1) : w);
;             v4u o;
; #pragma unroll
;             for (int j = 0; j < 4; ++j) { const float c0 = bflo(v[j]), c1 = bfhi(v[j]);
;                 sum[2 * j] += c0 - bflo(vb[j]); sum[2 * j + 1] += c1 - bfhi(vb[j]);
;                 o[j] = cvtpk(sum[2 * j] * rc - c0, sum[2 * j + 1] * rc - c1); }
;             __builtin_nontemporal_store(o, (v4u*)(yp + (size_t)t * 1024));
	v_mov_b32_e32 v24, 0x3f000000
	s_mov_b64 exec, s[12:13]
	v_mov_b32_e32 v24, 0x3eaaaaab
	s_mov_b64 exec, -1
	v_lshlrev_b32_e32 v10, 16, v108
	v_and_b32_e32 v11, 0xffff0000, v108
	v_cndmask_b32_e32 v35, v100, v92, vcc
	v_lshlrev_b32_e32 v0, 16, v35
	v_and_b32_e32 v1, 0xffff0000, v35
	v_pk_add_f32 v[0:1], v[10:11], v[0:1] neg_lo:[0,1] neg_hi:[0,1]
	v_pk_add_f32 v[26:27], v[26:27], v[0:1]
	v_pk_fma_f32 v[0:1], v[24:25], v[26:27], v[10:11] op_sel_hi:[0,1,1] neg_lo:[0,0,1] neg_hi:[0,0,1]
	v_cvt_pk_bf16_f32 v36, v0, v1
	v_lshlrev_b32_e32 v12, 16, v109
	v_and_b32_e32 v13, 0xffff0000, v109
	v_cndmask_b32_e32 v35, v101, v93, vcc
	v_lshlrev_b32_e32 v0, 16, v35
	v_and_b32_e32 v1, 0xffff0000, v35
	v_pk_add_f32 v[0:1], v[12:13], v[0:1] neg_lo:[0,1] neg_hi:[0,1]
	v_pk_add_f32 v[28:29], v[28:29], v[0:1]
	v_pk_fma_f32 v[0:1], v[24:25], v[28:29], v[12:13] op_sel_hi:[0,1,1] neg_lo:[0,0,1] neg_hi:[0,0,1]
	v_cvt_pk_bf16_f32 v37, v0, v1
	v_lshlrev_b32_e32 v14, 16, v110
	v_and_b32_e32 v15, 0xffff0000, v110
	v_cndmask_b32_e32 v35, v102, v94, vcc
	v_lshlrev_b32_e32 v0, 16, v35
	v_and_b32_e32 v1, 0xffff0000, v35
	v_pk_add_f32 v[0:1], v[14:15], v[0:1] neg_lo:[0,1] neg_hi:[0,1]
	v_pk_add_f32 v[30:31], v[30:31], v[0:1]
	v_pk_fma_f32 v[0:1], v[24:25], v[30:31], v[14:15] op_sel_hi:[0,1,1] neg_lo:[0,0,1] neg_hi:[0,0,1]
	v_cvt_pk_bf16_f32 v38, v0, v1
	v_lshlrev_b32_e32 v22, 16, v111
	v_and_b32_e32 v23, 0xffff0000, v111
	v_cndmask_b32_e32 v35, v103, v95, vcc
	v_lshlrev_b32_e32 v0, 16, v35
	v_and_b32_e32 v1, 0xffff0000, v35
	v_pk_add_f32 v[0:1], v[22:23], v[0:1] neg_lo:[0,1] neg_hi:[0,1]
	v_pk_add_f32 v[8:9], v[8:9], v[0:1]
	v_pk_fma_f32 v[0:1], v[24:25], v[8:9], v[22:23] op_sel_hi:[0,1,1] neg_lo:[0,0,1] neg_hi:[0,0,1]
	v_cvt_pk_bf16_f32 v39, v0, v1
	global_store_dwordx4 v[6:7], v[36:39], off nt
	s_waitcnt vmcnt(31)
	v_mov_b32_e32 v24, 0x3f000000
	s_mov_b64 exec, s[12:13]
	v_mov_b32_e32 v24, 0x3e800000
	s_mov_b64 exec, -1
	v_lshlrev_b32_e32 v10, 16, v112
	v_and_b32_e32 v11, 0xffff0000, v112
	v_cndmask_b32_e32 v35, v104, v96, vcc
	v_lshlrev_b32_e32 v0, 16, v35
	v_and_b32_e32 v1, 0xffff0000, v35
	v_pk_add_f32 v[0:1], v[10:11], v[0:1] neg_lo:[0,1] neg_hi:[0,1]
	v_pk_add_f32 v[26:27], v[26:27], v[0:1]
	v_pk_fma_f32 v[0:1], v[24:25], v[26:27], v[10:11] op_sel_hi:[0,1,1] neg_lo:[0,0,1] neg_hi:[0,0,1]
	v_cvt_pk_bf16_f32 v36, v0, v1
	v_lshlrev_b32_e32 v12, 16, v113
	v_and_b32_e32 v13, 0xffff0000, v113
	v_cndmask_b32_e32 v35, v105, v97, vcc
	v_lshlrev_b32_e32 v0, 16, v35
	v_and_b32_e32 v1, 0xffff0000, v35
	v_pk_add_f32 v[0:1], v[12:13], v[0:1] neg_lo:[0,1] neg_hi:[0,1]
	v_pk_add_f32 v[28:29], v[28:29], v[0:1]
	v_pk_fma_f32 v[0:1], v[24:25], v[28:29], v[12:13] op_sel_hi:[0,1,1] neg_lo:[0,0,1] neg_hi:[0,0,1]
	v_cvt_pk_bf16_f32 v37, v0, v1
	v_lshlrev_b32_e32 v14, 16, v114
	v_and_b32_e32 v15, 0xffff0000, v114
	v_cndmask_b32_e32 v35, v106, v98, vcc
	v_lshlrev_b32_e32 v0, 16, v35
	v_and_b32_e32 v1, 0xffff0000, v35
	v_pk_add_f32 v[0:1], v[14:15], v[0:1] neg_lo:[0,1] neg_hi:[0,1]
	v_pk_add_f32 v[30:31], v[30:31], v[0:1]
	v_pk_fma_f32 v[0:1], v[24:25], v[30:31], v[14:15] op_sel_hi:[0,1,1] neg_lo:[0,0,1] neg_hi:[0,0,1]
	v_cvt_pk_bf16_f32 v38, v0, v1
	v_lshlrev_b32_e32 v22, 16, v115
	v_and_b32_e32 v23, 0xffff0000, v115
	v_cndmask_b32_e32 v35, v107, v99, vcc
	v_lshlrev_b32_e32 v0, 16, v35
	v_and_b32_e32 v1, 0xffff0000, v35
	v_pk_add_f32 v[0:1], v[22:23], v[0:1] neg_lo:[0,1] neg_hi:[0,1]
	v_pk_add_f32 v[8:9], v[8:9], v[0:1]
	v_pk_fma_f32 v[0:1], v[24:25], v[8:9], v[22:23] op_sel_hi:[0,1,1] neg_lo:[0,0,1] neg_hi:[0,0,1]
	v_cvt_pk_bf16_f32 v39, v0, v1
	global_store_dwordx4 v[6:7], v[36:39], off offset:2048 nt
	s_waitcnt vmcnt(31)
	v_lshlrev_b32_e32 v10, 16, v116
	v_and_b32_e32 v11, 0xffff0000, v116
	v_cndmask_b32_e32 v35, v108, v100, vcc
	v_lshlrev_b32_e32 v0, 16, v35
	v_and_b32_e32 v1, 0xffff0000, v35
	v_pk_add_f32 v[0:1], v[10:11], v[0:1] neg_lo:[0,1] neg_hi:[0,1]
	v_pk_add_f32 v[26:27], v[26:27], v[0:1]
	v_pk_fma_f32 v[0:1], v[24:25], v[26:27], v[10:11] op_sel_hi:[0,1,1] neg_lo:[0,0,1] neg_hi:[0,0,1]
	v_cvt_pk_bf16_f32 v36, v0, v1
	v_lshlrev_b32_e32 v12, 16, v117
	v_and_b32_e32 v13, 0xffff0000, v117
	v_cndmask_b32_e32 v35, v109, v101, vcc
	v_lshlrev_b32_e32 v0, 16, v35
	v_and_b32_e32 v1, 0xffff0000, v35
	v_pk_add_f32 v[0:1], v[12:13], v[0:1] neg_lo:[0,1] neg_hi:[0,1]
	v_pk_add_f32 v[28:29], v[28:29], v[0:1]
	v_pk_fma_f32 v[0:1], v[24:25], v[28:29], v[12:13] op_sel_hi:[0,1,1] neg_lo:[0,0,1] neg_hi:[0,0,1]
	v_cvt_pk_bf16_f32 v37, v0, v1
	v_lshlrev_b32_e32 v14, 16, v118
	v_and_b32_e32 v15, 0xffff0000, v118
	v_cndmask_b32_e32 v35, v110, v102, vcc
	v_lshlrev_b32_e32 v0, 16, v35
	v_and_b32_e32 v1, 0xffff0000, v35
	v_pk_add_f32 v[0:1], v[14:15], v[0:1] neg_lo:[0,1] neg_hi:[0,1]
	v_pk_add_f32 v[30:31], v[30:31], v[0:1]
	v_pk_fma_f32 v[0:1], v[24:25], v[30:31], v[14:15] op_sel_hi:[0,1,1] neg_lo:[0,0,1] neg_hi:[0,0,1]
	v_cvt_pk_bf16_f32 v38, v0, v1
	v_lshlrev_b32_e32 v22, 16, v119
	v_and_b32_e32 v23, 0xffff0000, v119
	v_cndmask_b32_e32 v35, v111, v103, vcc
	v_lshlrev_b32_e32 v0, 16, v35
	v_and_b32_e32 v1, 0xffff0000, v35
	v_pk_add_f32 v[0:1], v[22:23], v[0:1] neg_lo:[0,1] neg_hi:[0,1]
	v_pk_add_f32 v[8:9], v[8:9], v[0:1]
	v_pk_fma_f32 v[0:1], v[24:25], v[8:9], v[22:23] op_sel_hi:[0,1,1] neg_lo:[0,0,1] neg_hi:[0,0,1]
	v_cvt_pk_bf16_f32 v39, v0, v1
	v_lshl_add_u64 v[6:7], v[6:7], 0, s[16:17]
	global_store_dwordx4 v[6:7], v[36:39], off offset:-4096 nt
	s_waitcnt vmcnt(31)
; __device__ __forceinline__ unsigned cvtpk(float lo, float hi) { return pg8::cvt_pk_bf16(lo, hi); }
; __device__ __forceinline__ float bflo(unsigned u) { return __uint_as_float(u << 16); }
; __device__ __forceinline__ float bfhi(unsigned u) { return __uint_as_float(u & 0xffff0000u); }
; __device__ __forceinline__ void pool_pass(const bf16* __restrict__ U, bf16* __restrict__ Y, int gtid, int gthreads) {
;     ...
;         for (int t = t0; t < t0 + 32; ++t) {
;             const v4u v = *(const v4u*)(up + (size_t)t * 1024);
;             const int tb = t - w; v4u vb = {0u, 0u, 0u, 0u};
;             if (t > t0 && tb >= 0) vb = *(const v4u*)(up + (size_t)tb * 1024);
;             const float rc = 1.0f / (float)((t + 1 < w) ? (t + 1) : w);
;             v4u o;
; #pragma unroll
;             for (int j = 0; j < 4; ++j) { const float c0 = bflo(v[j]), c1 = bfhi(v[j]);
;                 sum[2 * j] += c0 - bflo(vb[j]); sum[2 * j + 1] += c1 - bfhi(vb[j]);
;                 o[j] = cvtpk(sum[2 * j] * rc - c0, sum[2 * j + 1] * rc - c1); }
;             __builtin_nontemporal_store(o, (v4u*)(yp + (size_t)t * 1024));
	v_lshlrev_b32_e32 v10, 16, v120
	v_and_b32_e32 v11, 0xffff0000, v120
	v_cndmask_b32_e32 v35, v112, v104, vcc
	v_lshlrev_b32_e32 v0, 16, v35
	v_and_b32_e32 v1, 0xffff0000, v35
	v_pk_add_f32 v[0:1], v[10:11], v[0:1] neg_lo:[0,1] neg_hi:[0,1]
	v_pk_add_f32 v[26:27], v[26:27], v[0:1]
	v_pk_fma_f32 v[0:1], v[24:25], v[26:27], v[10:11] op_sel_hi:[0,1,1] neg_lo:[0,0,1] neg_hi:[0,0,1]
	v_cvt_pk_bf16_f32 v36, v0, v1
	v_lshlrev_b32_e32 v12, 16, v121
	v_and_b32_e32 v13, 0xffff0000, v121
	v_cndmask_b32_e32 v35, v113, v105, vcc
	v_lshlrev_b32_e32 v0, 16, v35
	v_and_b32_e32 v1, 0xffff0000, v35
	v_pk_add_f32 v[0:1], v[12:13], v[0:1] neg_lo:[0,1] neg_hi:[0,1]
	v_pk_add_f32 v[28:29], v[28:29], v[0:1]
	v_pk_fma_f32 v[0:1], v[24:25], v[28:29], v[12:13] op_sel_hi:[0,1,1] neg_lo:[0,0,1] neg_hi:[0,0,1]
	v_cvt_pk_bf16_f32 v37, v0, v1
	v_lshlrev_b32_e32 v14, 16, v122
	v_and_b32_e32 v15, 0xffff0000, v122
	v_cndmask_b32_e32 v35, v114, v106, vcc
	v_lshlrev_b32_e32 v0, 16, v35
	v_and_b32_e32 v1, 0xffff0000, v35
	v_pk_add_f32 v[0:1], v[14:15], v[0:1] neg_lo:[0,1] neg_hi:[0,1]
	v_pk_add_f32 v[30:31], v[30:31], v[0:1]
	v_pk_fma_f32 v[0:1], v[24:25], v[30:31], v[14:15] op_sel_hi:[0,1,1] neg_lo:[0,0,1] neg_hi:[0,0,1]
	v_cvt_pk_bf16_f32 v38, v0, v1
	v_lshlrev_b32_e32 v22, 16, v123
	v_and_b32_e32 v23, 0xffff0000, v123
	v_cndmask_b32_e32 v35, v115, v107, vcc
	v_lshlrev_b32_e32 v0, 16, v35
	v_and_b32_e32 v1, 0xffff0000, v35
	v_pk_add_f32 v[0:1], v[22:23], v[0:1] neg_lo:[0,1] neg_hi:[0,1]
	v_pk_add_f32 v[8:9], v[8:9], v[0:1]
	v_pk_fma_f32 v[0:1], v[24:25], v[8:9], v[22:23] op_sel_hi:[0,1,1] neg_lo:[0,0,1] neg_hi:[0,0,1]
	v_cvt_pk_bf16_f32 v39, v0, v1
	global_store_dwordx4 v[6:7], v[36:39], off offset:-2048 nt
	s_waitcnt vmcnt(31)
	v_lshlrev_b32_e32 v10, 16, v124
	v_and_b32_e32 v11, 0xffff0000, v124
	v_cndmask_b32_e32 v35, v116, v108, vcc
	v_lshlrev_b32_e32 v0, 16, v35
	v_and_b32_e32 v1, 0xffff0000, v35
	v_pk_add_f32 v[0:1], v[10:11], v[0:1] neg_lo:[0,1] neg_hi:[0,1]
	v_pk_add_f32 v[26:27], v[26:27], v[0:1]
	v_pk_fma_f32 v[0:1], v[24:25], v[26:27], v[10:11] op_sel_hi:[0,1,1] neg_lo:[0,0,1] neg_hi:[0,0,1]
	v_cvt_pk_bf16_f32 v36, v0, v1
	v_lshlrev_b32_e32 v12, 16, v125
	v_and_b32_e32 v13, 0xffff0000, v125
	v_cndmask_b32_e32 v35, v117, v109, vcc
	v_lshlrev_b32_e32 v0, 16, v35
	v_and_b32_e32 v1, 0xffff0000, v35
	v_pk_add_f32 v[0:1], v[12:13], v[0:1] neg_lo:[0,1] neg_hi:[0,1]
	v_pk_add_f32 v[28:29], v[28:29], v[0:1]
	v_pk_fma_f32 v[0:1], v[24:25], v[28:29], v[12:13] op_sel_hi:[0,1,1] neg_lo:[0,0,1] neg_hi:[0,0,1]
	v_cvt_pk_bf16_f32 v37, v0, v1
	v_lshlrev_b32_e32 v14, 16, v126
	v_and_b32_e32 v15, 0xffff0000, v126
	v_cndmask_b32_e32 v35, v118, v110, vcc
	v_lshlrev_b32_e32 v0, 16, v35
	v_and_b32_e32 v1, 0xffff0000, v35
	v_pk_add_f32 v[0:1], v[14:15], v[0:1] neg_lo:[0,1] neg_hi:[0,1]
	v_pk_add_f32 v[30:31], v[30:31], v[0:1]
	v_pk_fma_f32 v[0:1], v[24:25], v[30:31], v[14:15] op_sel_hi:[0,1,1] neg_lo:[0,0,1] neg_hi:[0,0,1]
	v_cvt_pk_bf16_f32 v38, v0, v1
	v_lshlrev_b32_e32 v22, 16, v127
	v_and_b32_e32 v23, 0xffff0000, v127
	v_cndmask_b32_e32 v35, v119, v111, vcc
	v_lshlrev_b32_e32 v0, 16, v35
	v_and_b32_e32 v1, 0xffff0000, v35
	v_pk_add_f32 v[0:1], v[22:23], v[0:1] neg_lo:[0,1] neg_hi:[0,1]
	v_pk_add_f32 v[8:9], v[8:9], v[0:1]
	v_pk_fma_f32 v[0:1], v[24:25], v[8:9], v[22:23] op_sel_hi:[0,1,1] neg_lo:[0,0,1] neg_hi:[0,0,1]
	v_cvt_pk_bf16_f32 v39, v0, v1
	global_store_dwordx4 v[6:7], v[36:39], off nt
	s_waitcnt vmcnt(31)
	v_lshlrev_b32_e32 v10, 16, v128
	v_and_b32_e32 v11, 0xffff0000, v128
	v_cndmask_b32_e32 v35, v120, v112, vcc
	v_lshlrev_b32_e32 v0, 16, v35
	v_and_b32_e32 v1, 0xffff0000, v35
	v_pk_add_f32 v[0:1], v[10:11], v[0:1] neg_lo:[0,1] neg_hi:[0,1]
	v_pk_add_f32 v[26:27], v[26:27], v[0:1]
	v_pk_fma_f32 v[0:1], v[24:25], v[26:27], v[10:11] op_sel_hi:[0,1,1] neg_lo:[0,0,1] neg_hi:[0,0,1]
	v_cvt_pk_bf16_f32 v36, v0, v1
	v_lshlrev_b32_e32 v12, 16, v129
	v_and_b32_e32 v13, 0xffff0000, v129
	v_cndmask_b32_e32 v35, v121, v113, vcc
	v_lshlrev_b32_e32 v0, 16, v35
	v_and_b32_e32 v1, 0xffff0000, v35
	v_pk_add_f32 v[0:1], v[12:13], v[0:1] neg_lo:[0,1] neg_hi:[0,1]
	v_pk_add_f32 v[28:29], v[28:29], v[0:1]
	v_pk_fma_f32 v[0:1], v[24:25], v[28:29], v[12:13] op_sel_hi:[0,1,1] neg_lo:[0,0,1] neg_hi:[0,0,1]
	v_cvt_pk_bf16_f32 v37, v0, v1
	v_lshlrev_b32_e32 v14, 16, v130
	v_and_b32_e32 v15, 0xffff0000, v130
	v_cndmask_b32_e32 v35, v122, v114, vcc
	v_lshlrev_b32_e32 v0, 16, v35
	v_and_b32_e32 v1, 0xffff0000, v35
	v_pk_add_f32 v[0:1], v[14:15], v[0:1] neg_lo:[0,1] neg_hi:[0,1]
	v_pk_add_f32 v[30:31], v[30:31], v[0:1]
	v_pk_fma_f32 v[0:1], v[24:25], v[30:31], v[14:15] op_sel_hi:[0,1,1] neg_lo:[0,0,1] neg_hi:[0,0,1]
	v_cvt_pk_bf16_f32 v38, v0, v1
	v_lshlrev_b32_e32 v22, 16, v131
	v_and_b32_e32 v23, 0xffff0000, v131
	v_cndmask_b32_e32 v35, v123, v115, vcc
	v_lshlrev_b32_e32 v0, 16, v35
	v_and_b32_e32 v1, 0xffff0000, v35
	v_pk_add_f32 v[0:1], v[22:23], v[0:1] neg_lo:[0,1] neg_hi:[0,1]
	v_pk_add_f32 v[8:9], v[8:9], v[0:1]
	v_pk_fma_f32 v[0:1], v[24:25], v[8:9], v[22:23] op_sel_hi:[0,1,1] neg_lo:[0,0,1] neg_hi:[0,0,1]
	v_cvt_pk_bf16_f32 v39, v0, v1
	global_store_dwordx4 v[6:7], v[36:39], off offset:2048 nt
	s_waitcnt vmcnt(31)
; __device__ __forceinline__ unsigned cvtpk(float lo, float hi) { return pg8::cvt_pk_bf16(lo, hi); }
; __device__ __forceinline__ float bflo(unsigned u) { return __uint_as_float(u << 16); }
; __device__ __forceinline__ float bfhi(unsigned u) { return __uint_as_float(u & 0xffff0000u); }
; __device__ __forceinline__ void pool_pass(const bf16* __restrict__ U, bf16* __restrict__ Y, int gtid, int gthreads) {
;     ...
;         for (int t = t0; t < t0 + 32; ++t) {
;             const v4u v = *(const v4u*)(up + (size_t)t * 1024);
;             const int tb = t - w; v4u vb = {0u, 0u, 0u, 0u};
;             if (t > t0 && tb >= 0) vb = *(const v4u*)(up + (size_t)tb * 1024);
;             const float rc = 1.0f / (float)((t + 1 < w) ? (t + 1) : w);
;             v4u o;
; #pragma unroll
;             for (int j = 0; j < 4; ++j) { const float c0 = bflo(v[j]), c1 = bfhi(v[j]);
;                 sum[2 * j] += c0 - bflo(vb[j]); sum[2 * j + 1] += c1 - bfhi(vb[j]);
;                 o[j] = cvtpk(sum[2 * j] * rc - c0, sum[2 * j + 1] * rc - c1); }
;             __builtin_nontemporal_store(o, (v4u*)(yp + (size_t)t * 1024));
	v_lshlrev_b32_e32 v10, 16, v132
	v_and_b32_e32 v11, 0xffff0000, v132
	v_cndmask_b32_e32 v35, v124, v116, vcc
	v_lshlrev_b32_e32 v0, 16, v35
	v_and_b32_e32 v1, 0xffff0000, v35
	v_pk_add_f32 v[0:1], v[10:11], v[0:1] neg_lo:[0,1] neg_hi:[0,1]
	v_pk_add_f32 v[26:27], v[26:27], v[0:1]
	v_pk_fma_f32 v[0:1], v[24:25], v[26:27], v[10:11] op_sel_hi:[0,1,1] neg_lo:[0,0,1] neg_hi:[0,0,1]
	v_cvt_pk_bf16_f32 v36, v0, v1
	v_lshlrev_b32_e32 v12, 16, v133
	v_and_b32_e32 v13, 0xffff0000, v133
	v_cndmask_b32_e32 v35, v125, v117, vcc
	v_lshlrev_b32_e32 v0, 16, v35
	v_and_b32_e32 v1, 0xffff0000, v35
	v_pk_add_f32 v[0:1], v[12:13], v[0:1] neg_lo:[0,1] neg_hi:[0,1]
	v_pk_add_f32 v[28:29], v[28:29], v[0:1]
	v_pk_fma_f32 v[0:1], v[24:25], v[28:29], v[12:13] op_sel_hi:[0,1,1] neg_lo:[0,0,1] neg_hi:[0,0,1]
	v_cvt_pk_bf16_f32 v37, v0, v1
	v_lshlrev_b32_e32 v14, 16, v134
	v_and_b32_e32 v15, 0xffff0000, v134
	v_cndmask_b32_e32 v35, v126, v118, vcc
	v_lshlrev_b32_e32 v0, 16, v35
	v_and_b32_e32 v1, 0xffff0000, v35
	v_pk_add_f32 v[0:1], v[14:15], v[0:1] neg_lo:[0,1] neg_hi:[0,1]
	v_pk_add_f32 v[30:31], v[30:31], v[0:1]
	v_pk_fma_f32 v[0:1], v[24:25], v[30:31], v[14:15] op_sel_hi:[0,1,1] neg_lo:[0,0,1] neg_hi:[0,0,1]
	v_cvt_pk_bf16_f32 v38, v0, v1
	v_lshlrev_b32_e32 v22, 16, v135
	v_and_b32_e32 v23, 0xffff0000, v135
	v_cndmask_b32_e32 v35, v127, v119, vcc
	v_lshlrev_b32_e32 v0, 16, v35
	v_and_b32_e32 v1, 0xffff0000, v35
	v_pk_add_f32 v[0:1], v[22:23], v[0:1] neg_lo:[0,1] neg_hi:[0,1]
	v_pk_add_f32 v[8:9], v[8:9], v[0:1]
	v_pk_fma_f32 v[0:1], v[24:25], v[8:9], v[22:23] op_sel_hi:[0,1,1] neg_lo:[0,0,1] neg_hi:[0,0,1]
	v_cvt_pk_bf16_f32 v39, v0, v1
	v_lshl_add_u64 v[6:7], v[6:7], 0, s[16:17]
	global_store_dwordx4 v[6:7], v[36:39], off offset:-4096 nt
	s_waitcnt vmcnt(31)
	v_lshlrev_b32_e32 v10, 16, v136
	v_and_b32_e32 v11, 0xffff0000, v136
	v_cndmask_b32_e32 v35, v128, v120, vcc
	v_lshlrev_b32_e32 v0, 16, v35
	v_and_b32_e32 v1, 0xffff0000, v35
	v_pk_add_f32 v[0:1], v[10:11], v[0:1] neg_lo:[0,1] neg_hi:[0,1]
	v_pk_add_f32 v[26:27], v[26:27], v[0:1]
	v_pk_fma_f32 v[0:1], v[24:25], v[26:27], v[10:11] op_sel_hi:[0,1,1] neg_lo:[0,0,1] neg_hi:[0,0,1]
	v_cvt_pk_bf16_f32 v36, v0, v1
	v_lshlrev_b32_e32 v12, 16, v137
	v_and_b32_e32 v13, 0xffff0000, v137
	v_cndmask_b32_e32 v35, v129, v121, vcc
	v_lshlrev_b32_e32 v0, 16, v35
	v_and_b32_e32 v1, 0xffff0000, v35
	v_pk_add_f32 v[0:1], v[12:13], v[0:1] neg_lo:[0,1] neg_hi:[0,1]
	v_pk_add_f32 v[28:29], v[28:29], v[0:1]
	v_pk_fma_f32 v[0:1], v[24:25], v[28:29], v[12:13] op_sel_hi:[0,1,1] neg_lo:[0,0,1] neg_hi:[0,0,1]
	v_cvt_pk_bf16_f32 v37, v0, v1
	v_lshlrev_b32_e32 v14, 16, v138
	v_and_b32_e32 v15, 0xffff0000, v138
	v_cndmask_b32_e32 v35, v130, v122, vcc
	v_lshlrev_b32_e32 v0, 16, v35
	v_and_b32_e32 v1, 0xffff0000, v35
	v_pk_add_f32 v[0:1], v[14:15], v[0:1] neg_lo:[0,1] neg_hi:[0,1]
	v_pk_add_f32 v[30:31], v[30:31], v[0:1]
	v_pk_fma_f32 v[0:1], v[24:25], v[30:31], v[14:15] op_sel_hi:[0,1,1] neg_lo:[0,0,1] neg_hi:[0,0,1]
	v_cvt_pk_bf16_f32 v38, v0, v1
	v_lshlrev_b32_e32 v22, 16, v139
	v_and_b32_e32 v23, 0xffff0000, v139
	v_cndmask_b32_e32 v35, v131, v123, vcc
	v_lshlrev_b32_e32 v0, 16, v35
	v_and_b32_e32 v1, 0xffff0000, v35
	v_pk_add_f32 v[0:1], v[22:23], v[0:1] neg_lo:[0,1] neg_hi:[0,1]
	v_pk_add_f32 v[8:9], v[8:9], v[0:1]
	v_pk_fma_f32 v[0:1], v[24:25], v[8:9], v[22:23] op_sel_hi:[0,1,1] neg_lo:[0,0,1] neg_hi:[0,0,1]
	v_cvt_pk_bf16_f32 v39, v0, v1
	global_store_dwordx4 v[6:7], v[36:39], off offset:-2048 nt
	s_waitcnt vmcnt(31)
	v_lshlrev_b32_e32 v10, 16, v140
	v_and_b32_e32 v11, 0xffff0000, v140
	v_cndmask_b32_e32 v35, v132, v124, vcc
	v_lshlrev_b32_e32 v0, 16, v35
	v_and_b32_e32 v1, 0xffff0000, v35
	v_pk_add_f32 v[0:1], v[10:11], v[0:1] neg_lo:[0,1] neg_hi:[0,1]
	v_pk_add_f32 v[26:27], v[26:27], v[0:1]
	v_pk_fma_f32 v[0:1], v[24:25], v[26:27], v[10:11] op_sel_hi:[0,1,1] neg_lo:[0,0,1] neg_hi:[0,0,1]
	v_cvt_pk_bf16_f32 v36, v0, v1
	v_lshlrev_b32_e32 v12, 16, v141
	v_and_b32_e32 v13, 0xffff0000, v141
	v_cndmask_b32_e32 v35, v133, v125, vcc
	v_lshlrev_b32_e32 v0, 16, v35
	v_and_b32_e32 v1, 0xffff0000, v35
	v_pk_add_f32 v[0:1], v[12:13], v[0:1] neg_lo:[0,1] neg_hi:[0,1]
	v_pk_add_f32 v[28:29], v[28:29], v[0:1]
	v_pk_fma_f32 v[0:1], v[24:25], v[28:29], v[12:13] op_sel_hi:[0,1,1] neg_lo:[0,0,1] neg_hi:[0,0,1]
	v_cvt_pk_bf16_f32 v37, v0, v1
	v_lshlrev_b32_e32 v14, 16, v142
	v_and_b32_e32 v15, 0xffff0000, v142
	v_cndmask_b32_e32 v35, v134, v126, vcc
	v_lshlrev_b32_e32 v0, 16, v35
	v_and_b32_e32 v1, 0xffff0000, v35
	v_pk_add_f32 v[0:1], v[14:15], v[0:1] neg_lo:[0,1] neg_hi:[0,1]
	v_pk_add_f32 v[30:31], v[30:31], v[0:1]
	v_pk_fma_f32 v[0:1], v[24:25], v[30:31], v[14:15] op_sel_hi:[0,1,1] neg_lo:[0,0,1] neg_hi:[0,0,1]
	v_cvt_pk_bf16_f32 v38, v0, v1
	v_lshlrev_b32_e32 v22, 16, v143
	v_and_b32_e32 v23, 0xffff0000, v143
	v_cndmask_b32_e32 v35, v135, v127, vcc
	v_lshlrev_b32_e32 v0, 16, v35
	v_and_b32_e32 v1, 0xffff0000, v35
	v_pk_add_f32 v[0:1], v[22:23], v[0:1] neg_lo:[0,1] neg_hi:[0,1]
	v_pk_add_f32 v[8:9], v[8:9], v[0:1]
	v_pk_fma_f32 v[0:1], v[24:25], v[8:9], v[22:23] op_sel_hi:[0,1,1] neg_lo:[0,0,1] neg_hi:[0,0,1]
	v_cvt_pk_bf16_f32 v39, v0, v1
	global_store_dwordx4 v[6:7], v[36:39], off nt
	s_waitcnt vmcnt(31)
; __device__ __forceinline__ unsigned cvtpk(float lo, float hi) { return pg8::cvt_pk_bf16(lo, hi); }
; __device__ __forceinline__ float bflo(unsigned u) { return __uint_as_float(u << 16); }
; __device__ __forceinline__ float bfhi(unsigned u) { return __uint_as_float(u & 0xffff0000u); }
; __device__ __forceinline__ void pool_pass(const bf16* __restrict__ U, bf16* __restrict__ Y, int gtid, int gthreads) {
;     ...
;         for (int t = t0; t < t0 + 32; ++t) {
;             const v4u v = *(const v4u*)(up + (size_t)t * 1024);
;             const int tb = t - w; v4u vb = {0u, 0u, 0u, 0u};
;             if (t > t0 && tb >= 0) vb = *(const v4u*)(up + (size_t)tb * 1024);
;             const float rc = 1.0f / (float)((t + 1 < w) ? (t + 1) : w);
;             v4u o;
; #pragma unroll
;             for (int j = 0; j < 4; ++j) { const float c0 = bflo(v[j]), c1 = bfhi(v[j]);
;                 sum[2 * j] += c0 - bflo(vb[j]); sum[2 * j + 1] += c1 - bfhi(vb[j]);
;                 o[j] = cvtpk(sum[2 * j] * rc - c0, sum[2 * j + 1] * rc - c1); }
;             __builtin_nontemporal_store(o, (v4u*)(yp + (size_t)t * 1024));
	v_lshlrev_b32_e32 v10, 16, v144
	v_and_b32_e32 v11, 0xffff0000, v144
	v_cndmask_b32_e32 v35, v136, v128, vcc
	v_lshlrev_b32_e32 v0, 16, v35
	v_and_b32_e32 v1, 0xffff0000, v35
	v_pk_add_f32 v[0:1], v[10:11], v[0:1] neg_lo:[0,1] neg_hi:[0,1]
	v_pk_add_f32 v[26:27], v[26:27], v[0:1]
	v_pk_fma_f32 v[0:1], v[24:25], v[26:27], v[10:11] op_sel_hi:[0,1,1] neg_lo:[0,0,1] neg_hi:[0,0,1]
	v_cvt_pk_bf16_f32 v36, v0, v1
	v_lshlrev_b32_e32 v12, 16, v145
	v_and_b32_e32 v13, 0xffff0000, v145
	v_cndmask_b32_e32 v35, v137, v129, vcc
	v_lshlrev_b32_e32 v0, 16, v35
	v_and_b32_e32 v1, 0xffff0000, v35
	v_pk_add_f32 v[0:1], v[12:13], v[0:1] neg_lo:[0,1] neg_hi:[0,1]
	v_pk_add_f32 v[28:29], v[28:29], v[0:1]
	v_pk_fma_f32 v[0:1], v[24:25], v[28:29], v[12:13] op_sel_hi:[0,1,1] neg_lo:[0,0,1] neg_hi:[0,0,1]
	v_cvt_pk_bf16_f32 v37, v0, v1
	v_lshlrev_b32_e32 v14, 16, v146
	v_and_b32_e32 v15, 0xffff0000, v146
	v_cndmask_b32_e32 v35, v138, v130, vcc
	v_lshlrev_b32_e32 v0, 16, v35
	v_and_b32_e32 v1, 0xffff0000, v35
	v_pk_add_f32 v[0:1], v[14:15], v[0:1] neg_lo:[0,1] neg_hi:[0,1]
	v_pk_add_f32 v[30:31], v[30:31], v[0:1]
	v_pk_fma_f32 v[0:1], v[24:25], v[30:31], v[14:15] op_sel_hi:[0,1,1] neg_lo:[0,0,1] neg_hi:[0,0,1]
	v_cvt_pk_bf16_f32 v38, v0, v1
	v_lshlrev_b32_e32 v22, 16, v147
	v_and_b32_e32 v23, 0xffff0000, v147
	v_cndmask_b32_e32 v35, v139, v131, vcc
	v_lshlrev_b32_e32 v0, 16, v35
	v_and_b32_e32 v1, 0xffff0000, v35
	v_pk_add_f32 v[0:1], v[22:23], v[0:1] neg_lo:[0,1] neg_hi:[0,1]
	v_pk_add_f32 v[8:9], v[8:9], v[0:1]
	v_pk_fma_f32 v[0:1], v[24:25], v[8:9], v[22:23] op_sel_hi:[0,1,1] neg_lo:[0,0,1] neg_hi:[0,0,1]
	v_cvt_pk_bf16_f32 v39, v0, v1
	global_store_dwordx4 v[6:7], v[36:39], off offset:2048 nt
	s_waitcnt vmcnt(31)
	v_lshlrev_b32_e32 v10, 16, v148
	v_and_b32_e32 v11, 0xffff0000, v148
	v_cndmask_b32_e32 v35, v140, v132, vcc
	v_lshlrev_b32_e32 v0, 16, v35
	v_and_b32_e32 v1, 0xffff0000, v35
	v_pk_add_f32 v[0:1], v[10:11], v[0:1] neg_lo:[0,1] neg_hi:[0,1]
	v_pk_add_f32 v[26:27], v[26:27], v[0:1]
	v_pk_fma_f32 v[0:1], v[24:25], v[26:27], v[10:11] op_sel_hi:[0,1,1] neg_lo:[0,0,1] neg_hi:[0,0,1]
	v_cvt_pk_bf16_f32 v36, v0, v1
	v_lshlrev_b32_e32 v12, 16, v149
	v_and_b32_e32 v13, 0xffff0000, v149
	v_cndmask_b32_e32 v35, v141, v133, vcc
	v_lshlrev_b32_e32 v0, 16, v35
	v_and_b32_e32 v1, 0xffff0000, v35
	v_pk_add_f32 v[0:1], v[12:13], v[0:1] neg_lo:[0,1] neg_hi:[0,1]
	v_pk_add_f32 v[28:29], v[28:29], v[0:1]
	v_pk_fma_f32 v[0:1], v[24:25], v[28:29], v[12:13] op_sel_hi:[0,1,1] neg_lo:[0,0,1] neg_hi:[0,0,1]
	v_cvt_pk_bf16_f32 v37, v0, v1
	v_lshlrev_b32_e32 v14, 16, v150
	v_and_b32_e32 v15, 0xffff0000, v150
	v_cndmask_b32_e32 v35, v142, v134, vcc
	v_lshlrev_b32_e32 v0, 16, v35
	v_and_b32_e32 v1, 0xffff0000, v35
	v_pk_add_f32 v[0:1], v[14:15], v[0:1] neg_lo:[0,1] neg_hi:[0,1]
	v_pk_add_f32 v[30:31], v[30:31], v[0:1]
	v_pk_fma_f32 v[0:1], v[24:25], v[30:31], v[14:15] op_sel_hi:[0,1,1] neg_lo:[0,0,1] neg_hi:[0,0,1]
	v_cvt_pk_bf16_f32 v38, v0, v1
	v_lshlrev_b32_e32 v22, 16, v151
	v_and_b32_e32 v23, 0xffff0000, v151
	v_cndmask_b32_e32 v35, v143, v135, vcc
	v_lshlrev_b32_e32 v0, 16, v35
	v_and_b32_e32 v1, 0xffff0000, v35
	v_pk_add_f32 v[0:1], v[22:23], v[0:1] neg_lo:[0,1] neg_hi:[0,1]
	v_pk_add_f32 v[8:9], v[8:9], v[0:1]
	v_pk_fma_f32 v[0:1], v[24:25], v[8:9], v[22:23] op_sel_hi:[0,1,1] neg_lo:[0,0,1] neg_hi:[0,0,1]
	v_cvt_pk_bf16_f32 v39, v0, v1
	v_lshl_add_u64 v[6:7], v[6:7], 0, s[16:17]
	global_store_dwordx4 v[6:7], v[36:39], off offset:-4096 nt
	s_waitcnt vmcnt(31)
	v_lshlrev_b32_e32 v10, 16, v156
	v_and_b32_e32 v11, 0xffff0000, v156
	v_cndmask_b32_e32 v35, v144, v136, vcc
	v_lshlrev_b32_e32 v0, 16, v35
	v_and_b32_e32 v1, 0xffff0000, v35
	v_pk_add_f32 v[0:1], v[10:11], v[0:1] neg_lo:[0,1] neg_hi:[0,1]
	v_pk_add_f32 v[26:27], v[26:27], v[0:1]
	v_pk_fma_f32 v[0:1], v[24:25], v[26:27], v[10:11] op_sel_hi:[0,1,1] neg_lo:[0,0,1] neg_hi:[0,0,1]
	v_cvt_pk_bf16_f32 v36, v0, v1
	v_lshlrev_b32_e32 v12, 16, v157
	v_and_b32_e32 v13, 0xffff0000, v157
	v_cndmask_b32_e32 v35, v145, v137, vcc
	v_lshlrev_b32_e32 v0, 16, v35
	v_and_b32_e32 v1, 0xffff0000, v35
	v_pk_add_f32 v[0:1], v[12:13], v[0:1] neg_lo:[0,1] neg_hi:[0,1]
	v_pk_add_f32 v[28:29], v[28:29], v[0:1]
	v_pk_fma_f32 v[0:1], v[24:25], v[28:29], v[12:13] op_sel_hi:[0,1,1] neg_lo:[0,0,1] neg_hi:[0,0,1]
	v_cvt_pk_bf16_f32 v37, v0, v1
	v_lshlrev_b32_e32 v14, 16, v158
	v_and_b32_e32 v15, 0xffff0000, v158
	v_cndmask_b32_e32 v35, v146, v138, vcc
	v_lshlrev_b32_e32 v0, 16, v35
	v_and_b32_e32 v1, 0xffff0000, v35
	v_pk_add_f32 v[0:1], v[14:15], v[0:1] neg_lo:[0,1] neg_hi:[0,1]
	v_pk_add_f32 v[30:31], v[30:31], v[0:1]
	v_pk_fma_f32 v[0:1], v[24:25], v[30:31], v[14:15] op_sel_hi:[0,1,1] neg_lo:[0,0,1] neg_hi:[0,0,1]
	v_cvt_pk_bf16_f32 v38, v0, v1
	v_lshlrev_b32_e32 v22, 16, v159
	v_and_b32_e32 v23, 0xffff0000, v159
	v_cndmask_b32_e32 v35, v147, v139, vcc
	v_lshlrev_b32_e32 v0, 16, v35
	v_and_b32_e32 v1, 0xffff0000, v35
	v_pk_add_f32 v[0:1], v[22:23], v[0:1] neg_lo:[0,1] neg_hi:[0,1]
	v_pk_add_f32 v[8:9], v[8:9], v[0:1]
	v_pk_fma_f32 v[0:1], v[24:25], v[8:9], v[22:23] op_sel_hi:[0,1,1] neg_lo:[0,0,1] neg_hi:[0,0,1]
	v_cvt_pk_bf16_f32 v39, v0, v1
	global_store_dwordx4 v[6:7], v[36:39], off offset:-2048 nt
	s_waitcnt vmcnt(31)
; __device__ __forceinline__ unsigned cvtpk(float lo, float hi) { return pg8::cvt_pk_bf16(lo, hi); }
; __device__ __forceinline__ float bflo(unsigned u) { return __uint_as_float(u << 16); }
; __device__ __forceinline__ float bfhi(unsigned u) { return __uint_as_float(u & 0xffff0000u); }
; __device__ __forceinline__ void pool_pass(const bf16* __restrict__ U, bf16* __restrict__ Y, int gtid, int gthreads) {
;     ...
;         for (int t = t0; t < t0 + 32; ++t) {
;             const v4u v = *(const v4u*)(up + (size_t)t * 1024);
;             const int tb = t - w; v4u vb = {0u, 0u, 0u, 0u};
;             if (t > t0 && tb >= 0) vb = *(const v4u*)(up + (size_t)tb * 1024);
;             const float rc = 1.0f / (float)((t + 1 < w) ? (t + 1) : w);
;             v4u o;
; #pragma unroll
;             for (int j = 0; j < 4; ++j) { const float c0 = bflo(v[j]), c1 = bfhi(v[j]);
;                 sum[2 * j] += c0 - bflo(vb[j]); sum[2 * j + 1] += c1 - bfhi(vb[j]);
;                 o[j] = cvtpk(sum[2 * j] * rc - c0, sum[2 * j + 1] * rc - c1); }
;             __builtin_nontemporal_store(o, (v4u*)(yp + (size_t)t * 1024));
	v_lshlrev_b32_e32 v10, 16, v160
	v_and_b32_e32 v11, 0xffff0000, v160
	v_cndmask_b32_e32 v35, v148, v140, vcc
	v_lshlrev_b32_e32 v0, 16, v35
	v_and_b32_e32 v1, 0xffff0000, v35
	v_pk_add_f32 v[0:1], v[10:11], v[0:1] neg_lo:[0,1] neg_hi:[0,1]
	v_pk_add_f32 v[26:27], v[26:27], v[0:1]
	v_pk_fma_f32 v[0:1], v[24:25], v[26:27], v[10:11] op_sel_hi:[0,1,1] neg_lo:[0,0,1] neg_hi:[0,0,1]
	v_cvt_pk_bf16_f32 v36, v0, v1
	v_lshlrev_b32_e32 v12, 16, v161
	v_and_b32_e32 v13, 0xffff0000, v161
	v_cndmask_b32_e32 v35, v149, v141, vcc
	v_lshlrev_b32_e32 v0, 16, v35
	v_and_b32_e32 v1, 0xffff0000, v35
	v_pk_add_f32 v[0:1], v[12:13], v[0:1] neg_lo:[0,1] neg_hi:[0,1]
	v_pk_add_f32 v[28:29], v[28:29], v[0:1]
	v_pk_fma_f32 v[0:1], v[24:25], v[28:29], v[12:13] op_sel_hi:[0,1,1] neg_lo:[0,0,1] neg_hi:[0,0,1]
	v_cvt_pk_bf16_f32 v37, v0, v1
	v_lshlrev_b32_e32 v14, 16, v162
	v_and_b32_e32 v15, 0xffff0000, v162
	v_cndmask_b32_e32 v35, v150, v142, vcc
	v_lshlrev_b32_e32 v0, 16, v35
	v_and_b32_e32 v1, 0xffff0000, v35
	v_pk_add_f32 v[0:1], v[14:15], v[0:1] neg_lo:[0,1] neg_hi:[0,1]
	v_pk_add_f32 v[30:31], v[30:31], v[0:1]
	v_pk_fma_f32 v[0:1], v[24:25], v[30:31], v[14:15] op_sel_hi:[0,1,1] neg_lo:[0,0,1] neg_hi:[0,0,1]
	v_cvt_pk_bf16_f32 v38, v0, v1
	v_lshlrev_b32_e32 v22, 16, v163
	v_and_b32_e32 v23, 0xffff0000, v163
	v_cndmask_b32_e32 v35, v151, v143, vcc
	v_lshlrev_b32_e32 v0, 16, v35
	v_and_b32_e32 v1, 0xffff0000, v35
	v_pk_add_f32 v[0:1], v[22:23], v[0:1] neg_lo:[0,1] neg_hi:[0,1]
	v_pk_add_f32 v[8:9], v[8:9], v[0:1]
	v_pk_fma_f32 v[0:1], v[24:25], v[8:9], v[22:23] op_sel_hi:[0,1,1] neg_lo:[0,0,1] neg_hi:[0,0,1]
	v_cvt_pk_bf16_f32 v39, v0, v1
	global_store_dwordx4 v[6:7], v[36:39], off nt
	s_waitcnt vmcnt(31)
	v_lshlrev_b32_e32 v10, 16, v164
	v_and_b32_e32 v11, 0xffff0000, v164
	v_cndmask_b32_e32 v35, v156, v144, vcc
	v_lshlrev_b32_e32 v0, 16, v35
	v_and_b32_e32 v1, 0xffff0000, v35
	v_pk_add_f32 v[0:1], v[10:11], v[0:1] neg_lo:[0,1] neg_hi:[0,1]
	v_pk_add_f32 v[26:27], v[26:27], v[0:1]
	v_pk_fma_f32 v[0:1], v[24:25], v[26:27], v[10:11] op_sel_hi:[0,1,1] neg_lo:[0,0,1] neg_hi:[0,0,1]
	v_cvt_pk_bf16_f32 v36, v0, v1
	v_lshlrev_b32_e32 v12, 16, v165
	v_and_b32_e32 v13, 0xffff0000, v165
	v_cndmask_b32_e32 v35, v157, v145, vcc
	v_lshlrev_b32_e32 v0, 16, v35
	v_and_b32_e32 v1, 0xffff0000, v35
	v_pk_add_f32 v[0:1], v[12:13], v[0:1] neg_lo:[0,1] neg_hi:[0,1]
	v_pk_add_f32 v[28:29], v[28:29], v[0:1]
	v_pk_fma_f32 v[0:1], v[24:25], v[28:29], v[12:13] op_sel_hi:[0,1,1] neg_lo:[0,0,1] neg_hi:[0,0,1]
	v_cvt_pk_bf16_f32 v37, v0, v1
	v_lshlrev_b32_e32 v14, 16, v166
	v_and_b32_e32 v15, 0xffff0000, v166
	v_cndmask_b32_e32 v35, v158, v146, vcc
	v_lshlrev_b32_e32 v0, 16, v35
	v_and_b32_e32 v1, 0xffff0000, v35
	v_pk_add_f32 v[0:1], v[14:15], v[0:1] neg_lo:[0,1] neg_hi:[0,1]
	v_pk_add_f32 v[30:31], v[30:31], v[0:1]
	v_pk_fma_f32 v[0:1], v[24:25], v[30:31], v[14:15] op_sel_hi:[0,1,1] neg_lo:[0,0,1] neg_hi:[0,0,1]
	v_cvt_pk_bf16_f32 v38, v0, v1
	v_lshlrev_b32_e32 v22, 16, v167
	v_and_b32_e32 v23, 0xffff0000, v167
	v_cndmask_b32_e32 v35, v159, v147, vcc
	v_lshlrev_b32_e32 v0, 16, v35
	v_and_b32_e32 v1, 0xffff0000, v35
	v_pk_add_f32 v[0:1], v[22:23], v[0:1] neg_lo:[0,1] neg_hi:[0,1]
	v_pk_add_f32 v[8:9], v[8:9], v[0:1]
	v_pk_fma_f32 v[0:1], v[24:25], v[8:9], v[22:23] op_sel_hi:[0,1,1] neg_lo:[0,0,1] neg_hi:[0,0,1]
	v_cvt_pk_bf16_f32 v39, v0, v1
	global_store_dwordx4 v[6:7], v[36:39], off offset:2048 nt
	s_waitcnt vmcnt(31)
	v_lshlrev_b32_e32 v10, 16, v168
	v_and_b32_e32 v11, 0xffff0000, v168
	v_cndmask_b32_e32 v35, v160, v148, vcc
	v_lshlrev_b32_e32 v0, 16, v35
	v_and_b32_e32 v1, 0xffff0000, v35
	v_pk_add_f32 v[0:1], v[10:11], v[0:1] neg_lo:[0,1] neg_hi:[0,1]
	v_pk_add_f32 v[26:27], v[26:27], v[0:1]
	v_pk_fma_f32 v[0:1], v[24:25], v[26:27], v[10:11] op_sel_hi:[0,1,1] neg_lo:[0,0,1] neg_hi:[0,0,1]
	v_cvt_pk_bf16_f32 v36, v0, v1
	v_lshlrev_b32_e32 v12, 16, v169
	v_and_b32_e32 v13, 0xffff0000, v169
	v_cndmask_b32_e32 v35, v161, v149, vcc
	v_lshlrev_b32_e32 v0, 16, v35
	v_and_b32_e32 v1, 0xffff0000, v35
	v_pk_add_f32 v[0:1], v[12:13], v[0:1] neg_lo:[0,1] neg_hi:[0,1]
	v_pk_add_f32 v[28:29], v[28:29], v[0:1]
	v_pk_fma_f32 v[0:1], v[24:25], v[28:29], v[12:13] op_sel_hi:[0,1,1] neg_lo:[0,0,1] neg_hi:[0,0,1]
	v_cvt_pk_bf16_f32 v37, v0, v1
	v_lshlrev_b32_e32 v14, 16, v170
	v_and_b32_e32 v15, 0xffff0000, v170
	v_cndmask_b32_e32 v35, v162, v150, vcc
	v_lshlrev_b32_e32 v0, 16, v35
	v_and_b32_e32 v1, 0xffff0000, v35
	v_pk_add_f32 v[0:1], v[14:15], v[0:1] neg_lo:[0,1] neg_hi:[0,1]
	v_pk_add_f32 v[30:31], v[30:31], v[0:1]
	v_pk_fma_f32 v[0:1], v[24:25], v[30:31], v[14:15] op_sel_hi:[0,1,1] neg_lo:[0,0,1] neg_hi:[0,0,1]
	v_cvt_pk_bf16_f32 v38, v0, v1
	v_lshlrev_b32_e32 v22, 16, v171
	v_and_b32_e32 v23, 0xffff0000, v171
	v_cndmask_b32_e32 v35, v163, v151, vcc
	v_lshlrev_b32_e32 v0, 16, v35
	v_and_b32_e32 v1, 0xffff0000, v35
	v_pk_add_f32 v[0:1], v[22:23], v[0:1] neg_lo:[0,1] neg_hi:[0,1]
	v_pk_add_f32 v[8:9], v[8:9], v[0:1]
	v_pk_fma_f32 v[0:1], v[24:25], v[8:9], v[22:23] op_sel_hi:[0,1,1] neg_lo:[0,0,1] neg_hi:[0,0,1]
	v_cvt_pk_bf16_f32 v39, v0, v1
	v_lshl_add_u64 v[6:7], v[6:7], 0, s[16:17]
	global_store_dwordx4 v[6:7], v[36:39], off offset:-4096 nt
	s_waitcnt vmcnt(31)
; __device__ __forceinline__ unsigned cvtpk(float lo, float hi) { return pg8::cvt_pk_bf16(lo, hi); }
; __device__ __forceinline__ float bflo(unsigned u) { return __uint_as_float(u << 16); }
; __device__ __forceinline__ float bfhi(unsigned u) { return __uint_as_float(u & 0xffff0000u); }
; __device__ __forceinline__ void pool_pass(const bf16* __restrict__ U, bf16* __restrict__ Y, int gtid, int gthreads) {
;     ...
;         for (int t = t0; t < t0 + 32; ++t) {
;             const v4u v = *(const v4u*)(up + (size_t)t * 1024);
;             const int tb = t - w; v4u vb = {0u, 0u, 0u, 0u};
;             if (t > t0 && tb >= 0) vb = *(const v4u*)(up + (size_t)tb * 1024);
;             const float rc = 1.0f / (float)((t + 1 < w) ? (t + 1) : w);
;             v4u o;
; #pragma unroll
;             for (int j = 0; j < 4; ++j) { const float c0 = bflo(v[j]), c1 = bfhi(v[j]);
;                 sum[2 * j] += c0 - bflo(vb[j]); sum[2 * j + 1] += c1 - bfhi(vb[j]);
;                 o[j] = cvtpk(sum[2 * j] * rc - c0, sum[2 * j + 1] * rc - c1); }
;             __builtin_nontemporal_store(o, (v4u*)(yp + (size_t)t * 1024));
	v_lshlrev_b32_e32 v10, 16, v172
	v_and_b32_e32 v11, 0xffff0000, v172
	v_cndmask_b32_e32 v35, v164, v156, vcc
	v_lshlrev_b32_e32 v0, 16, v35
	v_and_b32_e32 v1, 0xffff0000, v35
	v_pk_add_f32 v[0:1], v[10:11], v[0:1] neg_lo:[0,1] neg_hi:[0,1]
	v_pk_add_f32 v[26:27], v[26:27], v[0:1]
	v_pk_fma_f32 v[0:1], v[24:25], v[26:27], v[10:11] op_sel_hi:[0,1,1] neg_lo:[0,0,1] neg_hi:[0,0,1]
	v_cvt_pk_bf16_f32 v36, v0, v1
	v_lshlrev_b32_e32 v12, 16, v173
	v_and_b32_e32 v13, 0xffff0000, v173
	v_cndmask_b32_e32 v35, v165, v157, vcc
	v_lshlrev_b32_e32 v0, 16, v35
	v_and_b32_e32 v1, 0xffff0000, v35
	v_pk_add_f32 v[0:1], v[12:13], v[0:1] neg_lo:[0,1] neg_hi:[0,1]
	v_pk_add_f32 v[28:29], v[28:29], v[0:1]
	v_pk_fma_f32 v[0:1], v[24:25], v[28:29], v[12:13] op_sel_hi:[0,1,1] neg_lo:[0,0,1] neg_hi:[0,0,1]
	v_cvt_pk_bf16_f32 v37, v0, v1
	v_lshlrev_b32_e32 v14, 16, v174
	v_and_b32_e32 v15, 0xffff0000, v174
	v_cndmask_b32_e32 v35, v166, v158, vcc
	v_lshlrev_b32_e32 v0, 16, v35
	v_and_b32_e32 v1, 0xffff0000, v35
	v_pk_add_f32 v[0:1], v[14:15], v[0:1] neg_lo:[0,1] neg_hi:[0,1]
	v_pk_add_f32 v[30:31], v[30:31], v[0:1]
	v_pk_fma_f32 v[0:1], v[24:25], v[30:31], v[14:15] op_sel_hi:[0,1,1] neg_lo:[0,0,1] neg_hi:[0,0,1]
	v_cvt_pk_bf16_f32 v38, v0, v1
	v_lshlrev_b32_e32 v22, 16, v175
	v_and_b32_e32 v23, 0xffff0000, v175
	v_cndmask_b32_e32 v35, v167, v159, vcc
	v_lshlrev_b32_e32 v0, 16, v35
	v_and_b32_e32 v1, 0xffff0000, v35
	v_pk_add_f32 v[0:1], v[22:23], v[0:1] neg_lo:[0,1] neg_hi:[0,1]
	v_pk_add_f32 v[8:9], v[8:9], v[0:1]
	v_pk_fma_f32 v[0:1], v[24:25], v[8:9], v[22:23] op_sel_hi:[0,1,1] neg_lo:[0,0,1] neg_hi:[0,0,1]
	v_cvt_pk_bf16_f32 v39, v0, v1
	global_store_dwordx4 v[6:7], v[36:39], off offset:-2048 nt
	s_waitcnt vmcnt(31)
	v_lshlrev_b32_e32 v10, 16, v176
	v_and_b32_e32 v11, 0xffff0000, v176
	v_cndmask_b32_e32 v35, v168, v160, vcc
	v_lshlrev_b32_e32 v0, 16, v35
	v_and_b32_e32 v1, 0xffff0000, v35
	v_pk_add_f32 v[0:1], v[10:11], v[0:1] neg_lo:[0,1] neg_hi:[0,1]
	v_pk_add_f32 v[26:27], v[26:27], v[0:1]
	v_pk_fma_f32 v[0:1], v[24:25], v[26:27], v[10:11] op_sel_hi:[0,1,1] neg_lo:[0,0,1] neg_hi:[0,0,1]
	v_cvt_pk_bf16_f32 v36, v0, v1
	v_lshlrev_b32_e32 v12, 16, v177
	v_and_b32_e32 v13, 0xffff0000, v177
	v_cndmask_b32_e32 v35, v169, v161, vcc
	v_lshlrev_b32_e32 v0, 16, v35
	v_and_b32_e32 v1, 0xffff0000, v35
	v_pk_add_f32 v[0:1], v[12:13], v[0:1] neg_lo:[0,1] neg_hi:[0,1]
	v_pk_add_f32 v[28:29], v[28:29], v[0:1]
	v_pk_fma_f32 v[0:1], v[24:25], v[28:29], v[12:13] op_sel_hi:[0,1,1] neg_lo:[0,0,1] neg_hi:[0,0,1]
	v_cvt_pk_bf16_f32 v37, v0, v1
	v_lshlrev_b32_e32 v14, 16, v178
	v_and_b32_e32 v15, 0xffff0000, v178
	v_cndmask_b32_e32 v35, v170, v162, vcc
	v_lshlrev_b32_e32 v0, 16, v35
	v_and_b32_e32 v1, 0xffff0000, v35
	v_pk_add_f32 v[0:1], v[14:15], v[0:1] neg_lo:[0,1] neg_hi:[0,1]
	v_pk_add_f32 v[30:31], v[30:31], v[0:1]
	v_pk_fma_f32 v[0:1], v[24:25], v[30:31], v[14:15] op_sel_hi:[0,1,1] neg_lo:[0,0,1] neg_hi:[0,0,1]
	v_cvt_pk_bf16_f32 v38, v0, v1
	v_lshlrev_b32_e32 v22, 16, v179
	v_and_b32_e32 v23, 0xffff0000, v179
	v_cndmask_b32_e32 v35, v171, v163, vcc
	v_lshlrev_b32_e32 v0, 16, v35
	v_and_b32_e32 v1, 0xffff0000, v35
	v_pk_add_f32 v[0:1], v[22:23], v[0:1] neg_lo:[0,1] neg_hi:[0,1]
	v_pk_add_f32 v[8:9], v[8:9], v[0:1]
	v_pk_fma_f32 v[0:1], v[24:25], v[8:9], v[22:23] op_sel_hi:[0,1,1] neg_lo:[0,0,1] neg_hi:[0,0,1]
	v_cvt_pk_bf16_f32 v39, v0, v1
	global_store_dwordx4 v[6:7], v[36:39], off nt
	s_waitcnt vmcnt(31)
	v_lshlrev_b32_e32 v10, 16, v180
	v_and_b32_e32 v11, 0xffff0000, v180
	v_cndmask_b32_e32 v35, v172, v164, vcc
	v_lshlrev_b32_e32 v0, 16, v35
	v_and_b32_e32 v1, 0xffff0000, v35
	v_pk_add_f32 v[0:1], v[10:11], v[0:1] neg_lo:[0,1] neg_hi:[0,1]
	v_pk_add_f32 v[26:27], v[26:27], v[0:1]
	v_pk_fma_f32 v[0:1], v[24:25], v[26:27], v[10:11] op_sel_hi:[0,1,1] neg_lo:[0,0,1] neg_hi:[0,0,1]
	v_cvt_pk_bf16_f32 v36, v0, v1
	v_lshlrev_b32_e32 v12, 16, v181
	v_and_b32_e32 v13, 0xffff0000, v181
	v_cndmask_b32_e32 v35, v173, v165, vcc
	v_lshlrev_b32_e32 v0, 16, v35
	v_and_b32_e32 v1, 0xffff0000, v35
	v_pk_add_f32 v[0:1], v[12:13], v[0:1] neg_lo:[0,1] neg_hi:[0,1]
	v_pk_add_f32 v[28:29], v[28:29], v[0:1]
	v_pk_fma_f32 v[0:1], v[24:25], v[28:29], v[12:13] op_sel_hi:[0,1,1] neg_lo:[0,0,1] neg_hi:[0,0,1]
	v_cvt_pk_bf16_f32 v37, v0, v1
	v_lshlrev_b32_e32 v14, 16, v182
	v_and_b32_e32 v15, 0xffff0000, v182
	v_cndmask_b32_e32 v35, v174, v166, vcc
	v_lshlrev_b32_e32 v0, 16, v35
	v_and_b32_e32 v1, 0xffff0000, v35
	v_pk_add_f32 v[0:1], v[14:15], v[0:1] neg_lo:[0,1] neg_hi:[0,1]
	v_pk_add_f32 v[30:31], v[30:31], v[0:1]
	v_pk_fma_f32 v[0:1], v[24:25], v[30:31], v[14:15] op_sel_hi:[0,1,1] neg_lo:[0,0,1] neg_hi:[0,0,1]
	v_cvt_pk_bf16_f32 v38, v0, v1
	v_lshlrev_b32_e32 v22, 16, v183
	v_and_b32_e32 v23, 0xffff0000, v183
	v_cndmask_b32_e32 v35, v175, v167, vcc
	v_lshlrev_b32_e32 v0, 16, v35
	v_and_b32_e32 v1, 0xffff0000, v35
	v_pk_add_f32 v[0:1], v[22:23], v[0:1] neg_lo:[0,1] neg_hi:[0,1]
	v_pk_add_f32 v[8:9], v[8:9], v[0:1]
	v_pk_fma_f32 v[0:1], v[24:25], v[8:9], v[22:23] op_sel_hi:[0,1,1] neg_lo:[0,0,1] neg_hi:[0,0,1]
	v_cvt_pk_bf16_f32 v39, v0, v1
	global_store_dwordx4 v[6:7], v[36:39], off offset:2048 nt
	s_waitcnt vmcnt(31)
; __device__ __forceinline__ unsigned cvtpk(float lo, float hi) { return pg8::cvt_pk_bf16(lo, hi); }
; __device__ __forceinline__ float bflo(unsigned u) { return __uint_as_float(u << 16); }
; __device__ __forceinline__ float bfhi(unsigned u) { return __uint_as_float(u & 0xffff0000u); }
; __device__ __forceinline__ void pool_pass(const bf16* __restrict__ U, bf16* __restrict__ Y, int gtid, int gthreads) {
;     ...
;         for (int t = t0; t < t0 + 32; ++t) {
;             const v4u v = *(const v4u*)(up + (size_t)t * 1024);
;             const int tb = t - w; v4u vb = {0u, 0u, 0u, 0u};
;             if (t > t0 && tb >= 0) vb = *(const v4u*)(up + (size_t)tb * 1024);
;             const float rc = 1.0f / (float)((t + 1 < w) ? (t + 1) : w);
;             v4u o;
; #pragma unroll
;             for (int j = 0; j < 4; ++j) { const float c0 = bflo(v[j]), c1 = bfhi(v[j]);
;                 sum[2 * j] += c0 - bflo(vb[j]); sum[2 * j + 1] += c1 - bfhi(vb[j]);
;                 o[j] = cvtpk(sum[2 * j] * rc - c0, sum[2 * j + 1] * rc - c1); }
;             __builtin_nontemporal_store(o, (v4u*)(yp + (size_t)t * 1024));
	v_lshlrev_b32_e32 v10, 16, v184
	v_and_b32_e32 v11, 0xffff0000, v184
	v_cndmask_b32_e32 v35, v176, v168, vcc
	v_lshlrev_b32_e32 v0, 16, v35
	v_and_b32_e32 v1, 0xffff0000, v35
	v_pk_add_f32 v[0:1], v[10:11], v[0:1] neg_lo:[0,1] neg_hi:[0,1]
	v_pk_add_f32 v[26:27], v[26:27], v[0:1]
	v_pk_fma_f32 v[0:1], v[24:25], v[26:27], v[10:11] op_sel_hi:[0,1,1] neg_lo:[0,0,1] neg_hi:[0,0,1]
	v_cvt_pk_bf16_f32 v36, v0, v1
	v_lshlrev_b32_e32 v12, 16, v185
	v_and_b32_e32 v13, 0xffff0000, v185
	v_cndmask_b32_e32 v35, v177, v169, vcc
	v_lshlrev_b32_e32 v0, 16, v35
	v_and_b32_e32 v1, 0xffff0000, v35
	v_pk_add_f32 v[0:1], v[12:13], v[0:1] neg_lo:[0,1] neg_hi:[0,1]
	v_pk_add_f32 v[28:29], v[28:29], v[0:1]
	v_pk_fma_f32 v[0:1], v[24:25], v[28:29], v[12:13] op_sel_hi:[0,1,1] neg_lo:[0,0,1] neg_hi:[0,0,1]
	v_cvt_pk_bf16_f32 v37, v0, v1
	v_lshlrev_b32_e32 v14, 16, v186
	v_and_b32_e32 v15, 0xffff0000, v186
	v_cndmask_b32_e32 v35, v178, v170, vcc
	v_lshlrev_b32_e32 v0, 16, v35
	v_and_b32_e32 v1, 0xffff0000, v35
	v_pk_add_f32 v[0:1], v[14:15], v[0:1] neg_lo:[0,1] neg_hi:[0,1]
	v_pk_add_f32 v[30:31], v[30:31], v[0:1]
	v_pk_fma_f32 v[0:1], v[24:25], v[30:31], v[14:15] op_sel_hi:[0,1,1] neg_lo:[0,0,1] neg_hi:[0,0,1]
	v_cvt_pk_bf16_f32 v38, v0, v1
	v_lshlrev_b32_e32 v22, 16, v187
	v_and_b32_e32 v23, 0xffff0000, v187
	v_cndmask_b32_e32 v35, v179, v171, vcc
	v_lshlrev_b32_e32 v0, 16, v35
	v_and_b32_e32 v1, 0xffff0000, v35
	v_pk_add_f32 v[0:1], v[22:23], v[0:1] neg_lo:[0,1] neg_hi:[0,1]
	v_pk_add_f32 v[8:9], v[8:9], v[0:1]
	v_pk_fma_f32 v[0:1], v[24:25], v[8:9], v[22:23] op_sel_hi:[0,1,1] neg_lo:[0,0,1] neg_hi:[0,0,1]
	v_cvt_pk_bf16_f32 v39, v0, v1
	v_lshl_add_u64 v[6:7], v[6:7], 0, s[16:17]
	global_store_dwordx4 v[6:7], v[36:39], off offset:-4096 nt
	s_waitcnt vmcnt(31)
	v_lshlrev_b32_e32 v10, 16, v188
	v_and_b32_e32 v11, 0xffff0000, v188
	v_cndmask_b32_e32 v35, v180, v172, vcc
	v_lshlrev_b32_e32 v0, 16, v35
	v_and_b32_e32 v1, 0xffff0000, v35
	v_pk_add_f32 v[0:1], v[10:11], v[0:1] neg_lo:[0,1] neg_hi:[0,1]
	v_pk_add_f32 v[26:27], v[26:27], v[0:1]
	v_pk_fma_f32 v[0:1], v[24:25], v[26:27], v[10:11] op_sel_hi:[0,1,1] neg_lo:[0,0,1] neg_hi:[0,0,1]
	v_cvt_pk_bf16_f32 v36, v0, v1
	v_lshlrev_b32_e32 v12, 16, v189
	v_and_b32_e32 v13, 0xffff0000, v189
	v_cndmask_b32_e32 v35, v181, v173, vcc
	v_lshlrev_b32_e32 v0, 16, v35
	v_and_b32_e32 v1, 0xffff0000, v35
	v_pk_add_f32 v[0:1], v[12:13], v[0:1] neg_lo:[0,1] neg_hi:[0,1]
	v_pk_add_f32 v[28:29], v[28:29], v[0:1]
	v_pk_fma_f32 v[0:1], v[24:25], v[28:29], v[12:13] op_sel_hi:[0,1,1] neg_lo:[0,0,1] neg_hi:[0,0,1]
	v_cvt_pk_bf16_f32 v37, v0, v1
	v_lshlrev_b32_e32 v14, 16, v190
	v_and_b32_e32 v15, 0xffff0000, v190
	v_cndmask_b32_e32 v35, v182, v174, vcc
	v_lshlrev_b32_e32 v0, 16, v35
	v_and_b32_e32 v1, 0xffff0000, v35
	v_pk_add_f32 v[0:1], v[14:15], v[0:1] neg_lo:[0,1] neg_hi:[0,1]
	v_pk_add_f32 v[30:31], v[30:31], v[0:1]
	v_pk_fma_f32 v[0:1], v[24:25], v[30:31], v[14:15] op_sel_hi:[0,1,1] neg_lo:[0,0,1] neg_hi:[0,0,1]
	v_cvt_pk_bf16_f32 v38, v0, v1
	v_lshlrev_b32_e32 v22, 16, v191
	v_and_b32_e32 v23, 0xffff0000, v191
	v_cndmask_b32_e32 v35, v183, v175, vcc
	v_lshlrev_b32_e32 v0, 16, v35
	v_and_b32_e32 v1, 0xffff0000, v35
	v_pk_add_f32 v[0:1], v[22:23], v[0:1] neg_lo:[0,1] neg_hi:[0,1]
	v_pk_add_f32 v[8:9], v[8:9], v[0:1]
	v_pk_fma_f32 v[0:1], v[24:25], v[8:9], v[22:23] op_sel_hi:[0,1,1] neg_lo:[0,0,1] neg_hi:[0,0,1]
	v_cvt_pk_bf16_f32 v39, v0, v1
	global_store_dwordx4 v[6:7], v[36:39], off offset:-2048 nt
	s_waitcnt vmcnt(31)
	v_lshlrev_b32_e32 v10, 16, v192
	v_and_b32_e32 v11, 0xffff0000, v192
	v_cndmask_b32_e32 v35, v184, v176, vcc
	v_lshlrev_b32_e32 v0, 16, v35
	v_and_b32_e32 v1, 0xffff0000, v35
	v_pk_add_f32 v[0:1], v[10:11], v[0:1] neg_lo:[0,1] neg_hi:[0,1]
	v_pk_add_f32 v[26:27], v[26:27], v[0:1]
	v_pk_fma_f32 v[0:1], v[24:25], v[26:27], v[10:11] op_sel_hi:[0,1,1] neg_lo:[0,0,1] neg_hi:[0,0,1]
	v_cvt_pk_bf16_f32 v36, v0, v1
	v_lshlrev_b32_e32 v12, 16, v193
	v_and_b32_e32 v13, 0xffff0000, v193
	v_cndmask_b32_e32 v35, v185, v177, vcc
	v_lshlrev_b32_e32 v0, 16, v35
	v_and_b32_e32 v1, 0xffff0000, v35
	v_pk_add_f32 v[0:1], v[12:13], v[0:1] neg_lo:[0,1] neg_hi:[0,1]
	v_pk_add_f32 v[28:29], v[28:29], v[0:1]
	v_pk_fma_f32 v[0:1], v[24:25], v[28:29], v[12:13] op_sel_hi:[0,1,1] neg_lo:[0,0,1] neg_hi:[0,0,1]
	v_cvt_pk_bf16_f32 v37, v0, v1
	v_lshlrev_b32_e32 v14, 16, v194
	v_and_b32_e32 v15, 0xffff0000, v194
	v_cndmask_b32_e32 v35, v186, v178, vcc
	v_lshlrev_b32_e32 v0, 16, v35
	v_and_b32_e32 v1, 0xffff0000, v35
	v_pk_add_f32 v[0:1], v[14:15], v[0:1] neg_lo:[0,1] neg_hi:[0,1]
	v_pk_add_f32 v[30:31], v[30:31], v[0:1]
	v_pk_fma_f32 v[0:1], v[24:25], v[30:31], v[14:15] op_sel_hi:[0,1,1] neg_lo:[0,0,1] neg_hi:[0,0,1]
	v_cvt_pk_bf16_f32 v38, v0, v1
	v_lshlrev_b32_e32 v22, 16, v195
	v_and_b32_e32 v23, 0xffff0000, v195
	v_cndmask_b32_e32 v35, v187, v179, vcc
	v_lshlrev_b32_e32 v0, 16, v35
	v_and_b32_e32 v1, 0xffff0000, v35
	v_pk_add_f32 v[0:1], v[22:23], v[0:1] neg_lo:[0,1] neg_hi:[0,1]
	v_pk_add_f32 v[8:9], v[8:9], v[0:1]
	v_pk_fma_f32 v[0:1], v[24:25], v[8:9], v[22:23] op_sel_hi:[0,1,1] neg_lo:[0,0,1] neg_hi:[0,0,1]
	v_cvt_pk_bf16_f32 v39, v0, v1
	global_store_dwordx4 v[6:7], v[36:39], off nt
	s_waitcnt vmcnt(31)
; __device__ __forceinline__ unsigned cvtpk(float lo, float hi) { return pg8::cvt_pk_bf16(lo, hi); }
; __device__ __forceinline__ float bflo(unsigned u) { return __uint_as_float(u << 16); }
; __device__ __forceinline__ float bfhi(unsigned u) { return __uint_as_float(u & 0xffff0000u); }
; __device__ __forceinline__ void pool_pass(const bf16* __restrict__ U, bf16* __restrict__ Y, int gtid, int gthreads) {
;     ...
;         for (int t = t0; t < t0 + 32; ++t) {
;             const v4u v = *(const v4u*)(up + (size_t)t * 1024);
;             const int tb = t - w; v4u vb = {0u, 0u, 0u, 0u};
;             if (t > t0 && tb >= 0) vb = *(const v4u*)(up + (size_t)tb * 1024);
;             const float rc = 1.0f / (float)((t + 1 < w) ? (t + 1) : w);
;             v4u o;
; #pragma unroll
;             for (int j = 0; j < 4; ++j) { const float c0 = bflo(v[j]), c1 = bfhi(v[j]);
;                 sum[2 * j] += c0 - bflo(vb[j]); sum[2 * j + 1] += c1 - bfhi(vb[j]);
;                 o[j] = cvtpk(sum[2 * j] * rc - c0, sum[2 * j + 1] * rc - c1); }
;             __builtin_nontemporal_store(o, (v4u*)(yp + (size_t)t * 1024));
	v_lshlrev_b32_e32 v10, 16, v196
	v_and_b32_e32 v11, 0xffff0000, v196
	v_cndmask_b32_e32 v35, v188, v180, vcc
	v_lshlrev_b32_e32 v0, 16, v35
	v_and_b32_e32 v1, 0xffff0000, v35
	v_pk_add_f32 v[0:1], v[10:11], v[0:1] neg_lo:[0,1] neg_hi:[0,1]
	v_pk_add_f32 v[26:27], v[26:27], v[0:1]
	v_pk_fma_f32 v[0:1], v[24:25], v[26:27], v[10:11] op_sel_hi:[0,1,1] neg_lo:[0,0,1] neg_hi:[0,0,1]
	v_cvt_pk_bf16_f32 v36, v0, v1
	v_lshlrev_b32_e32 v12, 16, v197
	v_and_b32_e32 v13, 0xffff0000, v197
	v_cndmask_b32_e32 v35, v189, v181, vcc
	v_lshlrev_b32_e32 v0, 16, v35
	v_and_b32_e32 v1, 0xffff0000, v35
	v_pk_add_f32 v[0:1], v[12:13], v[0:1] neg_lo:[0,1] neg_hi:[0,1]
	v_pk_add_f32 v[28:29], v[28:29], v[0:1]
	v_pk_fma_f32 v[0:1], v[24:25], v[28:29], v[12:13] op_sel_hi:[0,1,1] neg_lo:[0,0,1] neg_hi:[0,0,1]
	v_cvt_pk_bf16_f32 v37, v0, v1
	v_lshlrev_b32_e32 v14, 16, v198
	v_and_b32_e32 v15, 0xffff0000, v198
	v_cndmask_b32_e32 v35, v190, v182, vcc
	v_lshlrev_b32_e32 v0, 16, v35
	v_and_b32_e32 v1, 0xffff0000, v35
	v_pk_add_f32 v[0:1], v[14:15], v[0:1] neg_lo:[0,1] neg_hi:[0,1]
	v_pk_add_f32 v[30:31], v[30:31], v[0:1]
	v_pk_fma_f32 v[0:1], v[24:25], v[30:31], v[14:15] op_sel_hi:[0,1,1] neg_lo:[0,0,1] neg_hi:[0,0,1]
	v_cvt_pk_bf16_f32 v38, v0, v1
	v_lshlrev_b32_e32 v22, 16, v199
	v_and_b32_e32 v23, 0xffff0000, v199
	v_cndmask_b32_e32 v35, v191, v183, vcc
	v_lshlrev_b32_e32 v0, 16, v35
	v_and_b32_e32 v1, 0xffff0000, v35
	v_pk_add_f32 v[0:1], v[22:23], v[0:1] neg_lo:[0,1] neg_hi:[0,1]
	v_pk_add_f32 v[8:9], v[8:9], v[0:1]
	v_pk_fma_f32 v[0:1], v[24:25], v[8:9], v[22:23] op_sel_hi:[0,1,1] neg_lo:[0,0,1] neg_hi:[0,0,1]
	v_cvt_pk_bf16_f32 v39, v0, v1
	global_store_dwordx4 v[6:7], v[36:39], off offset:2048 nt
	s_waitcnt vmcnt(31)
	v_lshlrev_b32_e32 v10, 16, v200
	v_and_b32_e32 v11, 0xffff0000, v200
	v_cndmask_b32_e32 v35, v192, v184, vcc
	v_lshlrev_b32_e32 v0, 16, v35
	v_and_b32_e32 v1, 0xffff0000, v35
	v_pk_add_f32 v[0:1], v[10:11], v[0:1] neg_lo:[0,1] neg_hi:[0,1]
	v_pk_add_f32 v[26:27], v[26:27], v[0:1]
	v_pk_fma_f32 v[0:1], v[24:25], v[26:27], v[10:11] op_sel_hi:[0,1,1] neg_lo:[0,0,1] neg_hi:[0,0,1]
	v_cvt_pk_bf16_f32 v36, v0, v1
	v_lshlrev_b32_e32 v12, 16, v201
	v_and_b32_e32 v13, 0xffff0000, v201
	v_cndmask_b32_e32 v35, v193, v185, vcc
	v_lshlrev_b32_e32 v0, 16, v35
	v_and_b32_e32 v1, 0xffff0000, v35
	v_pk_add_f32 v[0:1], v[12:13], v[0:1] neg_lo:[0,1] neg_hi:[0,1]
	v_pk_add_f32 v[28:29], v[28:29], v[0:1]
	v_pk_fma_f32 v[0:1], v[24:25], v[28:29], v[12:13] op_sel_hi:[0,1,1] neg_lo:[0,0,1] neg_hi:[0,0,1]
	v_cvt_pk_bf16_f32 v37, v0, v1
	v_lshlrev_b32_e32 v14, 16, v202
	v_and_b32_e32 v15, 0xffff0000, v202
	v_cndmask_b32_e32 v35, v194, v186, vcc
	v_lshlrev_b32_e32 v0, 16, v35
	v_and_b32_e32 v1, 0xffff0000, v35
	v_pk_add_f32 v[0:1], v[14:15], v[0:1] neg_lo:[0,1] neg_hi:[0,1]
	v_pk_add_f32 v[30:31], v[30:31], v[0:1]
	v_pk_fma_f32 v[0:1], v[24:25], v[30:31], v[14:15] op_sel_hi:[0,1,1] neg_lo:[0,0,1] neg_hi:[0,0,1]
	v_cvt_pk_bf16_f32 v38, v0, v1
	v_lshlrev_b32_e32 v22, 16, v203
	v_and_b32_e32 v23, 0xffff0000, v203
	v_cndmask_b32_e32 v35, v195, v187, vcc
	v_lshlrev_b32_e32 v0, 16, v35
	v_and_b32_e32 v1, 0xffff0000, v35
	v_pk_add_f32 v[0:1], v[22:23], v[0:1] neg_lo:[0,1] neg_hi:[0,1]
	v_pk_add_f32 v[8:9], v[8:9], v[0:1]
	v_pk_fma_f32 v[0:1], v[24:25], v[8:9], v[22:23] op_sel_hi:[0,1,1] neg_lo:[0,0,1] neg_hi:[0,0,1]
	v_cvt_pk_bf16_f32 v39, v0, v1
	v_lshl_add_u64 v[6:7], v[6:7], 0, s[16:17]
	global_store_dwordx4 v[6:7], v[36:39], off offset:-4096 nt
	s_waitcnt vmcnt(31)
	v_lshlrev_b32_e32 v10, 16, v204
	v_and_b32_e32 v11, 0xffff0000, v204
	v_cndmask_b32_e32 v35, v196, v188, vcc
	v_lshlrev_b32_e32 v0, 16, v35
	v_and_b32_e32 v1, 0xffff0000, v35
	v_pk_add_f32 v[0:1], v[10:11], v[0:1] neg_lo:[0,1] neg_hi:[0,1]
	v_pk_add_f32 v[26:27], v[26:27], v[0:1]
	v_pk_fma_f32 v[0:1], v[24:25], v[26:27], v[10:11] op_sel_hi:[0,1,1] neg_lo:[0,0,1] neg_hi:[0,0,1]
	v_cvt_pk_bf16_f32 v36, v0, v1
	v_lshlrev_b32_e32 v12, 16, v205
	v_and_b32_e32 v13, 0xffff0000, v205
	v_cndmask_b32_e32 v35, v197, v189, vcc
	v_lshlrev_b32_e32 v0, 16, v35
	v_and_b32_e32 v1, 0xffff0000, v35
	v_pk_add_f32 v[0:1], v[12:13], v[0:1] neg_lo:[0,1] neg_hi:[0,1]
	v_pk_add_f32 v[28:29], v[28:29], v[0:1]
	v_pk_fma_f32 v[0:1], v[24:25], v[28:29], v[12:13] op_sel_hi:[0,1,1] neg_lo:[0,0,1] neg_hi:[0,0,1]
	v_cvt_pk_bf16_f32 v37, v0, v1
	v_lshlrev_b32_e32 v14, 16, v206
	v_and_b32_e32 v15, 0xffff0000, v206
	v_cndmask_b32_e32 v35, v198, v190, vcc
	v_lshlrev_b32_e32 v0, 16, v35
	v_and_b32_e32 v1, 0xffff0000, v35
	v_pk_add_f32 v[0:1], v[14:15], v[0:1] neg_lo:[0,1] neg_hi:[0,1]
	v_pk_add_f32 v[30:31], v[30:31], v[0:1]
	v_pk_fma_f32 v[0:1], v[24:25], v[30:31], v[14:15] op_sel_hi:[0,1,1] neg_lo:[0,0,1] neg_hi:[0,0,1]
	v_cvt_pk_bf16_f32 v38, v0, v1
	v_lshlrev_b32_e32 v22, 16, v207
	v_and_b32_e32 v23, 0xffff0000, v207
	v_cndmask_b32_e32 v35, v199, v191, vcc
	v_lshlrev_b32_e32 v0, 16, v35
	v_and_b32_e32 v1, 0xffff0000, v35
	v_pk_add_f32 v[0:1], v[22:23], v[0:1] neg_lo:[0,1] neg_hi:[0,1]
	v_pk_add_f32 v[8:9], v[8:9], v[0:1]
	v_pk_fma_f32 v[0:1], v[24:25], v[8:9], v[22:23] op_sel_hi:[0,1,1] neg_lo:[0,0,1] neg_hi:[0,0,1]
	v_cvt_pk_bf16_f32 v39, v0, v1
	global_store_dwordx4 v[6:7], v[36:39], off offset:-2048 nt
	s_waitcnt vmcnt(31)
; __device__ __forceinline__ unsigned cvtpk(float lo, float hi) { return pg8::cvt_pk_bf16(lo, hi); }
; __device__ __forceinline__ float bflo(unsigned u) { return __uint_as_float(u << 16); }
; __device__ __forceinline__ float bfhi(unsigned u) { return __uint_as_float(u & 0xffff0000u); }
; __device__ __forceinline__ void pool_pass(const bf16* __restrict__ U, bf16* __restrict__ Y, int gtid, int gthreads) {
;     ...
;         for (int t = t0; t < t0 + 32; ++t) {
;             const v4u v = *(const v4u*)(up + (size_t)t * 1024);
;             const int tb = t - w; v4u vb = {0u, 0u, 0u, 0u};
;             if (t > t0 && tb >= 0) vb = *(const v4u*)(up + (size_t)tb * 1024);
;             const float rc = 1.0f / (float)((t + 1 < w) ? (t + 1) : w);
;             v4u o;
; #pragma unroll
;             for (int j = 0; j < 4; ++j) { const float c0 = bflo(v[j]), c1 = bfhi(v[j]);
;                 sum[2 * j] += c0 - bflo(vb[j]); sum[2 * j + 1] += c1 - bfhi(vb[j]);
;                 o[j] = cvtpk(sum[2 * j] * rc - c0, sum[2 * j + 1] * rc - c1); }
;             __builtin_nontemporal_store(o, (v4u*)(yp + (size_t)t * 1024));
	v_lshlrev_b32_e32 v10, 16, v208
	v_and_b32_e32 v11, 0xffff0000, v208
	v_cndmask_b32_e32 v35, v200, v192, vcc
	v_lshlrev_b32_e32 v0, 16, v35
	v_and_b32_e32 v1, 0xffff0000, v35
	v_pk_add_f32 v[0:1], v[10:11], v[0:1] neg_lo:[0,1] neg_hi:[0,1]
	v_pk_add_f32 v[26:27], v[26:27], v[0:1]
	v_pk_fma_f32 v[0:1], v[24:25], v[26:27], v[10:11] op_sel_hi:[0,1,1] neg_lo:[0,0,1] neg_hi:[0,0,1]
	v_cvt_pk_bf16_f32 v36, v0, v1
	v_lshlrev_b32_e32 v12, 16, v209
	v_and_b32_e32 v13, 0xffff0000, v209
	v_cndmask_b32_e32 v35, v201, v193, vcc
	v_lshlrev_b32_e32 v0, 16, v35
	v_and_b32_e32 v1, 0xffff0000, v35
	v_pk_add_f32 v[0:1], v[12:13], v[0:1] neg_lo:[0,1] neg_hi:[0,1]
	v_pk_add_f32 v[28:29], v[28:29], v[0:1]
	v_pk_fma_f32 v[0:1], v[24:25], v[28:29], v[12:13] op_sel_hi:[0,1,1] neg_lo:[0,0,1] neg_hi:[0,0,1]
	v_cvt_pk_bf16_f32 v37, v0, v1
	v_lshlrev_b32_e32 v14, 16, v210
	v_and_b32_e32 v15, 0xffff0000, v210
	v_cndmask_b32_e32 v35, v202, v194, vcc
	v_lshlrev_b32_e32 v0, 16, v35
	v_and_b32_e32 v1, 0xffff0000, v35
	v_pk_add_f32 v[0:1], v[14:15], v[0:1] neg_lo:[0,1] neg_hi:[0,1]
	v_pk_add_f32 v[30:31], v[30:31], v[0:1]
	v_pk_fma_f32 v[0:1], v[24:25], v[30:31], v[14:15] op_sel_hi:[0,1,1] neg_lo:[0,0,1] neg_hi:[0,0,1]
	v_cvt_pk_bf16_f32 v38, v0, v1
	v_lshlrev_b32_e32 v22, 16, v211
	v_and_b32_e32 v23, 0xffff0000, v211
	v_cndmask_b32_e32 v35, v203, v195, vcc
	v_lshlrev_b32_e32 v0, 16, v35
	v_and_b32_e32 v1, 0xffff0000, v35
	v_pk_add_f32 v[0:1], v[22:23], v[0:1] neg_lo:[0,1] neg_hi:[0,1]
	v_pk_add_f32 v[8:9], v[8:9], v[0:1]
	v_pk_fma_f32 v[0:1], v[24:25], v[8:9], v[22:23] op_sel_hi:[0,1,1] neg_lo:[0,0,1] neg_hi:[0,0,1]
	v_cvt_pk_bf16_f32 v39, v0, v1
	global_store_dwordx4 v[6:7], v[36:39], off nt
	s_waitcnt vmcnt(31)
	v_lshlrev_b32_e32 v10, 16, v212
	v_and_b32_e32 v11, 0xffff0000, v212
	v_cndmask_b32_e32 v35, v204, v196, vcc
	v_lshlrev_b32_e32 v0, 16, v35
	v_and_b32_e32 v1, 0xffff0000, v35
	v_pk_add_f32 v[0:1], v[10:11], v[0:1] neg_lo:[0,1] neg_hi:[0,1]
	v_pk_add_f32 v[26:27], v[26:27], v[0:1]
	v_pk_fma_f32 v[0:1], v[24:25], v[26:27], v[10:11] op_sel_hi:[0,1,1] neg_lo:[0,0,1] neg_hi:[0,0,1]
	v_cvt_pk_bf16_f32 v36, v0, v1
	v_lshlrev_b32_e32 v12, 16, v213
	v_and_b32_e32 v13, 0xffff0000, v213
	v_cndmask_b32_e32 v35, v205, v197, vcc
	v_lshlrev_b32_e32 v0, 16, v35
	v_and_b32_e32 v1, 0xffff0000, v35
	v_pk_add_f32 v[0:1], v[12:13], v[0:1] neg_lo:[0,1] neg_hi:[0,1]
	v_pk_add_f32 v[28:29], v[28:29], v[0:1]
	v_pk_fma_f32 v[0:1], v[24:25], v[28:29], v[12:13] op_sel_hi:[0,1,1] neg_lo:[0,0,1] neg_hi:[0,0,1]
	v_cvt_pk_bf16_f32 v37, v0, v1
	v_lshlrev_b32_e32 v14, 16, v214
	v_and_b32_e32 v15, 0xffff0000, v214
	v_cndmask_b32_e32 v35, v206, v198, vcc
	v_lshlrev_b32_e32 v0, 16, v35
	v_and_b32_e32 v1, 0xffff0000, v35
	v_pk_add_f32 v[0:1], v[14:15], v[0:1] neg_lo:[0,1] neg_hi:[0,1]
	v_pk_add_f32 v[30:31], v[30:31], v[0:1]
	v_pk_fma_f32 v[0:1], v[24:25], v[30:31], v[14:15] op_sel_hi:[0,1,1] neg_lo:[0,0,1] neg_hi:[0,0,1]
	v_cvt_pk_bf16_f32 v38, v0, v1
	v_lshlrev_b32_e32 v22, 16, v215
	v_and_b32_e32 v23, 0xffff0000, v215
	v_cndmask_b32_e32 v35, v207, v199, vcc
	v_lshlrev_b32_e32 v0, 16, v35
	v_and_b32_e32 v1, 0xffff0000, v35
	v_pk_add_f32 v[0:1], v[22:23], v[0:1] neg_lo:[0,1] neg_hi:[0,1]
	v_pk_add_f32 v[8:9], v[8:9], v[0:1]
	v_pk_fma_f32 v[0:1], v[24:25], v[8:9], v[22:23] op_sel_hi:[0,1,1] neg_lo:[0,0,1] neg_hi:[0,0,1]
	v_cvt_pk_bf16_f32 v39, v0, v1
	global_store_dwordx4 v[6:7], v[36:39], off offset:2048 nt
	s_waitcnt vmcnt(31)
	v_lshlrev_b32_e32 v10, 16, v216
	v_and_b32_e32 v11, 0xffff0000, v216
	v_cndmask_b32_e32 v35, v208, v200, vcc
	v_lshlrev_b32_e32 v0, 16, v35
	v_and_b32_e32 v1, 0xffff0000, v35
	v_pk_add_f32 v[0:1], v[10:11], v[0:1] neg_lo:[0,1] neg_hi:[0,1]
	v_pk_add_f32 v[26:27], v[26:27], v[0:1]
	v_pk_fma_f32 v[0:1], v[24:25], v[26:27], v[10:11] op_sel_hi:[0,1,1] neg_lo:[0,0,1] neg_hi:[0,0,1]
	v_cvt_pk_bf16_f32 v36, v0, v1
	v_lshlrev_b32_e32 v12, 16, v217
	v_and_b32_e32 v13, 0xffff0000, v217
	v_cndmask_b32_e32 v35, v209, v201, vcc
	v_lshlrev_b32_e32 v0, 16, v35
	v_and_b32_e32 v1, 0xffff0000, v35
	v_pk_add_f32 v[0:1], v[12:13], v[0:1] neg_lo:[0,1] neg_hi:[0,1]
	v_pk_add_f32 v[28:29], v[28:29], v[0:1]
	v_pk_fma_f32 v[0:1], v[24:25], v[28:29], v[12:13] op_sel_hi:[0,1,1] neg_lo:[0,0,1] neg_hi:[0,0,1]
	v_cvt_pk_bf16_f32 v37, v0, v1
	v_lshlrev_b32_e32 v14, 16, v218
	v_and_b32_e32 v15, 0xffff0000, v218
	v_cndmask_b32_e32 v35, v210, v202, vcc
	v_lshlrev_b32_e32 v0, 16, v35
	v_and_b32_e32 v1, 0xffff0000, v35
	v_pk_add_f32 v[0:1], v[14:15], v[0:1] neg_lo:[0,1] neg_hi:[0,1]
	v_pk_add_f32 v[30:31], v[30:31], v[0:1]
	v_pk_fma_f32 v[0:1], v[24:25], v[30:31], v[14:15] op_sel_hi:[0,1,1] neg_lo:[0,0,1] neg_hi:[0,0,1]
	v_cvt_pk_bf16_f32 v38, v0, v1
	v_lshlrev_b32_e32 v22, 16, v219
	v_and_b32_e32 v23, 0xffff0000, v219
	v_cndmask_b32_e32 v35, v211, v203, vcc
	v_lshlrev_b32_e32 v0, 16, v35
	v_and_b32_e32 v1, 0xffff0000, v35
	v_pk_add_f32 v[0:1], v[22:23], v[0:1] neg_lo:[0,1] neg_hi:[0,1]
	v_pk_add_f32 v[8:9], v[8:9], v[0:1]
	v_pk_fma_f32 v[0:1], v[24:25], v[8:9], v[22:23] op_sel_hi:[0,1,1] neg_lo:[0,0,1] neg_hi:[0,0,1]
	v_cvt_pk_bf16_f32 v39, v0, v1
	v_lshl_add_u64 v[6:7], v[6:7], 0, s[16:17]
	global_store_dwordx4 v[6:7], v[36:39], off offset:-4096 nt
	s_waitcnt vmcnt(31)
; __device__ __forceinline__ unsigned cvtpk(float lo, float hi) { return pg8::cvt_pk_bf16(lo, hi); }
; __device__ __forceinline__ float bflo(unsigned u) { return __uint_as_float(u << 16); }
; __device__ __forceinline__ float bfhi(unsigned u) { return __uint_as_float(u & 0xffff0000u); }
; __device__ __forceinline__ void pool_pass(const bf16* __restrict__ U, bf16* __restrict__ Y, int gtid, int gthreads) {
;     ...
;         for (int t = t0; t < t0 + 32; ++t) {
;             const v4u v = *(const v4u*)(up + (size_t)t * 1024);
;             const int tb = t - w; v4u vb = {0u, 0u, 0u, 0u};
;             if (t > t0 && tb >= 0) vb = *(const v4u*)(up + (size_t)tb * 1024);
;             const float rc = 1.0f / (float)((t + 1 < w) ? (t + 1) : w);
;             v4u o;
; #pragma unroll
;             for (int j = 0; j < 4; ++j) { const float c0 = bflo(v[j]), c1 = bfhi(v[j]);
;                 sum[2 * j] += c0 - bflo(vb[j]); sum[2 * j + 1] += c1 - bfhi(vb[j]);
;                 o[j] = cvtpk(sum[2 * j] * rc - c0, sum[2 * j + 1] * rc - c1); }
;             __builtin_nontemporal_store(o, (v4u*)(yp + (size_t)t * 1024));
;         }
;     }
	v_lshlrev_b32_e32 v10, 16, v220
	v_and_b32_e32 v11, 0xffff0000, v220
	v_cndmask_b32_e32 v35, v212, v204, vcc
	v_lshlrev_b32_e32 v0, 16, v35
	v_and_b32_e32 v1, 0xffff0000, v35
	v_pk_add_f32 v[0:1], v[10:11], v[0:1] neg_lo:[0,1] neg_hi:[0,1]
	v_pk_add_f32 v[26:27], v[26:27], v[0:1]
	v_pk_fma_f32 v[0:1], v[24:25], v[26:27], v[10:11] op_sel_hi:[0,1,1] neg_lo:[0,0,1] neg_hi:[0,0,1]
	v_cvt_pk_bf16_f32 v36, v0, v1
	v_lshlrev_b32_e32 v12, 16, v221
	v_and_b32_e32 v13, 0xffff0000, v221
	v_cndmask_b32_e32 v35, v213, v205, vcc
	v_lshlrev_b32_e32 v0, 16, v35
	v_and_b32_e32 v1, 0xffff0000, v35
	v_pk_add_f32 v[0:1], v[12:13], v[0:1] neg_lo:[0,1] neg_hi:[0,1]
	v_pk_add_f32 v[28:29], v[28:29], v[0:1]
	v_pk_fma_f32 v[0:1], v[24:25], v[28:29], v[12:13] op_sel_hi:[0,1,1] neg_lo:[0,0,1] neg_hi:[0,0,1]
	v_cvt_pk_bf16_f32 v37, v0, v1
	v_lshlrev_b32_e32 v14, 16, v222
	v_and_b32_e32 v15, 0xffff0000, v222
	v_cndmask_b32_e32 v35, v214, v206, vcc
	v_lshlrev_b32_e32 v0, 16, v35
	v_and_b32_e32 v1, 0xffff0000, v35
	v_pk_add_f32 v[0:1], v[14:15], v[0:1] neg_lo:[0,1] neg_hi:[0,1]
	v_pk_add_f32 v[30:31], v[30:31], v[0:1]
	v_pk_fma_f32 v[0:1], v[24:25], v[30:31], v[14:15] op_sel_hi:[0,1,1] neg_lo:[0,0,1] neg_hi:[0,0,1]
	v_cvt_pk_bf16_f32 v38, v0, v1
	v_lshlrev_b32_e32 v22, 16, v223
	v_and_b32_e32 v23, 0xffff0000, v223
	v_cndmask_b32_e32 v35, v215, v207, vcc
	v_lshlrev_b32_e32 v0, 16, v35
	v_and_b32_e32 v1, 0xffff0000, v35
	v_pk_add_f32 v[0:1], v[22:23], v[0:1] neg_lo:[0,1] neg_hi:[0,1]
	v_pk_add_f32 v[8:9], v[8:9], v[0:1]
	v_pk_fma_f32 v[0:1], v[24:25], v[8:9], v[22:23] op_sel_hi:[0,1,1] neg_lo:[0,0,1] neg_hi:[0,0,1]
	v_cvt_pk_bf16_f32 v39, v0, v1
	global_store_dwordx4 v[6:7], v[36:39], off offset:-2048 nt
	s_waitcnt vmcnt(31)
	v_lshlrev_b32_e32 v10, 16, v224
	v_and_b32_e32 v11, 0xffff0000, v224
	v_cndmask_b32_e32 v35, v216, v208, vcc
	v_lshlrev_b32_e32 v0, 16, v35
	v_and_b32_e32 v1, 0xffff0000, v35
	v_pk_add_f32 v[0:1], v[10:11], v[0:1] neg_lo:[0,1] neg_hi:[0,1]
	v_pk_add_f32 v[26:27], v[26:27], v[0:1]
	v_pk_fma_f32 v[0:1], v[24:25], v[26:27], v[10:11] op_sel_hi:[0,1,1] neg_lo:[0,0,1] neg_hi:[0,0,1]
	v_cvt_pk_bf16_f32 v36, v0, v1
	v_lshlrev_b32_e32 v12, 16, v225
	v_and_b32_e32 v13, 0xffff0000, v225
	v_cndmask_b32_e32 v35, v217, v209, vcc
	v_lshlrev_b32_e32 v0, 16, v35
	v_and_b32_e32 v1, 0xffff0000, v35
	v_pk_add_f32 v[0:1], v[12:13], v[0:1] neg_lo:[0,1] neg_hi:[0,1]
	v_pk_add_f32 v[28:29], v[28:29], v[0:1]
	v_pk_fma_f32 v[0:1], v[24:25], v[28:29], v[12:13] op_sel_hi:[0,1,1] neg_lo:[0,0,1] neg_hi:[0,0,1]
	v_cvt_pk_bf16_f32 v37, v0, v1
	v_lshlrev_b32_e32 v14, 16, v226
	v_and_b32_e32 v15, 0xffff0000, v226
	v_cndmask_b32_e32 v35, v218, v210, vcc
	v_lshlrev_b32_e32 v0, 16, v35
	v_and_b32_e32 v1, 0xffff0000, v35
	v_pk_add_f32 v[0:1], v[14:15], v[0:1] neg_lo:[0,1] neg_hi:[0,1]
	v_pk_add_f32 v[30:31], v[30:31], v[0:1]
	v_pk_fma_f32 v[0:1], v[24:25], v[30:31], v[14:15] op_sel_hi:[0,1,1] neg_lo:[0,0,1] neg_hi:[0,0,1]
	v_cvt_pk_bf16_f32 v38, v0, v1
	v_lshlrev_b32_e32 v22, 16, v227
	v_and_b32_e32 v23, 0xffff0000, v227
	v_cndmask_b32_e32 v35, v219, v211, vcc
	v_lshlrev_b32_e32 v0, 16, v35
	v_and_b32_e32 v1, 0xffff0000, v35
	v_pk_add_f32 v[0:1], v[22:23], v[0:1] neg_lo:[0,1] neg_hi:[0,1]
	v_pk_add_f32 v[8:9], v[8:9], v[0:1]
	v_pk_fma_f32 v[0:1], v[24:25], v[8:9], v[22:23] op_sel_hi:[0,1,1] neg_lo:[0,0,1] neg_hi:[0,0,1]
	v_cvt_pk_bf16_f32 v39, v0, v1
	global_store_dwordx4 v[6:7], v[36:39], off nt
	s_waitcnt vmcnt(31)
	v_lshlrev_b32_e32 v10, 16, v228
	v_and_b32_e32 v11, 0xffff0000, v228
	v_cndmask_b32_e32 v35, v220, v212, vcc
	v_lshlrev_b32_e32 v0, 16, v35
	v_and_b32_e32 v1, 0xffff0000, v35
	v_pk_add_f32 v[0:1], v[10:11], v[0:1] neg_lo:[0,1] neg_hi:[0,1]
	v_pk_add_f32 v[26:27], v[26:27], v[0:1]
	v_pk_fma_f32 v[0:1], v[24:25], v[26:27], v[10:11] op_sel_hi:[0,1,1] neg_lo:[0,0,1] neg_hi:[0,0,1]
	v_cvt_pk_bf16_f32 v36, v0, v1
	v_lshlrev_b32_e32 v12, 16, v229
	v_and_b32_e32 v13, 0xffff0000, v229
	v_cndmask_b32_e32 v35, v221, v213, vcc
	v_lshlrev_b32_e32 v0, 16, v35
	v_and_b32_e32 v1, 0xffff0000, v35
	v_pk_add_f32 v[0:1], v[12:13], v[0:1] neg_lo:[0,1] neg_hi:[0,1]
	v_pk_add_f32 v[28:29], v[28:29], v[0:1]
	v_pk_fma_f32 v[0:1], v[24:25], v[28:29], v[12:13] op_sel_hi:[0,1,1] neg_lo:[0,0,1] neg_hi:[0,0,1]
	v_cvt_pk_bf16_f32 v37, v0, v1
	v_lshlrev_b32_e32 v14, 16, v230
	v_and_b32_e32 v15, 0xffff0000, v230
	v_cndmask_b32_e32 v35, v222, v214, vcc
	v_lshlrev_b32_e32 v0, 16, v35
	v_and_b32_e32 v1, 0xffff0000, v35
	v_pk_add_f32 v[0:1], v[14:15], v[0:1] neg_lo:[0,1] neg_hi:[0,1]
	v_pk_add_f32 v[30:31], v[30:31], v[0:1]
	v_pk_fma_f32 v[0:1], v[24:25], v[30:31], v[14:15] op_sel_hi:[0,1,1] neg_lo:[0,0,1] neg_hi:[0,0,1]
	v_cvt_pk_bf16_f32 v38, v0, v1
	v_lshlrev_b32_e32 v22, 16, v231
	v_and_b32_e32 v23, 0xffff0000, v231
	v_cndmask_b32_e32 v35, v223, v215, vcc
	v_lshlrev_b32_e32 v0, 16, v35
	v_and_b32_e32 v1, 0xffff0000, v35
	v_pk_add_f32 v[0:1], v[22:23], v[0:1] neg_lo:[0,1] neg_hi:[0,1]
	v_pk_add_f32 v[8:9], v[8:9], v[0:1]
	v_pk_fma_f32 v[0:1], v[24:25], v[8:9], v[22:23] op_sel_hi:[0,1,1] neg_lo:[0,0,1] neg_hi:[0,0,1]
	v_cvt_pk_bf16_f32 v39, v0, v1
	global_store_dwordx4 v[6:7], v[36:39], off offset:2048 nt
	s_branch .LBB0_930
; __device__ __forceinline__ unsigned cvtpk(float lo, float hi) { return pg8::cvt_pk_bf16(lo, hi); }
; __device__ __forceinline__ float bflo(unsigned u) { return __uint_as_float(u << 16); }
; __device__ __forceinline__ float bfhi(unsigned u) { return __uint_as_float(u & 0xffff0000u); }
; __device__ __forceinline__ void pool_pass(const bf16* __restrict__ U, bf16* __restrict__ Y, int gtid, int gthreads) {
;     ...
;         float sum[8];
; #pragma unroll
;         for (int j = 0; j < 8; ++j) sum[j] = 0.f;
;         for (int i = 1; i < w; ++i) { const int t = t0 - i; if (t >= 0) { const v4u v = *(const v4u*)(up + (size_t)t * 1024);
; #pragma unroll
;             for (int j = 0; j < 4; ++j) { sum[2 * j] += bflo(v[j]); sum[2 * j + 1] += bfhi(v[j]); } } }
; #pragma unroll 4
;         for (int t = t0; t < t0 + 32; ++t) {
;             const v4u v = *(const v4u*)(up + (size_t)t * 1024);
;             const int tb = t - w; v4u vb = {0u, 0u, 0u, 0u};
;             if (t > t0 && tb >= 0) vb = *(const v4u*)(up + (size_t)tb * 1024);
;             const float rc = 1.0f / (float)((t + 1 < w) ? (t + 1) : w);
;             v4u o;
; #pragma unroll
;             for (int j = 0; j < 4; ++j) { const float c0 = bflo(v[j]), c1 = bfhi(v[j]);
;                 sum[2 * j] += c0 - bflo(vb[j]); sum[2 * j + 1] += c1 - bfhi(vb[j]);
;                 o[j] = cvtpk(sum[2 * j] * rc - c0, sum[2 * j + 1] * rc - c1); }
;             __builtin_nontemporal_store(o, (v4u*)(yp + (size_t)t * 1024));
.Lp10_w8f:
	s_mov_b32 s2, 0xffff9800
	s_mov_b32 s3, -1
	v_lshl_add_u64 v[4:5], v[2:3], 0, s[2:3]
	v_lshl_add_u64 v[4:5], v[4:5], 0, s[16:17]
	v_lshl_add_u64 v[4:5], v[4:5], 0, s[16:17]
	v_lshl_add_u64 v[4:5], v[4:5], 0, s[16:17]
	global_load_dwordx4 v[100:103], v[4:5], off offset:2048
	v_lshl_add_u64 v[4:5], v[4:5], 0, s[16:17]
	global_load_dwordx4 v[104:107], v[4:5], off offset:-4096
	global_load_dwordx4 v[108:111], v[4:5], off offset:-2048
	global_load_dwordx4 v[112:115], v[4:5], off
	global_load_dwordx4 v[116:119], v[4:5], off offset:2048
	v_lshl_add_u64 v[4:5], v[4:5], 0, s[16:17]
	global_load_dwordx4 v[120:123], v[4:5], off offset:-4096
	global_load_dwordx4 v[124:127], v[4:5], off offset:-2048
	global_load_dwordx4 v[128:131], v[4:5], off
	global_load_dwordx4 v[132:135], v[4:5], off offset:2048
	v_lshl_add_u64 v[4:5], v[4:5], 0, s[16:17]
	global_load_dwordx4 v[136:139], v[4:5], off offset:-4096
	global_load_dwordx4 v[140:143], v[4:5], off offset:-2048
	global_load_dwordx4 v[144:147], v[4:5], off
	global_load_dwordx4 v[148:151], v[4:5], off offset:2048
	v_lshl_add_u64 v[4:5], v[4:5], 0, s[16:17]
	global_load_dwordx4 v[156:159], v[4:5], off offset:-4096
	global_load_dwordx4 v[160:163], v[4:5], off offset:-2048
	global_load_dwordx4 v[164:167], v[4:5], off
	global_load_dwordx4 v[168:171], v[4:5], off offset:2048
	v_lshl_add_u64 v[4:5], v[4:5], 0, s[16:17]
	global_load_dwordx4 v[172:175], v[4:5], off offset:-4096
	global_load_dwordx4 v[176:179], v[4:5], off offset:-2048
	global_load_dwordx4 v[180:183], v[4:5], off
	global_load_dwordx4 v[184:187], v[4:5], off offset:2048
	v_lshl_add_u64 v[4:5], v[4:5], 0, s[16:17]
	global_load_dwordx4 v[188:191], v[4:5], off offset:-4096
	global_load_dwordx4 v[192:195], v[4:5], off offset:-2048
	global_load_dwordx4 v[196:199], v[4:5], off
	global_load_dwordx4 v[200:203], v[4:5], off offset:2048
	v_lshl_add_u64 v[4:5], v[4:5], 0, s[16:17]
	global_load_dwordx4 v[204:207], v[4:5], off offset:-4096
	global_load_dwordx4 v[208:211], v[4:5], off offset:-2048
	global_load_dwordx4 v[212:215], v[4:5], off
	global_load_dwordx4 v[216:219], v[4:5], off offset:2048
	v_lshl_add_u64 v[4:5], v[4:5], 0, s[16:17]
	global_load_dwordx4 v[220:223], v[4:5], off offset:-4096
	global_load_dwordx4 v[224:227], v[4:5], off offset:-2048
	global_load_dwordx4 v[228:231], v[4:5], off
	s_mov_b32 s2, 0x8001000
	s_mov_b32 s3, 0
	v_lshl_add_u64 v[6:7], v[2:3], 0, s[2:3]
	v_mov_b32_e32 v26, 0
	v_mov_b32_e32 v27, 0
	v_mov_b32_e32 v28, 0
	v_mov_b32_e32 v29, 0
	v_mov_b32_e32 v30, 0
	v_mov_b32_e32 v31, 0
	v_mov_b32_e32 v8, 0
	v_mov_b32_e32 v9, 0
	v_mov_b32_e32 v96, 0
	v_mov_b32_e32 v97, 0
	v_mov_b32_e32 v98, 0
	v_mov_b32_e32 v99, 0
	v_mov_b32_e32 v92, 0
	v_mov_b32_e32 v93, 0
	v_mov_b32_e32 v94, 0
	v_mov_b32_e32 v95, 0
	v_mov_b32_e32 v88, 0
	v_mov_b32_e32 v89, 0
	v_mov_b32_e32 v90, 0
	v_mov_b32_e32 v91, 0
	v_mov_b32_e32 v84, 0
	v_mov_b32_e32 v85, 0
	v_mov_b32_e32 v86, 0
	v_mov_b32_e32 v87, 0
	v_mov_b32_e32 v80, 0
	v_mov_b32_e32 v81, 0
	v_mov_b32_e32 v82, 0
	v_mov_b32_e32 v83, 0
	v_mov_b32_e32 v76, 0
	v_mov_b32_e32 v77, 0
	v_mov_b32_e32 v78, 0
	v_mov_b32_e32 v79, 0
	v_mov_b32_e32 v72, 0
	v_mov_b32_e32 v73, 0
	v_mov_b32_e32 v74, 0
	v_mov_b32_e32 v75, 0
	v_mov_b32_e32 v68, 0
	v_mov_b32_e32 v69, 0
	v_mov_b32_e32 v70, 0
	v_mov_b32_e32 v71, 0
	v_mov_b32_e32 v64, 0
	v_mov_b32_e32 v65, 0
	v_mov_b32_e32 v66, 0
	v_mov_b32_e32 v67, 0
	v_mov_b32_e32 v60, 0
	v_mov_b32_e32 v61, 0
	v_mov_b32_e32 v62, 0
	v_mov_b32_e32 v63, 0
	v_mov_b32_e32 v56, 0
	v_mov_b32_e32 v57, 0
	v_mov_b32_e32 v58, 0
	v_mov_b32_e32 v59, 0
	v_mov_b32_e32 v52, 0
	v_mov_b32_e32 v53, 0
	v_mov_b32_e32 v54, 0
	v_mov_b32_e32 v55, 0
	v_mov_b32_e32 v48, 0
	v_mov_b32_e32 v49, 0
	v_mov_b32_e32 v50, 0
	v_mov_b32_e32 v51, 0
	v_mov_b32_e32 v44, 0
	v_mov_b32_e32 v45, 0
	v_mov_b32_e32 v46, 0
	v_mov_b32_e32 v47, 0
	v_mov_b32_e32 v40, 0
	v_mov_b32_e32 v41, 0
	v_mov_b32_e32 v42, 0
	v_mov_b32_e32 v43, 0
	s_mov_b64 exec, -1
	s_waitcnt vmcnt(31)
	v_mov_b32_e32 v24, 0x3f800000
	v_lshlrev_b32_e32 v10, 16, v100
	v_and_b32_e32 v11, 0xffff0000, v100
	v_pk_add_f32 v[26:27], v[26:27], v[10:11]
	v_pk_fma_f32 v[0:1], v[24:25], v[26:27], v[10:11] op_sel_hi:[0,1,1] neg_lo:[0,0,1] neg_hi:[0,0,1]
	v_cvt_pk_bf16_f32 v36, v0, v1
	v_lshlrev_b32_e32 v12, 16, v101
	v_and_b32_e32 v13, 0xffff0000, v101
	v_pk_add_f32 v[28:29], v[28:29], v[12:13]
	v_pk_fma_f32 v[0:1], v[24:25], v[28:29], v[12:13] op_sel_hi:[0,1,1] neg_lo:[0,0,1] neg_hi:[0,0,1]
	v_cvt_pk_bf16_f32 v37, v0, v1
	v_lshlrev_b32_e32 v14, 16, v102
	v_and_b32_e32 v15, 0xffff0000, v102
	v_pk_add_f32 v[30:31], v[30:31], v[14:15]
	v_pk_fma_f32 v[0:1], v[24:25], v[30:31], v[14:15] op_sel_hi:[0,1,1] neg_lo:[0,0,1] neg_hi:[0,0,1]
	v_cvt_pk_bf16_f32 v38, v0, v1
	v_lshlrev_b32_e32 v22, 16, v103
	v_and_b32_e32 v23, 0xffff0000, v103
	v_pk_add_f32 v[8:9], v[8:9], v[22:23]
	v_pk_fma_f32 v[0:1], v[24:25], v[8:9], v[22:23] op_sel_hi:[0,1,1] neg_lo:[0,0,1] neg_hi:[0,0,1]
	v_cvt_pk_bf16_f32 v39, v0, v1
	global_store_dwordx4 v[6:7], v[36:39], off offset:-4096 nt
	s_waitcnt vmcnt(31)
; __device__ __forceinline__ unsigned cvtpk(float lo, float hi) { return pg8::cvt_pk_bf16(lo, hi); }
; __device__ __forceinline__ float bflo(unsigned u) { return __uint_as_float(u << 16); }
; __device__ __forceinline__ float bfhi(unsigned u) { return __uint_as_float(u & 0xffff0000u); }
; __device__ __forceinline__ void pool_pass(const bf16* __restrict__ U, bf16* __restrict__ Y, int gtid, int gthreads) {
;     ...
;         for (int t = t0; t < t0 + 32; ++t) {
;             const v4u v = *(const v4u*)(up + (size_t)t * 1024);
;             const int tb = t - w; v4u vb = {0u, 0u, 0u, 0u};
;             if (t > t0 && tb >= 0) vb = *(const v4u*)(up + (size_t)tb * 1024);
;             const float rc = 1.0f / (float)((t + 1 < w) ? (t + 1) : w);
;             v4u o;
; #pragma unroll
;             for (int j = 0; j < 4; ++j) { const float c0 = bflo(v[j]), c1 = bfhi(v[j]);
;                 sum[2 * j] += c0 - bflo(vb[j]); sum[2 * j + 1] += c1 - bfhi(vb[j]);
;                 o[j] = cvtpk(sum[2 * j] * rc - c0, sum[2 * j + 1] * rc - c1); }
;             __builtin_nontemporal_store(o, (v4u*)(yp + (size_t)t * 1024));
	v_mov_b32_e32 v24, 0x3f000000
	v_lshlrev_b32_e32 v10, 16, v104
	v_and_b32_e32 v11, 0xffff0000, v104
	v_cndmask_b32_e32 v35, v72, v40, vcc
	v_lshlrev_b32_e32 v0, 16, v35
	v_and_b32_e32 v1, 0xffff0000, v35
	v_pk_add_f32 v[0:1], v[10:11], v[0:1] neg_lo:[0,1] neg_hi:[0,1]
	v_pk_add_f32 v[26:27], v[26:27], v[0:1]
	v_pk_fma_f32 v[0:1], v[24:25], v[26:27], v[10:11] op_sel_hi:[0,1,1] neg_lo:[0,0,1] neg_hi:[0,0,1]
	v_cvt_pk_bf16_f32 v36, v0, v1
	v_lshlrev_b32_e32 v12, 16, v105
	v_and_b32_e32 v13, 0xffff0000, v105
	v_cndmask_b32_e32 v35, v73, v41, vcc
	v_lshlrev_b32_e32 v0, 16, v35
	v_and_b32_e32 v1, 0xffff0000, v35
	v_pk_add_f32 v[0:1], v[12:13], v[0:1] neg_lo:[0,1] neg_hi:[0,1]
	v_pk_add_f32 v[28:29], v[28:29], v[0:1]
	v_pk_fma_f32 v[0:1], v[24:25], v[28:29], v[12:13] op_sel_hi:[0,1,1] neg_lo:[0,0,1] neg_hi:[0,0,1]
	v_cvt_pk_bf16_f32 v37, v0, v1
	v_lshlrev_b32_e32 v14, 16, v106
	v_and_b32_e32 v15, 0xffff0000, v106
	v_cndmask_b32_e32 v35, v74, v42, vcc
	v_lshlrev_b32_e32 v0, 16, v35
	v_and_b32_e32 v1, 0xffff0000, v35
	v_pk_add_f32 v[0:1], v[14:15], v[0:1] neg_lo:[0,1] neg_hi:[0,1]
	v_pk_add_f32 v[30:31], v[30:31], v[0:1]
	v_pk_fma_f32 v[0:1], v[24:25], v[30:31], v[14:15] op_sel_hi:[0,1,1] neg_lo:[0,0,1] neg_hi:[0,0,1]
	v_cvt_pk_bf16_f32 v38, v0, v1
	v_lshlrev_b32_e32 v22, 16, v107
	v_and_b32_e32 v23, 0xffff0000, v107
	v_cndmask_b32_e32 v35, v75, v43, vcc
	v_lshlrev_b32_e32 v0, 16, v35
	v_and_b32_e32 v1, 0xffff0000, v35
	v_pk_add_f32 v[0:1], v[22:23], v[0:1] neg_lo:[0,1] neg_hi:[0,1]
	v_pk_add_f32 v[8:9], v[8:9], v[0:1]
	v_pk_fma_f32 v[0:1], v[24:25], v[8:9], v[22:23] op_sel_hi:[0,1,1] neg_lo:[0,0,1] neg_hi:[0,0,1]
	v_cvt_pk_bf16_f32 v39, v0, v1
	global_store_dwordx4 v[6:7], v[36:39], off offset:-2048 nt
	s_waitcnt vmcnt(31)
	v_mov_b32_e32 v24, 0x3eaaaaab
	v_lshlrev_b32_e32 v10, 16, v108
	v_and_b32_e32 v11, 0xffff0000, v108
	v_cndmask_b32_e32 v35, v76, v44, vcc
	v_lshlrev_b32_e32 v0, 16, v35
	v_and_b32_e32 v1, 0xffff0000, v35
	v_pk_add_f32 v[0:1], v[10:11], v[0:1] neg_lo:[0,1] neg_hi:[0,1]
	v_pk_add_f32 v[26:27], v[26:27], v[0:1]
	v_pk_fma_f32 v[0:1], v[24:25], v[26:27], v[10:11] op_sel_hi:[0,1,1] neg_lo:[0,0,1] neg_hi:[0,0,1]
	v_cvt_pk_bf16_f32 v36, v0, v1
	v_lshlrev_b32_e32 v12, 16, v109
	v_and_b32_e32 v13, 0xffff0000, v109
	v_cndmask_b32_e32 v35, v77, v45, vcc
	v_lshlrev_b32_e32 v0, 16, v35
	v_and_b32_e32 v1, 0xffff0000, v35
	v_pk_add_f32 v[0:1], v[12:13], v[0:1] neg_lo:[0,1] neg_hi:[0,1]
	v_pk_add_f32 v[28:29], v[28:29], v[0:1]
	v_pk_fma_f32 v[0:1], v[24:25], v[28:29], v[12:13] op_sel_hi:[0,1,1] neg_lo:[0,0,1] neg_hi:[0,0,1]
	v_cvt_pk_bf16_f32 v37, v0, v1
	v_lshlrev_b32_e32 v14, 16, v110
	v_and_b32_e32 v15, 0xffff0000, v110
	v_cndmask_b32_e32 v35, v78, v46, vcc
	v_lshlrev_b32_e32 v0, 16, v35
	v_and_b32_e32 v1, 0xffff0000, v35
	v_pk_add_f32 v[0:1], v[14:15], v[0:1] neg_lo:[0,1] neg_hi:[0,1]
	v_pk_add_f32 v[30:31], v[30:31], v[0:1]
	v_pk_fma_f32 v[0:1], v[24:25], v[30:31], v[14:15] op_sel_hi:[0,1,1] neg_lo:[0,0,1] neg_hi:[0,0,1]
	v_cvt_pk_bf16_f32 v38, v0, v1
	v_lshlrev_b32_e32 v22, 16, v111
	v_and_b32_e32 v23, 0xffff0000, v111
	v_cndmask_b32_e32 v35, v79, v47, vcc
	v_lshlrev_b32_e32 v0, 16, v35
	v_and_b32_e32 v1, 0xffff0000, v35
	v_pk_add_f32 v[0:1], v[22:23], v[0:1] neg_lo:[0,1] neg_hi:[0,1]
	v_pk_add_f32 v[8:9], v[8:9], v[0:1]
	v_pk_fma_f32 v[0:1], v[24:25], v[8:9], v[22:23] op_sel_hi:[0,1,1] neg_lo:[0,0,1] neg_hi:[0,0,1]
	v_cvt_pk_bf16_f32 v39, v0, v1
	global_store_dwordx4 v[6:7], v[36:39], off nt
	s_waitcnt vmcnt(31)
	v_mov_b32_e32 v24, 0x3e800000
	v_lshlrev_b32_e32 v10, 16, v112
	v_and_b32_e32 v11, 0xffff0000, v112
	v_cndmask_b32_e32 v35, v80, v48, vcc
	v_lshlrev_b32_e32 v0, 16, v35
	v_and_b32_e32 v1, 0xffff0000, v35
	v_pk_add_f32 v[0:1], v[10:11], v[0:1] neg_lo:[0,1] neg_hi:[0,1]
	v_pk_add_f32 v[26:27], v[26:27], v[0:1]
	v_pk_fma_f32 v[0:1], v[24:25], v[26:27], v[10:11] op_sel_hi:[0,1,1] neg_lo:[0,0,1] neg_hi:[0,0,1]
	v_cvt_pk_bf16_f32 v36, v0, v1
	v_lshlrev_b32_e32 v12, 16, v113
	v_and_b32_e32 v13, 0xffff0000, v113
	v_cndmask_b32_e32 v35, v81, v49, vcc
	v_lshlrev_b32_e32 v0, 16, v35
	v_and_b32_e32 v1, 0xffff0000, v35
	v_pk_add_f32 v[0:1], v[12:13], v[0:1] neg_lo:[0,1] neg_hi:[0,1]
	v_pk_add_f32 v[28:29], v[28:29], v[0:1]
	v_pk_fma_f32 v[0:1], v[24:25], v[28:29], v[12:13] op_sel_hi:[0,1,1] neg_lo:[0,0,1] neg_hi:[0,0,1]
	v_cvt_pk_bf16_f32 v37, v0, v1
	v_lshlrev_b32_e32 v14, 16, v114
	v_and_b32_e32 v15, 0xffff0000, v114
	v_cndmask_b32_e32 v35, v82, v50, vcc
	v_lshlrev_b32_e32 v0, 16, v35
	v_and_b32_e32 v1, 0xffff0000, v35
	v_pk_add_f32 v[0:1], v[14:15], v[0:1] neg_lo:[0,1] neg_hi:[0,1]
	v_pk_add_f32 v[30:31], v[30:31], v[0:1]
	v_pk_fma_f32 v[0:1], v[24:25], v[30:31], v[14:15] op_sel_hi:[0,1,1] neg_lo:[0,0,1] neg_hi:[0,0,1]
	v_cvt_pk_bf16_f32 v38, v0, v1
	v_lshlrev_b32_e32 v22, 16, v115
	v_and_b32_e32 v23, 0xffff0000, v115
	v_cndmask_b32_e32 v35, v83, v51, vcc
	v_lshlrev_b32_e32 v0, 16, v35
	v_and_b32_e32 v1, 0xffff0000, v35
	v_pk_add_f32 v[0:1], v[22:23], v[0:1] neg_lo:[0,1] neg_hi:[0,1]
	v_pk_add_f32 v[8:9], v[8:9], v[0:1]
	v_pk_fma_f32 v[0:1], v[24:25], v[8:9], v[22:23] op_sel_hi:[0,1,1] neg_lo:[0,0,1] neg_hi:[0,0,1]
	v_cvt_pk_bf16_f32 v39, v0, v1
	global_store_dwordx4 v[6:7], v[36:39], off offset:2048 nt
	s_waitcnt vmcnt(31)
; __device__ __forceinline__ unsigned cvtpk(float lo, float hi) { return pg8::cvt_pk_bf16(lo, hi); }
; __device__ __forceinline__ float bflo(unsigned u) { return __uint_as_float(u << 16); }
; __device__ __forceinline__ float bfhi(unsigned u) { return __uint_as_float(u & 0xffff0000u); }
; __device__ __forceinline__ void pool_pass(const bf16* __restrict__ U, bf16* __restrict__ Y, int gtid, int gthreads) {
;     ...
;         for (int t = t0; t < t0 + 32; ++t) {
;             const v4u v = *(const v4u*)(up + (size_t)t * 1024);
;             const int tb = t - w; v4u vb = {0u, 0u, 0u, 0u};
;             if (t > t0 && tb >= 0) vb = *(const v4u*)(up + (size_t)tb * 1024);
;             const float rc = 1.0f / (float)((t + 1 < w) ? (t + 1) : w);
;             v4u o;
; #pragma unroll
;             for (int j = 0; j < 4; ++j) { const float c0 = bflo(v[j]), c1 = bfhi(v[j]);
;                 sum[2 * j] += c0 - bflo(vb[j]); sum[2 * j + 1] += c1 - bfhi(vb[j]);
;                 o[j] = cvtpk(sum[2 * j] * rc - c0, sum[2 * j + 1] * rc - c1); }
;             __builtin_nontemporal_store(o, (v4u*)(yp + (size_t)t * 1024));
	v_mov_b32_e32 v24, 0x3e4ccccd
	v_lshlrev_b32_e32 v10, 16, v116
	v_and_b32_e32 v11, 0xffff0000, v116
	v_cndmask_b32_e32 v35, v84, v52, vcc
	v_lshlrev_b32_e32 v0, 16, v35
	v_and_b32_e32 v1, 0xffff0000, v35
	v_pk_add_f32 v[0:1], v[10:11], v[0:1] neg_lo:[0,1] neg_hi:[0,1]
	v_pk_add_f32 v[26:27], v[26:27], v[0:1]
	v_pk_fma_f32 v[0:1], v[24:25], v[26:27], v[10:11] op_sel_hi:[0,1,1] neg_lo:[0,0,1] neg_hi:[0,0,1]
	v_cvt_pk_bf16_f32 v36, v0, v1
	v_lshlrev_b32_e32 v12, 16, v117
	v_and_b32_e32 v13, 0xffff0000, v117
	v_cndmask_b32_e32 v35, v85, v53, vcc
	v_lshlrev_b32_e32 v0, 16, v35
	v_and_b32_e32 v1, 0xffff0000, v35
	v_pk_add_f32 v[0:1], v[12:13], v[0:1] neg_lo:[0,1] neg_hi:[0,1]
	v_pk_add_f32 v[28:29], v[28:29], v[0:1]
	v_pk_fma_f32 v[0:1], v[24:25], v[28:29], v[12:13] op_sel_hi:[0,1,1] neg_lo:[0,0,1] neg_hi:[0,0,1]
	v_cvt_pk_bf16_f32 v37, v0, v1
	v_lshlrev_b32_e32 v14, 16, v118
	v_and_b32_e32 v15, 0xffff0000, v118
	v_cndmask_b32_e32 v35, v86, v54, vcc
	v_lshlrev_b32_e32 v0, 16, v35
	v_and_b32_e32 v1, 0xffff0000, v35
	v_pk_add_f32 v[0:1], v[14:15], v[0:1] neg_lo:[0,1] neg_hi:[0,1]
	v_pk_add_f32 v[30:31], v[30:31], v[0:1]
	v_pk_fma_f32 v[0:1], v[24:25], v[30:31], v[14:15] op_sel_hi:[0,1,1] neg_lo:[0,0,1] neg_hi:[0,0,1]
	v_cvt_pk_bf16_f32 v38, v0, v1
	v_lshlrev_b32_e32 v22, 16, v119
	v_and_b32_e32 v23, 0xffff0000, v119
	v_cndmask_b32_e32 v35, v87, v55, vcc
	v_lshlrev_b32_e32 v0, 16, v35
	v_and_b32_e32 v1, 0xffff0000, v35
	v_pk_add_f32 v[0:1], v[22:23], v[0:1] neg_lo:[0,1] neg_hi:[0,1]
	v_pk_add_f32 v[8:9], v[8:9], v[0:1]
	v_pk_fma_f32 v[0:1], v[24:25], v[8:9], v[22:23] op_sel_hi:[0,1,1] neg_lo:[0,0,1] neg_hi:[0,0,1]
	v_cvt_pk_bf16_f32 v39, v0, v1
	v_lshl_add_u64 v[6:7], v[6:7], 0, s[16:17]
	global_store_dwordx4 v[6:7], v[36:39], off offset:-4096 nt
	s_waitcnt vmcnt(31)
	v_mov_b32_e32 v24, 0x3e2aaaab
	v_lshlrev_b32_e32 v10, 16, v120
	v_and_b32_e32 v11, 0xffff0000, v120
	v_cndmask_b32_e32 v35, v88, v56, vcc
	v_lshlrev_b32_e32 v0, 16, v35
	v_and_b32_e32 v1, 0xffff0000, v35
	v_pk_add_f32 v[0:1], v[10:11], v[0:1] neg_lo:[0,1] neg_hi:[0,1]
	v_pk_add_f32 v[26:27], v[26:27], v[0:1]
	v_pk_fma_f32 v[0:1], v[24:25], v[26:27], v[10:11] op_sel_hi:[0,1,1] neg_lo:[0,0,1] neg_hi:[0,0,1]
	v_cvt_pk_bf16_f32 v36, v0, v1
	v_lshlrev_b32_e32 v12, 16, v121
	v_and_b32_e32 v13, 0xffff0000, v121
	v_cndmask_b32_e32 v35, v89, v57, vcc
	v_lshlrev_b32_e32 v0, 16, v35
	v_and_b32_e32 v1, 0xffff0000, v35
	v_pk_add_f32 v[0:1], v[12:13], v[0:1] neg_lo:[0,1] neg_hi:[0,1]
	v_pk_add_f32 v[28:29], v[28:29], v[0:1]
	v_pk_fma_f32 v[0:1], v[24:25], v[28:29], v[12:13] op_sel_hi:[0,1,1] neg_lo:[0,0,1] neg_hi:[0,0,1]
	v_cvt_pk_bf16_f32 v37, v0, v1
	v_lshlrev_b32_e32 v14, 16, v122
	v_and_b32_e32 v15, 0xffff0000, v122
	v_cndmask_b32_e32 v35, v90, v58, vcc
	v_lshlrev_b32_e32 v0, 16, v35
	v_and_b32_e32 v1, 0xffff0000, v35
	v_pk_add_f32 v[0:1], v[14:15], v[0:1] neg_lo:[0,1] neg_hi:[0,1]
	v_pk_add_f32 v[30:31], v[30:31], v[0:1]
	v_pk_fma_f32 v[0:1], v[24:25], v[30:31], v[14:15] op_sel_hi:[0,1,1] neg_lo:[0,0,1] neg_hi:[0,0,1]
	v_cvt_pk_bf16_f32 v38, v0, v1
	v_lshlrev_b32_e32 v22, 16, v123
	v_and_b32_e32 v23, 0xffff0000, v123
	v_cndmask_b32_e32 v35, v91, v59, vcc
	v_lshlrev_b32_e32 v0, 16, v35
	v_and_b32_e32 v1, 0xffff0000, v35
	v_pk_add_f32 v[0:1], v[22:23], v[0:1] neg_lo:[0,1] neg_hi:[0,1]
	v_pk_add_f32 v[8:9], v[8:9], v[0:1]
	v_pk_fma_f32 v[0:1], v[24:25], v[8:9], v[22:23] op_sel_hi:[0,1,1] neg_lo:[0,0,1] neg_hi:[0,0,1]
	v_cvt_pk_bf16_f32 v39, v0, v1
	global_store_dwordx4 v[6:7], v[36:39], off offset:-2048 nt
	s_waitcnt vmcnt(31)
	v_mov_b32_e32 v24, 0x3e124925
	v_lshlrev_b32_e32 v10, 16, v124
	v_and_b32_e32 v11, 0xffff0000, v124
	v_cndmask_b32_e32 v35, v92, v60, vcc
	v_lshlrev_b32_e32 v0, 16, v35
	v_and_b32_e32 v1, 0xffff0000, v35
	v_pk_add_f32 v[0:1], v[10:11], v[0:1] neg_lo:[0,1] neg_hi:[0,1]
	v_pk_add_f32 v[26:27], v[26:27], v[0:1]
	v_pk_fma_f32 v[0:1], v[24:25], v[26:27], v[10:11] op_sel_hi:[0,1,1] neg_lo:[0,0,1] neg_hi:[0,0,1]
	v_cvt_pk_bf16_f32 v36, v0, v1
	v_lshlrev_b32_e32 v12, 16, v125
	v_and_b32_e32 v13, 0xffff0000, v125
	v_cndmask_b32_e32 v35, v93, v61, vcc
	v_lshlrev_b32_e32 v0, 16, v35
	v_and_b32_e32 v1, 0xffff0000, v35
	v_pk_add_f32 v[0:1], v[12:13], v[0:1] neg_lo:[0,1] neg_hi:[0,1]
	v_pk_add_f32 v[28:29], v[28:29], v[0:1]
	v_pk_fma_f32 v[0:1], v[24:25], v[28:29], v[12:13] op_sel_hi:[0,1,1] neg_lo:[0,0,1] neg_hi:[0,0,1]
	v_cvt_pk_bf16_f32 v37, v0, v1
	v_lshlrev_b32_e32 v14, 16, v126
	v_and_b32_e32 v15, 0xffff0000, v126
	v_cndmask_b32_e32 v35, v94, v62, vcc
	v_lshlrev_b32_e32 v0, 16, v35
	v_and_b32_e32 v1, 0xffff0000, v35
	v_pk_add_f32 v[0:1], v[14:15], v[0:1] neg_lo:[0,1] neg_hi:[0,1]
	v_pk_add_f32 v[30:31], v[30:31], v[0:1]
	v_pk_fma_f32 v[0:1], v[24:25], v[30:31], v[14:15] op_sel_hi:[0,1,1] neg_lo:[0,0,1] neg_hi:[0,0,1]
	v_cvt_pk_bf16_f32 v38, v0, v1
	v_lshlrev_b32_e32 v22, 16, v127
	v_and_b32_e32 v23, 0xffff0000, v127
	v_cndmask_b32_e32 v35, v95, v63, vcc
	v_lshlrev_b32_e32 v0, 16, v35
	v_and_b32_e32 v1, 0xffff0000, v35
	v_pk_add_f32 v[0:1], v[22:23], v[0:1] neg_lo:[0,1] neg_hi:[0,1]
	v_pk_add_f32 v[8:9], v[8:9], v[0:1]
	v_pk_fma_f32 v[0:1], v[24:25], v[8:9], v[22:23] op_sel_hi:[0,1,1] neg_lo:[0,0,1] neg_hi:[0,0,1]
	v_cvt_pk_bf16_f32 v39, v0, v1
	global_store_dwordx4 v[6:7], v[36:39], off nt
	s_waitcnt vmcnt(31)
; __device__ __forceinline__ unsigned cvtpk(float lo, float hi) { return pg8::cvt_pk_bf16(lo, hi); }
; __device__ __forceinline__ float bflo(unsigned u) { return __uint_as_float(u << 16); }
; __device__ __forceinline__ float bfhi(unsigned u) { return __uint_as_float(u & 0xffff0000u); }
; __device__ __forceinline__ void pool_pass(const bf16* __restrict__ U, bf16* __restrict__ Y, int gtid, int gthreads) {
;     ...
;         for (int t = t0; t < t0 + 32; ++t) {
;             const v4u v = *(const v4u*)(up + (size_t)t * 1024);
;             const int tb = t - w; v4u vb = {0u, 0u, 0u, 0u};
;             if (t > t0 && tb >= 0) vb = *(const v4u*)(up + (size_t)tb * 1024);
;             const float rc = 1.0f / (float)((t + 1 < w) ? (t + 1) : w);
;             v4u o;
; #pragma unroll
;             for (int j = 0; j < 4; ++j) { const float c0 = bflo(v[j]), c1 = bfhi(v[j]);
;                 sum[2 * j] += c0 - bflo(vb[j]); sum[2 * j + 1] += c1 - bfhi(vb[j]);
;                 o[j] = cvtpk(sum[2 * j] * rc - c0, sum[2 * j + 1] * rc - c1); }
;             __builtin_nontemporal_store(o, (v4u*)(yp + (size_t)t * 1024));
	v_mov_b32_e32 v24, 0x3e000000
	v_lshlrev_b32_e32 v10, 16, v128
	v_and_b32_e32 v11, 0xffff0000, v128
	v_cndmask_b32_e32 v35, v96, v64, vcc
	v_lshlrev_b32_e32 v0, 16, v35
	v_and_b32_e32 v1, 0xffff0000, v35
	v_pk_add_f32 v[0:1], v[10:11], v[0:1] neg_lo:[0,1] neg_hi:[0,1]
	v_pk_add_f32 v[26:27], v[26:27], v[0:1]
	v_pk_fma_f32 v[0:1], v[24:25], v[26:27], v[10:11] op_sel_hi:[0,1,1] neg_lo:[0,0,1] neg_hi:[0,0,1]
	v_cvt_pk_bf16_f32 v36, v0, v1
	v_lshlrev_b32_e32 v12, 16, v129
	v_and_b32_e32 v13, 0xffff0000, v129
	v_cndmask_b32_e32 v35, v97, v65, vcc
	v_lshlrev_b32_e32 v0, 16, v35
	v_and_b32_e32 v1, 0xffff0000, v35
	v_pk_add_f32 v[0:1], v[12:13], v[0:1] neg_lo:[0,1] neg_hi:[0,1]
	v_pk_add_f32 v[28:29], v[28:29], v[0:1]
	v_pk_fma_f32 v[0:1], v[24:25], v[28:29], v[12:13] op_sel_hi:[0,1,1] neg_lo:[0,0,1] neg_hi:[0,0,1]
	v_cvt_pk_bf16_f32 v37, v0, v1
	v_lshlrev_b32_e32 v14, 16, v130
	v_and_b32_e32 v15, 0xffff0000, v130
	v_cndmask_b32_e32 v35, v98, v66, vcc
	v_lshlrev_b32_e32 v0, 16, v35
	v_and_b32_e32 v1, 0xffff0000, v35
	v_pk_add_f32 v[0:1], v[14:15], v[0:1] neg_lo:[0,1] neg_hi:[0,1]
	v_pk_add_f32 v[30:31], v[30:31], v[0:1]
	v_pk_fma_f32 v[0:1], v[24:25], v[30:31], v[14:15] op_sel_hi:[0,1,1] neg_lo:[0,0,1] neg_hi:[0,0,1]
	v_cvt_pk_bf16_f32 v38, v0, v1
	v_lshlrev_b32_e32 v22, 16, v131
	v_and_b32_e32 v23, 0xffff0000, v131
	v_cndmask_b32_e32 v35, v99, v67, vcc
	v_lshlrev_b32_e32 v0, 16, v35
	v_and_b32_e32 v1, 0xffff0000, v35
	v_pk_add_f32 v[0:1], v[22:23], v[0:1] neg_lo:[0,1] neg_hi:[0,1]
	v_pk_add_f32 v[8:9], v[8:9], v[0:1]
	v_pk_fma_f32 v[0:1], v[24:25], v[8:9], v[22:23] op_sel_hi:[0,1,1] neg_lo:[0,0,1] neg_hi:[0,0,1]
	v_cvt_pk_bf16_f32 v39, v0, v1
	global_store_dwordx4 v[6:7], v[36:39], off offset:2048 nt
	s_waitcnt vmcnt(31)
	v_mov_b32_e32 v24, 0x3e000000
	s_mov_b64 exec, s[12:13]
	v_mov_b32_e32 v24, 0x3de38e39
	s_mov_b64 exec, -1
	v_lshlrev_b32_e32 v10, 16, v132
	v_and_b32_e32 v11, 0xffff0000, v132
	v_cndmask_b32_e32 v35, v100, v68, vcc
	v_lshlrev_b32_e32 v0, 16, v35
	v_and_b32_e32 v1, 0xffff0000, v35
	v_pk_add_f32 v[0:1], v[10:11], v[0:1] neg_lo:[0,1] neg_hi:[0,1]
	v_pk_add_f32 v[26:27], v[26:27], v[0:1]
	v_pk_fma_f32 v[0:1], v[24:25], v[26:27], v[10:11] op_sel_hi:[0,1,1] neg_lo:[0,0,1] neg_hi:[0,0,1]
	v_cvt_pk_bf16_f32 v36, v0, v1
	v_lshlrev_b32_e32 v12, 16, v133
	v_and_b32_e32 v13, 0xffff0000, v133
	v_cndmask_b32_e32 v35, v101, v69, vcc
	v_lshlrev_b32_e32 v0, 16, v35
	v_and_b32_e32 v1, 0xffff0000, v35
	v_pk_add_f32 v[0:1], v[12:13], v[0:1] neg_lo:[0,1] neg_hi:[0,1]
	v_pk_add_f32 v[28:29], v[28:29], v[0:1]
	v_pk_fma_f32 v[0:1], v[24:25], v[28:29], v[12:13] op_sel_hi:[0,1,1] neg_lo:[0,0,1] neg_hi:[0,0,1]
	v_cvt_pk_bf16_f32 v37, v0, v1
	v_lshlrev_b32_e32 v14, 16, v134
	v_and_b32_e32 v15, 0xffff0000, v134
	v_cndmask_b32_e32 v35, v102, v70, vcc
	v_lshlrev_b32_e32 v0, 16, v35
	v_and_b32_e32 v1, 0xffff0000, v35
	v_pk_add_f32 v[0:1], v[14:15], v[0:1] neg_lo:[0,1] neg_hi:[0,1]
	v_pk_add_f32 v[30:31], v[30:31], v[0:1]
	v_pk_fma_f32 v[0:1], v[24:25], v[30:31], v[14:15] op_sel_hi:[0,1,1] neg_lo:[0,0,1] neg_hi:[0,0,1]
	v_cvt_pk_bf16_f32 v38, v0, v1
	v_lshlrev_b32_e32 v22, 16, v135
	v_and_b32_e32 v23, 0xffff0000, v135
	v_cndmask_b32_e32 v35, v103, v71, vcc
	v_lshlrev_b32_e32 v0, 16, v35
	v_and_b32_e32 v1, 0xffff0000, v35
	v_pk_add_f32 v[0:1], v[22:23], v[0:1] neg_lo:[0,1] neg_hi:[0,1]
	v_pk_add_f32 v[8:9], v[8:9], v[0:1]
	v_pk_fma_f32 v[0:1], v[24:25], v[8:9], v[22:23] op_sel_hi:[0,1,1] neg_lo:[0,0,1] neg_hi:[0,0,1]
	v_cvt_pk_bf16_f32 v39, v0, v1
	v_lshl_add_u64 v[6:7], v[6:7], 0, s[16:17]
	global_store_dwordx4 v[6:7], v[36:39], off offset:-4096 nt
	s_waitcnt vmcnt(31)
	v_mov_b32_e32 v24, 0x3e000000
	s_mov_b64 exec, s[12:13]
	v_mov_b32_e32 v24, 0x3dcccccd
	s_mov_b64 exec, -1
	v_lshlrev_b32_e32 v10, 16, v136
	v_and_b32_e32 v11, 0xffff0000, v136
	v_cndmask_b32_e32 v35, v104, v72, vcc
	v_lshlrev_b32_e32 v0, 16, v35
	v_and_b32_e32 v1, 0xffff0000, v35
	v_pk_add_f32 v[0:1], v[10:11], v[0:1] neg_lo:[0,1] neg_hi:[0,1]
	v_pk_add_f32 v[26:27], v[26:27], v[0:1]
	v_pk_fma_f32 v[0:1], v[24:25], v[26:27], v[10:11] op_sel_hi:[0,1,1] neg_lo:[0,0,1] neg_hi:[0,0,1]
	v_cvt_pk_bf16_f32 v36, v0, v1
	v_lshlrev_b32_e32 v12, 16, v137
	v_and_b32_e32 v13, 0xffff0000, v137
	v_cndmask_b32_e32 v35, v105, v73, vcc
	v_lshlrev_b32_e32 v0, 16, v35
	v_and_b32_e32 v1, 0xffff0000, v35
	v_pk_add_f32 v[0:1], v[12:13], v[0:1] neg_lo:[0,1] neg_hi:[0,1]
	v_pk_add_f32 v[28:29], v[28:29], v[0:1]
	v_pk_fma_f32 v[0:1], v[24:25], v[28:29], v[12:13] op_sel_hi:[0,1,1] neg_lo:[0,0,1] neg_hi:[0,0,1]
	v_cvt_pk_bf16_f32 v37, v0, v1
	v_lshlrev_b32_e32 v14, 16, v138
	v_and_b32_e32 v15, 0xffff0000, v138
	v_cndmask_b32_e32 v35, v106, v74, vcc
	v_lshlrev_b32_e32 v0, 16, v35
	v_and_b32_e32 v1, 0xffff0000, v35
	v_pk_add_f32 v[0:1], v[14:15], v[0:1] neg_lo:[0,1] neg_hi:[0,1]
	v_pk_add_f32 v[30:31], v[30:31], v[0:1]
	v_pk_fma_f32 v[0:1], v[24:25], v[30:31], v[14:15] op_sel_hi:[0,1,1] neg_lo:[0,0,1] neg_hi:[0,0,1]
	v_cvt_pk_bf16_f32 v38, v0, v1
	v_lshlrev_b32_e32 v22, 16, v139
	v_and_b32_e32 v23, 0xffff0000, v139
	v_cndmask_b32_e32 v35, v107, v75, vcc
	v_lshlrev_b32_e32 v0, 16, v35
	v_and_b32_e32 v1, 0xffff0000, v35
	v_pk_add_f32 v[0:1], v[22:23], v[0:1] neg_lo:[0,1] neg_hi:[0,1]
	v_pk_add_f32 v[8:9], v[8:9], v[0:1]
	v_pk_fma_f32 v[0:1], v[24:25], v[8:9], v[22:23] op_sel_hi:[0,1,1] neg_lo:[0,0,1] neg_hi:[0,0,1]
	v_cvt_pk_bf16_f32 v39, v0, v1
	global_store_dwordx4 v[6:7], v[36:39], off offset:-2048 nt
	s_waitcnt vmcnt(31)
; __device__ __forceinline__ unsigned cvtpk(float lo, float hi) { return pg8::cvt_pk_bf16(lo, hi); }
; __device__ __forceinline__ float bflo(unsigned u) { return __uint_as_float(u << 16); }
; __device__ __forceinline__ float bfhi(unsigned u) { return __uint_as_float(u & 0xffff0000u); }
; __device__ __forceinline__ void pool_pass(const bf16* __restrict__ U, bf16* __restrict__ Y, int gtid, int gthreads) {
;     ...
;         for (int t = t0; t < t0 + 32; ++t) {
;             const v4u v = *(const v4u*)(up + (size_t)t * 1024);
;             const int tb = t - w; v4u vb = {0u, 0u, 0u, 0u};
;             if (t > t0 && tb >= 0) vb = *(const v4u*)(up + (size_t)tb * 1024);
;             const float rc = 1.0f / (float)((t + 1 < w) ? (t + 1) : w);
;             v4u o;
; #pragma unroll
;             for (int j = 0; j < 4; ++j) { const float c0 = bflo(v[j]), c1 = bfhi(v[j]);
;                 sum[2 * j] += c0 - bflo(vb[j]); sum[2 * j + 1] += c1 - bfhi(vb[j]);
;                 o[j] = cvtpk(sum[2 * j] * rc - c0, sum[2 * j + 1] * rc - c1); }
;             __builtin_nontemporal_store(o, (v4u*)(yp + (size_t)t * 1024));
	v_mov_b32_e32 v24, 0x3e000000
	s_mov_b64 exec, s[12:13]
	v_mov_b32_e32 v24, 0x3dba2e8c
	s_mov_b64 exec, -1
	v_lshlrev_b32_e32 v10, 16, v140
	v_and_b32_e32 v11, 0xffff0000, v140
	v_cndmask_b32_e32 v35, v108, v76, vcc
	v_lshlrev_b32_e32 v0, 16, v35
	v_and_b32_e32 v1, 0xffff0000, v35
	v_pk_add_f32 v[0:1], v[10:11], v[0:1] neg_lo:[0,1] neg_hi:[0,1]
	v_pk_add_f32 v[26:27], v[26:27], v[0:1]
	v_pk_fma_f32 v[0:1], v[24:25], v[26:27], v[10:11] op_sel_hi:[0,1,1] neg_lo:[0,0,1] neg_hi:[0,0,1]
	v_cvt_pk_bf16_f32 v36, v0, v1
	v_lshlrev_b32_e32 v12, 16, v141
	v_and_b32_e32 v13, 0xffff0000, v141
	v_cndmask_b32_e32 v35, v109, v77, vcc
	v_lshlrev_b32_e32 v0, 16, v35
	v_and_b32_e32 v1, 0xffff0000, v35
	v_pk_add_f32 v[0:1], v[12:13], v[0:1] neg_lo:[0,1] neg_hi:[0,1]
	v_pk_add_f32 v[28:29], v[28:29], v[0:1]
	v_pk_fma_f32 v[0:1], v[24:25], v[28:29], v[12:13] op_sel_hi:[0,1,1] neg_lo:[0,0,1] neg_hi:[0,0,1]
	v_cvt_pk_bf16_f32 v37, v0, v1
	v_lshlrev_b32_e32 v14, 16, v142
	v_and_b32_e32 v15, 0xffff0000, v142
	v_cndmask_b32_e32 v35, v110, v78, vcc
	v_lshlrev_b32_e32 v0, 16, v35
	v_and_b32_e32 v1, 0xffff0000, v35
	v_pk_add_f32 v[0:1], v[14:15], v[0:1] neg_lo:[0,1] neg_hi:[0,1]
	v_pk_add_f32 v[30:31], v[30:31], v[0:1]
	v_pk_fma_f32 v[0:1], v[24:25], v[30:31], v[14:15] op_sel_hi:[0,1,1] neg_lo:[0,0,1] neg_hi:[0,0,1]
	v_cvt_pk_bf16_f32 v38, v0, v1
	v_lshlrev_b32_e32 v22, 16, v143
	v_and_b32_e32 v23, 0xffff0000, v143
	v_cndmask_b32_e32 v35, v111, v79, vcc
	v_lshlrev_b32_e32 v0, 16, v35
	v_and_b32_e32 v1, 0xffff0000, v35
	v_pk_add_f32 v[0:1], v[22:23], v[0:1] neg_lo:[0,1] neg_hi:[0,1]
	v_pk_add_f32 v[8:9], v[8:9], v[0:1]
	v_pk_fma_f32 v[0:1], v[24:25], v[8:9], v[22:23] op_sel_hi:[0,1,1] neg_lo:[0,0,1] neg_hi:[0,0,1]
	v_cvt_pk_bf16_f32 v39, v0, v1
	global_store_dwordx4 v[6:7], v[36:39], off nt
	s_waitcnt vmcnt(31)
	v_mov_b32_e32 v24, 0x3e000000
	s_mov_b64 exec, s[12:13]
	v_mov_b32_e32 v24, 0x3daaaaab
	s_mov_b64 exec, -1
	v_lshlrev_b32_e32 v10, 16, v144
	v_and_b32_e32 v11, 0xffff0000, v144
	v_cndmask_b32_e32 v35, v112, v80, vcc
	v_lshlrev_b32_e32 v0, 16, v35
	v_and_b32_e32 v1, 0xffff0000, v35
	v_pk_add_f32 v[0:1], v[10:11], v[0:1] neg_lo:[0,1] neg_hi:[0,1]
	v_pk_add_f32 v[26:27], v[26:27], v[0:1]
	v_pk_fma_f32 v[0:1], v[24:25], v[26:27], v[10:11] op_sel_hi:[0,1,1] neg_lo:[0,0,1] neg_hi:[0,0,1]
	v_cvt_pk_bf16_f32 v36, v0, v1
	v_lshlrev_b32_e32 v12, 16, v145
	v_and_b32_e32 v13, 0xffff0000, v145
	v_cndmask_b32_e32 v35, v113, v81, vcc
	v_lshlrev_b32_e32 v0, 16, v35
	v_and_b32_e32 v1, 0xffff0000, v35
	v_pk_add_f32 v[0:1], v[12:13], v[0:1] neg_lo:[0,1] neg_hi:[0,1]
	v_pk_add_f32 v[28:29], v[28:29], v[0:1]
	v_pk_fma_f32 v[0:1], v[24:25], v[28:29], v[12:13] op_sel_hi:[0,1,1] neg_lo:[0,0,1] neg_hi:[0,0,1]
	v_cvt_pk_bf16_f32 v37, v0, v1
	v_lshlrev_b32_e32 v14, 16, v146
	v_and_b32_e32 v15, 0xffff0000, v146
	v_cndmask_b32_e32 v35, v114, v82, vcc
	v_lshlrev_b32_e32 v0, 16, v35
	v_and_b32_e32 v1, 0xffff0000, v35
	v_pk_add_f32 v[0:1], v[14:15], v[0:1] neg_lo:[0,1] neg_hi:[0,1]
	v_pk_add_f32 v[30:31], v[30:31], v[0:1]
	v_pk_fma_f32 v[0:1], v[24:25], v[30:31], v[14:15] op_sel_hi:[0,1,1] neg_lo:[0,0,1] neg_hi:[0,0,1]
	v_cvt_pk_bf16_f32 v38, v0, v1
	v_lshlrev_b32_e32 v22, 16, v147
	v_and_b32_e32 v23, 0xffff0000, v147
	v_cndmask_b32_e32 v35, v115, v83, vcc
	v_lshlrev_b32_e32 v0, 16, v35
	v_and_b32_e32 v1, 0xffff0000, v35
	v_pk_add_f32 v[0:1], v[22:23], v[0:1] neg_lo:[0,1] neg_hi:[0,1]
	v_pk_add_f32 v[8:9], v[8:9], v[0:1]
	v_pk_fma_f32 v[0:1], v[24:25], v[8:9], v[22:23] op_sel_hi:[0,1,1] neg_lo:[0,0,1] neg_hi:[0,0,1]
	v_cvt_pk_bf16_f32 v39, v0, v1
	global_store_dwordx4 v[6:7], v[36:39], off offset:2048 nt
	s_waitcnt vmcnt(31)
	v_mov_b32_e32 v24, 0x3e000000
	s_mov_b64 exec, s[12:13]
	v_mov_b32_e32 v24, 0x3d9d89d9
	s_mov_b64 exec, -1
	v_lshlrev_b32_e32 v10, 16, v148
	v_and_b32_e32 v11, 0xffff0000, v148
	v_cndmask_b32_e32 v35, v116, v84, vcc
	v_lshlrev_b32_e32 v0, 16, v35
	v_and_b32_e32 v1, 0xffff0000, v35
	v_pk_add_f32 v[0:1], v[10:11], v[0:1] neg_lo:[0,1] neg_hi:[0,1]
	v_pk_add_f32 v[26:27], v[26:27], v[0:1]
	v_pk_fma_f32 v[0:1], v[24:25], v[26:27], v[10:11] op_sel_hi:[0,1,1] neg_lo:[0,0,1] neg_hi:[0,0,1]
	v_cvt_pk_bf16_f32 v36, v0, v1
	v_lshlrev_b32_e32 v12, 16, v149
	v_and_b32_e32 v13, 0xffff0000, v149
	v_cndmask_b32_e32 v35, v117, v85, vcc
	v_lshlrev_b32_e32 v0, 16, v35
	v_and_b32_e32 v1, 0xffff0000, v35
	v_pk_add_f32 v[0:1], v[12:13], v[0:1] neg_lo:[0,1] neg_hi:[0,1]
	v_pk_add_f32 v[28:29], v[28:29], v[0:1]
	v_pk_fma_f32 v[0:1], v[24:25], v[28:29], v[12:13] op_sel_hi:[0,1,1] neg_lo:[0,0,1] neg_hi:[0,0,1]
	v_cvt_pk_bf16_f32 v37, v0, v1
	v_lshlrev_b32_e32 v14, 16, v150
	v_and_b32_e32 v15, 0xffff0000, v150
	v_cndmask_b32_e32 v35, v118, v86, vcc
	v_lshlrev_b32_e32 v0, 16, v35
	v_and_b32_e32 v1, 0xffff0000, v35
	v_pk_add_f32 v[0:1], v[14:15], v[0:1] neg_lo:[0,1] neg_hi:[0,1]
	v_pk_add_f32 v[30:31], v[30:31], v[0:1]
	v_pk_fma_f32 v[0:1], v[24:25], v[30:31], v[14:15] op_sel_hi:[0,1,1] neg_lo:[0,0,1] neg_hi:[0,0,1]
	v_cvt_pk_bf16_f32 v38, v0, v1
	v_lshlrev_b32_e32 v22, 16, v151
	v_and_b32_e32 v23, 0xffff0000, v151
	v_cndmask_b32_e32 v35, v119, v87, vcc
	v_lshlrev_b32_e32 v0, 16, v35
	v_and_b32_e32 v1, 0xffff0000, v35
	v_pk_add_f32 v[0:1], v[22:23], v[0:1] neg_lo:[0,1] neg_hi:[0,1]
	v_pk_add_f32 v[8:9], v[8:9], v[0:1]
	v_pk_fma_f32 v[0:1], v[24:25], v[8:9], v[22:23] op_sel_hi:[0,1,1] neg_lo:[0,0,1] neg_hi:[0,0,1]
	v_cvt_pk_bf16_f32 v39, v0, v1
	v_lshl_add_u64 v[6:7], v[6:7], 0, s[16:17]
	global_store_dwordx4 v[6:7], v[36:39], off offset:-4096 nt
	s_waitcnt vmcnt(31)
; __device__ __forceinline__ unsigned cvtpk(float lo, float hi) { return pg8::cvt_pk_bf16(lo, hi); }
; __device__ __forceinline__ float bflo(unsigned u) { return __uint_as_float(u << 16); }
; __device__ __forceinline__ float bfhi(unsigned u) { return __uint_as_float(u & 0xffff0000u); }
; __device__ __forceinline__ void pool_pass(const bf16* __restrict__ U, bf16* __restrict__ Y, int gtid, int gthreads) {
;     ...
;         for (int t = t0; t < t0 + 32; ++t) {
;             const v4u v = *(const v4u*)(up + (size_t)t * 1024);
;             const int tb = t - w; v4u vb = {0u, 0u, 0u, 0u};
;             if (t > t0 && tb >= 0) vb = *(const v4u*)(up + (size_t)tb * 1024);
;             const float rc = 1.0f / (float)((t + 1 < w) ? (t + 1) : w);
;             v4u o;
; #pragma unroll
;             for (int j = 0; j < 4; ++j) { const float c0 = bflo(v[j]), c1 = bfhi(v[j]);
;                 sum[2 * j] += c0 - bflo(vb[j]); sum[2 * j + 1] += c1 - bfhi(vb[j]);
;                 o[j] = cvtpk(sum[2 * j] * rc - c0, sum[2 * j + 1] * rc - c1); }
;             __builtin_nontemporal_store(o, (v4u*)(yp + (size_t)t * 1024));
	v_mov_b32_e32 v24, 0x3e000000
	s_mov_b64 exec, s[12:13]
	v_mov_b32_e32 v24, 0x3d924925
	s_mov_b64 exec, -1
	v_lshlrev_b32_e32 v10, 16, v156
	v_and_b32_e32 v11, 0xffff0000, v156
	v_cndmask_b32_e32 v35, v120, v88, vcc
	v_lshlrev_b32_e32 v0, 16, v35
	v_and_b32_e32 v1, 0xffff0000, v35
	v_pk_add_f32 v[0:1], v[10:11], v[0:1] neg_lo:[0,1] neg_hi:[0,1]
	v_pk_add_f32 v[26:27], v[26:27], v[0:1]
	v_pk_fma_f32 v[0:1], v[24:25], v[26:27], v[10:11] op_sel_hi:[0,1,1] neg_lo:[0,0,1] neg_hi:[0,0,1]
	v_cvt_pk_bf16_f32 v36, v0, v1
	v_lshlrev_b32_e32 v12, 16, v157
	v_and_b32_e32 v13, 0xffff0000, v157
	v_cndmask_b32_e32 v35, v121, v89, vcc
	v_lshlrev_b32_e32 v0, 16, v35
	v_and_b32_e32 v1, 0xffff0000, v35
	v_pk_add_f32 v[0:1], v[12:13], v[0:1] neg_lo:[0,1] neg_hi:[0,1]
	v_pk_add_f32 v[28:29], v[28:29], v[0:1]
	v_pk_fma_f32 v[0:1], v[24:25], v[28:29], v[12:13] op_sel_hi:[0,1,1] neg_lo:[0,0,1] neg_hi:[0,0,1]
	v_cvt_pk_bf16_f32 v37, v0, v1
	v_lshlrev_b32_e32 v14, 16, v158
	v_and_b32_e32 v15, 0xffff0000, v158
	v_cndmask_b32_e32 v35, v122, v90, vcc
	v_lshlrev_b32_e32 v0, 16, v35
	v_and_b32_e32 v1, 0xffff0000, v35
	v_pk_add_f32 v[0:1], v[14:15], v[0:1] neg_lo:[0,1] neg_hi:[0,1]
	v_pk_add_f32 v[30:31], v[30:31], v[0:1]
	v_pk_fma_f32 v[0:1], v[24:25], v[30:31], v[14:15] op_sel_hi:[0,1,1] neg_lo:[0,0,1] neg_hi:[0,0,1]
	v_cvt_pk_bf16_f32 v38, v0, v1
	v_lshlrev_b32_e32 v22, 16, v159
	v_and_b32_e32 v23, 0xffff0000, v159
	v_cndmask_b32_e32 v35, v123, v91, vcc
	v_lshlrev_b32_e32 v0, 16, v35
	v_and_b32_e32 v1, 0xffff0000, v35
	v_pk_add_f32 v[0:1], v[22:23], v[0:1] neg_lo:[0,1] neg_hi:[0,1]
	v_pk_add_f32 v[8:9], v[8:9], v[0:1]
	v_pk_fma_f32 v[0:1], v[24:25], v[8:9], v[22:23] op_sel_hi:[0,1,1] neg_lo:[0,0,1] neg_hi:[0,0,1]
	v_cvt_pk_bf16_f32 v39, v0, v1
	global_store_dwordx4 v[6:7], v[36:39], off offset:-2048 nt
	s_waitcnt vmcnt(31)
	v_mov_b32_e32 v24, 0x3e000000
	s_mov_b64 exec, s[12:13]
	v_mov_b32_e32 v24, 0x3d888889
	s_mov_b64 exec, -1
	v_lshlrev_b32_e32 v10, 16, v160
	v_and_b32_e32 v11, 0xffff0000, v160
	v_cndmask_b32_e32 v35, v124, v92, vcc
	v_lshlrev_b32_e32 v0, 16, v35
	v_and_b32_e32 v1, 0xffff0000, v35
	v_pk_add_f32 v[0:1], v[10:11], v[0:1] neg_lo:[0,1] neg_hi:[0,1]
	v_pk_add_f32 v[26:27], v[26:27], v[0:1]
	v_pk_fma_f32 v[0:1], v[24:25], v[26:27], v[10:11] op_sel_hi:[0,1,1] neg_lo:[0,0,1] neg_hi:[0,0,1]
	v_cvt_pk_bf16_f32 v36, v0, v1
	v_lshlrev_b32_e32 v12, 16, v161
	v_and_b32_e32 v13, 0xffff0000, v161
	v_cndmask_b32_e32 v35, v125, v93, vcc
	v_lshlrev_b32_e32 v0, 16, v35
	v_and_b32_e32 v1, 0xffff0000, v35
	v_pk_add_f32 v[0:1], v[12:13], v[0:1] neg_lo:[0,1] neg_hi:[0,1]
	v_pk_add_f32 v[28:29], v[28:29], v[0:1]
	v_pk_fma_f32 v[0:1], v[24:25], v[28:29], v[12:13] op_sel_hi:[0,1,1] neg_lo:[0,0,1] neg_hi:[0,0,1]
	v_cvt_pk_bf16_f32 v37, v0, v1
	v_lshlrev_b32_e32 v14, 16, v162
	v_and_b32_e32 v15, 0xffff0000, v162
	v_cndmask_b32_e32 v35, v126, v94, vcc
	v_lshlrev_b32_e32 v0, 16, v35
	v_and_b32_e32 v1, 0xffff0000, v35
	v_pk_add_f32 v[0:1], v[14:15], v[0:1] neg_lo:[0,1] neg_hi:[0,1]
	v_pk_add_f32 v[30:31], v[30:31], v[0:1]
	v_pk_fma_f32 v[0:1], v[24:25], v[30:31], v[14:15] op_sel_hi:[0,1,1] neg_lo:[0,0,1] neg_hi:[0,0,1]
	v_cvt_pk_bf16_f32 v38, v0, v1
	v_lshlrev_b32_e32 v22, 16, v163
	v_and_b32_e32 v23, 0xffff0000, v163
	v_cndmask_b32_e32 v35, v127, v95, vcc
	v_lshlrev_b32_e32 v0, 16, v35
	v_and_b32_e32 v1, 0xffff0000, v35
	v_pk_add_f32 v[0:1], v[22:23], v[0:1] neg_lo:[0,1] neg_hi:[0,1]
	v_pk_add_f32 v[8:9], v[8:9], v[0:1]
	v_pk_fma_f32 v[0:1], v[24:25], v[8:9], v[22:23] op_sel_hi:[0,1,1] neg_lo:[0,0,1] neg_hi:[0,0,1]
	v_cvt_pk_bf16_f32 v39, v0, v1
	global_store_dwordx4 v[6:7], v[36:39], off nt
	s_waitcnt vmcnt(31)
	v_mov_b32_e32 v24, 0x3e000000
	s_mov_b64 exec, s[12:13]
	v_mov_b32_e32 v24, 0x3d800000
	s_mov_b64 exec, -1
	v_lshlrev_b32_e32 v10, 16, v164
	v_and_b32_e32 v11, 0xffff0000, v164
	v_cndmask_b32_e32 v35, v128, v96, vcc
	v_lshlrev_b32_e32 v0, 16, v35
	v_and_b32_e32 v1, 0xffff0000, v35
	v_pk_add_f32 v[0:1], v[10:11], v[0:1] neg_lo:[0,1] neg_hi:[0,1]
	v_pk_add_f32 v[26:27], v[26:27], v[0:1]
	v_pk_fma_f32 v[0:1], v[24:25], v[26:27], v[10:11] op_sel_hi:[0,1,1] neg_lo:[0,0,1] neg_hi:[0,0,1]
	v_cvt_pk_bf16_f32 v36, v0, v1
	v_lshlrev_b32_e32 v12, 16, v165
	v_and_b32_e32 v13, 0xffff0000, v165
	v_cndmask_b32_e32 v35, v129, v97, vcc
	v_lshlrev_b32_e32 v0, 16, v35
	v_and_b32_e32 v1, 0xffff0000, v35
	v_pk_add_f32 v[0:1], v[12:13], v[0:1] neg_lo:[0,1] neg_hi:[0,1]
	v_pk_add_f32 v[28:29], v[28:29], v[0:1]
	v_pk_fma_f32 v[0:1], v[24:25], v[28:29], v[12:13] op_sel_hi:[0,1,1] neg_lo:[0,0,1] neg_hi:[0,0,1]
	v_cvt_pk_bf16_f32 v37, v0, v1
	v_lshlrev_b32_e32 v14, 16, v166
	v_and_b32_e32 v15, 0xffff0000, v166
	v_cndmask_b32_e32 v35, v130, v98, vcc
	v_lshlrev_b32_e32 v0, 16, v35
	v_and_b32_e32 v1, 0xffff0000, v35
	v_pk_add_f32 v[0:1], v[14:15], v[0:1] neg_lo:[0,1] neg_hi:[0,1]
	v_pk_add_f32 v[30:31], v[30:31], v[0:1]
	v_pk_fma_f32 v[0:1], v[24:25], v[30:31], v[14:15] op_sel_hi:[0,1,1] neg_lo:[0,0,1] neg_hi:[0,0,1]
	v_cvt_pk_bf16_f32 v38, v0, v1
	v_lshlrev_b32_e32 v22, 16, v167
	v_and_b32_e32 v23, 0xffff0000, v167
	v_cndmask_b32_e32 v35, v131, v99, vcc
	v_lshlrev_b32_e32 v0, 16, v35
	v_and_b32_e32 v1, 0xffff0000, v35
	v_pk_add_f32 v[0:1], v[22:23], v[0:1] neg_lo:[0,1] neg_hi:[0,1]
	v_pk_add_f32 v[8:9], v[8:9], v[0:1]
	v_pk_fma_f32 v[0:1], v[24:25], v[8:9], v[22:23] op_sel_hi:[0,1,1] neg_lo:[0,0,1] neg_hi:[0,0,1]
	v_cvt_pk_bf16_f32 v39, v0, v1
	global_store_dwordx4 v[6:7], v[36:39], off offset:2048 nt
	s_waitcnt vmcnt(31)
; __device__ __forceinline__ unsigned cvtpk(float lo, float hi) { return pg8::cvt_pk_bf16(lo, hi); }
; __device__ __forceinline__ float bflo(unsigned u) { return __uint_as_float(u << 16); }
; __device__ __forceinline__ float bfhi(unsigned u) { return __uint_as_float(u & 0xffff0000u); }
; __device__ __forceinline__ void pool_pass(const bf16* __restrict__ U, bf16* __restrict__ Y, int gtid, int gthreads) {
;     ...
;         for (int t = t0; t < t0 + 32; ++t) {
;             const v4u v = *(const v4u*)(up + (size_t)t * 1024);
;             const int tb = t - w; v4u vb = {0u, 0u, 0u, 0u};
;             if (t > t0 && tb >= 0) vb = *(const v4u*)(up + (size_t)tb * 1024);
;             const float rc = 1.0f / (float)((t + 1 < w) ? (t + 1) : w);
;             v4u o;
; #pragma unroll
;             for (int j = 0; j < 4; ++j) { const float c0 = bflo(v[j]), c1 = bfhi(v[j]);
;                 sum[2 * j] += c0 - bflo(vb[j]); sum[2 * j + 1] += c1 - bfhi(vb[j]);
;                 o[j] = cvtpk(sum[2 * j] * rc - c0, sum[2 * j + 1] * rc - c1); }
;             __builtin_nontemporal_store(o, (v4u*)(yp + (size_t)t * 1024));
	v_lshlrev_b32_e32 v10, 16, v168
	v_and_b32_e32 v11, 0xffff0000, v168
	v_cndmask_b32_e32 v35, v132, v100, vcc
	v_lshlrev_b32_e32 v0, 16, v35
	v_and_b32_e32 v1, 0xffff0000, v35
	v_pk_add_f32 v[0:1], v[10:11], v[0:1] neg_lo:[0,1] neg_hi:[0,1]
	v_pk_add_f32 v[26:27], v[26:27], v[0:1]
	v_pk_fma_f32 v[0:1], v[24:25], v[26:27], v[10:11] op_sel_hi:[0,1,1] neg_lo:[0,0,1] neg_hi:[0,0,1]
	v_cvt_pk_bf16_f32 v36, v0, v1
	v_lshlrev_b32_e32 v12, 16, v169
	v_and_b32_e32 v13, 0xffff0000, v169
	v_cndmask_b32_e32 v35, v133, v101, vcc
	v_lshlrev_b32_e32 v0, 16, v35
	v_and_b32_e32 v1, 0xffff0000, v35
	v_pk_add_f32 v[0:1], v[12:13], v[0:1] neg_lo:[0,1] neg_hi:[0,1]
	v_pk_add_f32 v[28:29], v[28:29], v[0:1]
	v_pk_fma_f32 v[0:1], v[24:25], v[28:29], v[12:13] op_sel_hi:[0,1,1] neg_lo:[0,0,1] neg_hi:[0,0,1]
	v_cvt_pk_bf16_f32 v37, v0, v1
	v_lshlrev_b32_e32 v14, 16, v170
	v_and_b32_e32 v15, 0xffff0000, v170
	v_cndmask_b32_e32 v35, v134, v102, vcc
	v_lshlrev_b32_e32 v0, 16, v35
	v_and_b32_e32 v1, 0xffff0000, v35
	v_pk_add_f32 v[0:1], v[14:15], v[0:1] neg_lo:[0,1] neg_hi:[0,1]
	v_pk_add_f32 v[30:31], v[30:31], v[0:1]
	v_pk_fma_f32 v[0:1], v[24:25], v[30:31], v[14:15] op_sel_hi:[0,1,1] neg_lo:[0,0,1] neg_hi:[0,0,1]
	v_cvt_pk_bf16_f32 v38, v0, v1
	v_lshlrev_b32_e32 v22, 16, v171
	v_and_b32_e32 v23, 0xffff0000, v171
	v_cndmask_b32_e32 v35, v135, v103, vcc
	v_lshlrev_b32_e32 v0, 16, v35
	v_and_b32_e32 v1, 0xffff0000, v35
	v_pk_add_f32 v[0:1], v[22:23], v[0:1] neg_lo:[0,1] neg_hi:[0,1]
	v_pk_add_f32 v[8:9], v[8:9], v[0:1]
	v_pk_fma_f32 v[0:1], v[24:25], v[8:9], v[22:23] op_sel_hi:[0,1,1] neg_lo:[0,0,1] neg_hi:[0,0,1]
	v_cvt_pk_bf16_f32 v39, v0, v1
	v_lshl_add_u64 v[6:7], v[6:7], 0, s[16:17]
	global_store_dwordx4 v[6:7], v[36:39], off offset:-4096 nt
	s_waitcnt vmcnt(31)
	v_lshlrev_b32_e32 v10, 16, v172
	v_and_b32_e32 v11, 0xffff0000, v172
	v_cndmask_b32_e32 v35, v136, v104, vcc
	v_lshlrev_b32_e32 v0, 16, v35
	v_and_b32_e32 v1, 0xffff0000, v35
	v_pk_add_f32 v[0:1], v[10:11], v[0:1] neg_lo:[0,1] neg_hi:[0,1]
	v_pk_add_f32 v[26:27], v[26:27], v[0:1]
	v_pk_fma_f32 v[0:1], v[24:25], v[26:27], v[10:11] op_sel_hi:[0,1,1] neg_lo:[0,0,1] neg_hi:[0,0,1]
	v_cvt_pk_bf16_f32 v36, v0, v1
	v_lshlrev_b32_e32 v12, 16, v173
	v_and_b32_e32 v13, 0xffff0000, v173
	v_cndmask_b32_e32 v35, v137, v105, vcc
	v_lshlrev_b32_e32 v0, 16, v35
	v_and_b32_e32 v1, 0xffff0000, v35
	v_pk_add_f32 v[0:1], v[12:13], v[0:1] neg_lo:[0,1] neg_hi:[0,1]
	v_pk_add_f32 v[28:29], v[28:29], v[0:1]
	v_pk_fma_f32 v[0:1], v[24:25], v[28:29], v[12:13] op_sel_hi:[0,1,1] neg_lo:[0,0,1] neg_hi:[0,0,1]
	v_cvt_pk_bf16_f32 v37, v0, v1
	v_lshlrev_b32_e32 v14, 16, v174
	v_and_b32_e32 v15, 0xffff0000, v174
	v_cndmask_b32_e32 v35, v138, v106, vcc
	v_lshlrev_b32_e32 v0, 16, v35
	v_and_b32_e32 v1, 0xffff0000, v35
	v_pk_add_f32 v[0:1], v[14:15], v[0:1] neg_lo:[0,1] neg_hi:[0,1]
	v_pk_add_f32 v[30:31], v[30:31], v[0:1]
	v_pk_fma_f32 v[0:1], v[24:25], v[30:31], v[14:15] op_sel_hi:[0,1,1] neg_lo:[0,0,1] neg_hi:[0,0,1]
	v_cvt_pk_bf16_f32 v38, v0, v1
	v_lshlrev_b32_e32 v22, 16, v175
	v_and_b32_e32 v23, 0xffff0000, v175
	v_cndmask_b32_e32 v35, v139, v107, vcc
	v_lshlrev_b32_e32 v0, 16, v35
	v_and_b32_e32 v1, 0xffff0000, v35
	v_pk_add_f32 v[0:1], v[22:23], v[0:1] neg_lo:[0,1] neg_hi:[0,1]
	v_pk_add_f32 v[8:9], v[8:9], v[0:1]
	v_pk_fma_f32 v[0:1], v[24:25], v[8:9], v[22:23] op_sel_hi:[0,1,1] neg_lo:[0,0,1] neg_hi:[0,0,1]
	v_cvt_pk_bf16_f32 v39, v0, v1
	global_store_dwordx4 v[6:7], v[36:39], off offset:-2048 nt
	s_waitcnt vmcnt(31)
	v_lshlrev_b32_e32 v10, 16, v176
	v_and_b32_e32 v11, 0xffff0000, v176
	v_cndmask_b32_e32 v35, v140, v108, vcc
	v_lshlrev_b32_e32 v0, 16, v35
	v_and_b32_e32 v1, 0xffff0000, v35
	v_pk_add_f32 v[0:1], v[10:11], v[0:1] neg_lo:[0,1] neg_hi:[0,1]
	v_pk_add_f32 v[26:27], v[26:27], v[0:1]
	v_pk_fma_f32 v[0:1], v[24:25], v[26:27], v[10:11] op_sel_hi:[0,1,1] neg_lo:[0,0,1] neg_hi:[0,0,1]
	v_cvt_pk_bf16_f32 v36, v0, v1
	v_lshlrev_b32_e32 v12, 16, v177
	v_and_b32_e32 v13, 0xffff0000, v177
	v_cndmask_b32_e32 v35, v141, v109, vcc
	v_lshlrev_b32_e32 v0, 16, v35
	v_and_b32_e32 v1, 0xffff0000, v35
	v_pk_add_f32 v[0:1], v[12:13], v[0:1] neg_lo:[0,1] neg_hi:[0,1]
	v_pk_add_f32 v[28:29], v[28:29], v[0:1]
	v_pk_fma_f32 v[0:1], v[24:25], v[28:29], v[12:13] op_sel_hi:[0,1,1] neg_lo:[0,0,1] neg_hi:[0,0,1]
	v_cvt_pk_bf16_f32 v37, v0, v1
	v_lshlrev_b32_e32 v14, 16, v178
	v_and_b32_e32 v15, 0xffff0000, v178
	v_cndmask_b32_e32 v35, v142, v110, vcc
	v_lshlrev_b32_e32 v0, 16, v35
	v_and_b32_e32 v1, 0xffff0000, v35
	v_pk_add_f32 v[0:1], v[14:15], v[0:1] neg_lo:[0,1] neg_hi:[0,1]
	v_pk_add_f32 v[30:31], v[30:31], v[0:1]
	v_pk_fma_f32 v[0:1], v[24:25], v[30:31], v[14:15] op_sel_hi:[0,1,1] neg_lo:[0,0,1] neg_hi:[0,0,1]
	v_cvt_pk_bf16_f32 v38, v0, v1
	v_lshlrev_b32_e32 v22, 16, v179
	v_and_b32_e32 v23, 0xffff0000, v179
	v_cndmask_b32_e32 v35, v143, v111, vcc
	v_lshlrev_b32_e32 v0, 16, v35
	v_and_b32_e32 v1, 0xffff0000, v35
	v_pk_add_f32 v[0:1], v[22:23], v[0:1] neg_lo:[0,1] neg_hi:[0,1]
	v_pk_add_f32 v[8:9], v[8:9], v[0:1]
	v_pk_fma_f32 v[0:1], v[24:25], v[8:9], v[22:23] op_sel_hi:[0,1,1] neg_lo:[0,0,1] neg_hi:[0,0,1]
	v_cvt_pk_bf16_f32 v39, v0, v1
	global_store_dwordx4 v[6:7], v[36:39], off nt
	s_waitcnt vmcnt(31)
; __device__ __forceinline__ unsigned cvtpk(float lo, float hi) { return pg8::cvt_pk_bf16(lo, hi); }
; __device__ __forceinline__ float bflo(unsigned u) { return __uint_as_float(u << 16); }
; __device__ __forceinline__ float bfhi(unsigned u) { return __uint_as_float(u & 0xffff0000u); }
; __device__ __forceinline__ void pool_pass(const bf16* __restrict__ U, bf16* __restrict__ Y, int gtid, int gthreads) {
;     ...
;         for (int t = t0; t < t0 + 32; ++t) {
;             const v4u v = *(const v4u*)(up + (size_t)t * 1024);
;             const int tb = t - w; v4u vb = {0u, 0u, 0u, 0u};
;             if (t > t0 && tb >= 0) vb = *(const v4u*)(up + (size_t)tb * 1024);
;             const float rc = 1.0f / (float)((t + 1 < w) ? (t + 1) : w);
;             v4u o;
; #pragma unroll
;             for (int j = 0; j < 4; ++j) { const float c0 = bflo(v[j]), c1 = bfhi(v[j]);
;                 sum[2 * j] += c0 - bflo(vb[j]); sum[2 * j + 1] += c1 - bfhi(vb[j]);
;                 o[j] = cvtpk(sum[2 * j] * rc - c0, sum[2 * j + 1] * rc - c1); }
;             __builtin_nontemporal_store(o, (v4u*)(yp + (size_t)t * 1024));
	v_lshlrev_b32_e32 v10, 16, v180
	v_and_b32_e32 v11, 0xffff0000, v180
	v_cndmask_b32_e32 v35, v144, v112, vcc
	v_lshlrev_b32_e32 v0, 16, v35
	v_and_b32_e32 v1, 0xffff0000, v35
	v_pk_add_f32 v[0:1], v[10:11], v[0:1] neg_lo:[0,1] neg_hi:[0,1]
	v_pk_add_f32 v[26:27], v[26:27], v[0:1]
	v_pk_fma_f32 v[0:1], v[24:25], v[26:27], v[10:11] op_sel_hi:[0,1,1] neg_lo:[0,0,1] neg_hi:[0,0,1]
	v_cvt_pk_bf16_f32 v36, v0, v1
	v_lshlrev_b32_e32 v12, 16, v181
	v_and_b32_e32 v13, 0xffff0000, v181
	v_cndmask_b32_e32 v35, v145, v113, vcc
	v_lshlrev_b32_e32 v0, 16, v35
	v_and_b32_e32 v1, 0xffff0000, v35
	v_pk_add_f32 v[0:1], v[12:13], v[0:1] neg_lo:[0,1] neg_hi:[0,1]
	v_pk_add_f32 v[28:29], v[28:29], v[0:1]
	v_pk_fma_f32 v[0:1], v[24:25], v[28:29], v[12:13] op_sel_hi:[0,1,1] neg_lo:[0,0,1] neg_hi:[0,0,1]
	v_cvt_pk_bf16_f32 v37, v0, v1
	v_lshlrev_b32_e32 v14, 16, v182
	v_and_b32_e32 v15, 0xffff0000, v182
	v_cndmask_b32_e32 v35, v146, v114, vcc
	v_lshlrev_b32_e32 v0, 16, v35
	v_and_b32_e32 v1, 0xffff0000, v35
	v_pk_add_f32 v[0:1], v[14:15], v[0:1] neg_lo:[0,1] neg_hi:[0,1]
	v_pk_add_f32 v[30:31], v[30:31], v[0:1]
	v_pk_fma_f32 v[0:1], v[24:25], v[30:31], v[14:15] op_sel_hi:[0,1,1] neg_lo:[0,0,1] neg_hi:[0,0,1]
	v_cvt_pk_bf16_f32 v38, v0, v1
	v_lshlrev_b32_e32 v22, 16, v183
	v_and_b32_e32 v23, 0xffff0000, v183
	v_cndmask_b32_e32 v35, v147, v115, vcc
	v_lshlrev_b32_e32 v0, 16, v35
	v_and_b32_e32 v1, 0xffff0000, v35
	v_pk_add_f32 v[0:1], v[22:23], v[0:1] neg_lo:[0,1] neg_hi:[0,1]
	v_pk_add_f32 v[8:9], v[8:9], v[0:1]
	v_pk_fma_f32 v[0:1], v[24:25], v[8:9], v[22:23] op_sel_hi:[0,1,1] neg_lo:[0,0,1] neg_hi:[0,0,1]
	v_cvt_pk_bf16_f32 v39, v0, v1
	global_store_dwordx4 v[6:7], v[36:39], off offset:2048 nt
	s_waitcnt vmcnt(31)
	v_lshlrev_b32_e32 v10, 16, v184
	v_and_b32_e32 v11, 0xffff0000, v184
	v_cndmask_b32_e32 v35, v148, v116, vcc
	v_lshlrev_b32_e32 v0, 16, v35
	v_and_b32_e32 v1, 0xffff0000, v35
	v_pk_add_f32 v[0:1], v[10:11], v[0:1] neg_lo:[0,1] neg_hi:[0,1]
	v_pk_add_f32 v[26:27], v[26:27], v[0:1]
	v_pk_fma_f32 v[0:1], v[24:25], v[26:27], v[10:11] op_sel_hi:[0,1,1] neg_lo:[0,0,1] neg_hi:[0,0,1]
	v_cvt_pk_bf16_f32 v36, v0, v1
	v_lshlrev_b32_e32 v12, 16, v185
	v_and_b32_e32 v13, 0xffff0000, v185
	v_cndmask_b32_e32 v35, v149, v117, vcc
	v_lshlrev_b32_e32 v0, 16, v35
	v_and_b32_e32 v1, 0xffff0000, v35
	v_pk_add_f32 v[0:1], v[12:13], v[0:1] neg_lo:[0,1] neg_hi:[0,1]
	v_pk_add_f32 v[28:29], v[28:29], v[0:1]
	v_pk_fma_f32 v[0:1], v[24:25], v[28:29], v[12:13] op_sel_hi:[0,1,1] neg_lo:[0,0,1] neg_hi:[0,0,1]
	v_cvt_pk_bf16_f32 v37, v0, v1
	v_lshlrev_b32_e32 v14, 16, v186
	v_and_b32_e32 v15, 0xffff0000, v186
	v_cndmask_b32_e32 v35, v150, v118, vcc
	v_lshlrev_b32_e32 v0, 16, v35
	v_and_b32_e32 v1, 0xffff0000, v35
	v_pk_add_f32 v[0:1], v[14:15], v[0:1] neg_lo:[0,1] neg_hi:[0,1]
	v_pk_add_f32 v[30:31], v[30:31], v[0:1]
	v_pk_fma_f32 v[0:1], v[24:25], v[30:31], v[14:15] op_sel_hi:[0,1,1] neg_lo:[0,0,1] neg_hi:[0,0,1]
	v_cvt_pk_bf16_f32 v38, v0, v1
	v_lshlrev_b32_e32 v22, 16, v187
	v_and_b32_e32 v23, 0xffff0000, v187
	v_cndmask_b32_e32 v35, v151, v119, vcc
	v_lshlrev_b32_e32 v0, 16, v35
	v_and_b32_e32 v1, 0xffff0000, v35
	v_pk_add_f32 v[0:1], v[22:23], v[0:1] neg_lo:[0,1] neg_hi:[0,1]
	v_pk_add_f32 v[8:9], v[8:9], v[0:1]
	v_pk_fma_f32 v[0:1], v[24:25], v[8:9], v[22:23] op_sel_hi:[0,1,1] neg_lo:[0,0,1] neg_hi:[0,0,1]
	v_cvt_pk_bf16_f32 v39, v0, v1
	v_lshl_add_u64 v[6:7], v[6:7], 0, s[16:17]
	global_store_dwordx4 v[6:7], v[36:39], off offset:-4096 nt
	s_waitcnt vmcnt(31)
	v_lshlrev_b32_e32 v10, 16, v188
	v_and_b32_e32 v11, 0xffff0000, v188
	v_cndmask_b32_e32 v35, v156, v120, vcc
	v_lshlrev_b32_e32 v0, 16, v35
	v_and_b32_e32 v1, 0xffff0000, v35
	v_pk_add_f32 v[0:1], v[10:11], v[0:1] neg_lo:[0,1] neg_hi:[0,1]
	v_pk_add_f32 v[26:27], v[26:27], v[0:1]
	v_pk_fma_f32 v[0:1], v[24:25], v[26:27], v[10:11] op_sel_hi:[0,1,1] neg_lo:[0,0,1] neg_hi:[0,0,1]
	v_cvt_pk_bf16_f32 v36, v0, v1
	v_lshlrev_b32_e32 v12, 16, v189
	v_and_b32_e32 v13, 0xffff0000, v189
	v_cndmask_b32_e32 v35, v157, v121, vcc
	v_lshlrev_b32_e32 v0, 16, v35
	v_and_b32_e32 v1, 0xffff0000, v35
	v_pk_add_f32 v[0:1], v[12:13], v[0:1] neg_lo:[0,1] neg_hi:[0,1]
	v_pk_add_f32 v[28:29], v[28:29], v[0:1]
	v_pk_fma_f32 v[0:1], v[24:25], v[28:29], v[12:13] op_sel_hi:[0,1,1] neg_lo:[0,0,1] neg_hi:[0,0,1]
	v_cvt_pk_bf16_f32 v37, v0, v1
	v_lshlrev_b32_e32 v14, 16, v190
	v_and_b32_e32 v15, 0xffff0000, v190
	v_cndmask_b32_e32 v35, v158, v122, vcc
	v_lshlrev_b32_e32 v0, 16, v35
	v_and_b32_e32 v1, 0xffff0000, v35
	v_pk_add_f32 v[0:1], v[14:15], v[0:1] neg_lo:[0,1] neg_hi:[0,1]
	v_pk_add_f32 v[30:31], v[30:31], v[0:1]
	v_pk_fma_f32 v[0:1], v[24:25], v[30:31], v[14:15] op_sel_hi:[0,1,1] neg_lo:[0,0,1] neg_hi:[0,0,1]
	v_cvt_pk_bf16_f32 v38, v0, v1
	v_lshlrev_b32_e32 v22, 16, v191
	v_and_b32_e32 v23, 0xffff0000, v191
	v_cndmask_b32_e32 v35, v159, v123, vcc
	v_lshlrev_b32_e32 v0, 16, v35
	v_and_b32_e32 v1, 0xffff0000, v35
	v_pk_add_f32 v[0:1], v[22:23], v[0:1] neg_lo:[0,1] neg_hi:[0,1]
	v_pk_add_f32 v[8:9], v[8:9], v[0:1]
	v_pk_fma_f32 v[0:1], v[24:25], v[8:9], v[22:23] op_sel_hi:[0,1,1] neg_lo:[0,0,1] neg_hi:[0,0,1]
	v_cvt_pk_bf16_f32 v39, v0, v1
	global_store_dwordx4 v[6:7], v[36:39], off offset:-2048 nt
	s_waitcnt vmcnt(31)
; __device__ __forceinline__ unsigned cvtpk(float lo, float hi) { return pg8::cvt_pk_bf16(lo, hi); }
; __device__ __forceinline__ float bflo(unsigned u) { return __uint_as_float(u << 16); }
; __device__ __forceinline__ float bfhi(unsigned u) { return __uint_as_float(u & 0xffff0000u); }
; __device__ __forceinline__ void pool_pass(const bf16* __restrict__ U, bf16* __restrict__ Y, int gtid, int gthreads) {
;     ...
;         for (int t = t0; t < t0 + 32; ++t) {
;             const v4u v = *(const v4u*)(up + (size_t)t * 1024);
;             const int tb = t - w; v4u vb = {0u, 0u, 0u, 0u};
;             if (t > t0 && tb >= 0) vb = *(const v4u*)(up + (size_t)tb * 1024);
;             const float rc = 1.0f / (float)((t + 1 < w) ? (t + 1) : w);
;             v4u o;
; #pragma unroll
;             for (int j = 0; j < 4; ++j) { const float c0 = bflo(v[j]), c1 = bfhi(v[j]);
;                 sum[2 * j] += c0 - bflo(vb[j]); sum[2 * j + 1] += c1 - bfhi(vb[j]);
;                 o[j] = cvtpk(sum[2 * j] * rc - c0, sum[2 * j + 1] * rc - c1); }
;             __builtin_nontemporal_store(o, (v4u*)(yp + (size_t)t * 1024));
	v_lshlrev_b32_e32 v10, 16, v192
	v_and_b32_e32 v11, 0xffff0000, v192
	v_cndmask_b32_e32 v35, v160, v124, vcc
	v_lshlrev_b32_e32 v0, 16, v35
	v_and_b32_e32 v1, 0xffff0000, v35
	v_pk_add_f32 v[0:1], v[10:11], v[0:1] neg_lo:[0,1] neg_hi:[0,1]
	v_pk_add_f32 v[26:27], v[26:27], v[0:1]
	v_pk_fma_f32 v[0:1], v[24:25], v[26:27], v[10:11] op_sel_hi:[0,1,1] neg_lo:[0,0,1] neg_hi:[0,0,1]
	v_cvt_pk_bf16_f32 v36, v0, v1
	v_lshlrev_b32_e32 v12, 16, v193
	v_and_b32_e32 v13, 0xffff0000, v193
	v_cndmask_b32_e32 v35, v161, v125, vcc
	v_lshlrev_b32_e32 v0, 16, v35
	v_and_b32_e32 v1, 0xffff0000, v35
	v_pk_add_f32 v[0:1], v[12:13], v[0:1] neg_lo:[0,1] neg_hi:[0,1]
	v_pk_add_f32 v[28:29], v[28:29], v[0:1]
	v_pk_fma_f32 v[0:1], v[24:25], v[28:29], v[12:13] op_sel_hi:[0,1,1] neg_lo:[0,0,1] neg_hi:[0,0,1]
	v_cvt_pk_bf16_f32 v37, v0, v1
	v_lshlrev_b32_e32 v14, 16, v194
	v_and_b32_e32 v15, 0xffff0000, v194
	v_cndmask_b32_e32 v35, v162, v126, vcc
	v_lshlrev_b32_e32 v0, 16, v35
	v_and_b32_e32 v1, 0xffff0000, v35
	v_pk_add_f32 v[0:1], v[14:15], v[0:1] neg_lo:[0,1] neg_hi:[0,1]
	v_pk_add_f32 v[30:31], v[30:31], v[0:1]
	v_pk_fma_f32 v[0:1], v[24:25], v[30:31], v[14:15] op_sel_hi:[0,1,1] neg_lo:[0,0,1] neg_hi:[0,0,1]
	v_cvt_pk_bf16_f32 v38, v0, v1
	v_lshlrev_b32_e32 v22, 16, v195
	v_and_b32_e32 v23, 0xffff0000, v195
	v_cndmask_b32_e32 v35, v163, v127, vcc
	v_lshlrev_b32_e32 v0, 16, v35
	v_and_b32_e32 v1, 0xffff0000, v35
	v_pk_add_f32 v[0:1], v[22:23], v[0:1] neg_lo:[0,1] neg_hi:[0,1]
	v_pk_add_f32 v[8:9], v[8:9], v[0:1]
	v_pk_fma_f32 v[0:1], v[24:25], v[8:9], v[22:23] op_sel_hi:[0,1,1] neg_lo:[0,0,1] neg_hi:[0,0,1]
	v_cvt_pk_bf16_f32 v39, v0, v1
	global_store_dwordx4 v[6:7], v[36:39], off nt
	s_waitcnt vmcnt(31)
	v_lshlrev_b32_e32 v10, 16, v196
	v_and_b32_e32 v11, 0xffff0000, v196
	v_cndmask_b32_e32 v35, v164, v128, vcc
	v_lshlrev_b32_e32 v0, 16, v35
	v_and_b32_e32 v1, 0xffff0000, v35
	v_pk_add_f32 v[0:1], v[10:11], v[0:1] neg_lo:[0,1] neg_hi:[0,1]
	v_pk_add_f32 v[26:27], v[26:27], v[0:1]
	v_pk_fma_f32 v[0:1], v[24:25], v[26:27], v[10:11] op_sel_hi:[0,1,1] neg_lo:[0,0,1] neg_hi:[0,0,1]
	v_cvt_pk_bf16_f32 v36, v0, v1
	v_lshlrev_b32_e32 v12, 16, v197
	v_and_b32_e32 v13, 0xffff0000, v197
	v_cndmask_b32_e32 v35, v165, v129, vcc
	v_lshlrev_b32_e32 v0, 16, v35
	v_and_b32_e32 v1, 0xffff0000, v35
	v_pk_add_f32 v[0:1], v[12:13], v[0:1] neg_lo:[0,1] neg_hi:[0,1]
	v_pk_add_f32 v[28:29], v[28:29], v[0:1]
	v_pk_fma_f32 v[0:1], v[24:25], v[28:29], v[12:13] op_sel_hi:[0,1,1] neg_lo:[0,0,1] neg_hi:[0,0,1]
	v_cvt_pk_bf16_f32 v37, v0, v1
	v_lshlrev_b32_e32 v14, 16, v198
	v_and_b32_e32 v15, 0xffff0000, v198
	v_cndmask_b32_e32 v35, v166, v130, vcc
	v_lshlrev_b32_e32 v0, 16, v35
	v_and_b32_e32 v1, 0xffff0000, v35
	v_pk_add_f32 v[0:1], v[14:15], v[0:1] neg_lo:[0,1] neg_hi:[0,1]
	v_pk_add_f32 v[30:31], v[30:31], v[0:1]
	v_pk_fma_f32 v[0:1], v[24:25], v[30:31], v[14:15] op_sel_hi:[0,1,1] neg_lo:[0,0,1] neg_hi:[0,0,1]
	v_cvt_pk_bf16_f32 v38, v0, v1
	v_lshlrev_b32_e32 v22, 16, v199
	v_and_b32_e32 v23, 0xffff0000, v199
	v_cndmask_b32_e32 v35, v167, v131, vcc
	v_lshlrev_b32_e32 v0, 16, v35
	v_and_b32_e32 v1, 0xffff0000, v35
	v_pk_add_f32 v[0:1], v[22:23], v[0:1] neg_lo:[0,1] neg_hi:[0,1]
	v_pk_add_f32 v[8:9], v[8:9], v[0:1]
	v_pk_fma_f32 v[0:1], v[24:25], v[8:9], v[22:23] op_sel_hi:[0,1,1] neg_lo:[0,0,1] neg_hi:[0,0,1]
	v_cvt_pk_bf16_f32 v39, v0, v1
	global_store_dwordx4 v[6:7], v[36:39], off offset:2048 nt
	s_waitcnt vmcnt(31)
	v_lshlrev_b32_e32 v10, 16, v200
	v_and_b32_e32 v11, 0xffff0000, v200
	v_cndmask_b32_e32 v35, v168, v132, vcc
	v_lshlrev_b32_e32 v0, 16, v35
	v_and_b32_e32 v1, 0xffff0000, v35
	v_pk_add_f32 v[0:1], v[10:11], v[0:1] neg_lo:[0,1] neg_hi:[0,1]
	v_pk_add_f32 v[26:27], v[26:27], v[0:1]
	v_pk_fma_f32 v[0:1], v[24:25], v[26:27], v[10:11] op_sel_hi:[0,1,1] neg_lo:[0,0,1] neg_hi:[0,0,1]
	v_cvt_pk_bf16_f32 v36, v0, v1
	v_lshlrev_b32_e32 v12, 16, v201
	v_and_b32_e32 v13, 0xffff0000, v201
	v_cndmask_b32_e32 v35, v169, v133, vcc
	v_lshlrev_b32_e32 v0, 16, v35
	v_and_b32_e32 v1, 0xffff0000, v35
	v_pk_add_f32 v[0:1], v[12:13], v[0:1] neg_lo:[0,1] neg_hi:[0,1]
	v_pk_add_f32 v[28:29], v[28:29], v[0:1]
	v_pk_fma_f32 v[0:1], v[24:25], v[28:29], v[12:13] op_sel_hi:[0,1,1] neg_lo:[0,0,1] neg_hi:[0,0,1]
	v_cvt_pk_bf16_f32 v37, v0, v1
	v_lshlrev_b32_e32 v14, 16, v202
	v_and_b32_e32 v15, 0xffff0000, v202
	v_cndmask_b32_e32 v35, v170, v134, vcc
	v_lshlrev_b32_e32 v0, 16, v35
	v_and_b32_e32 v1, 0xffff0000, v35
	v_pk_add_f32 v[0:1], v[14:15], v[0:1] neg_lo:[0,1] neg_hi:[0,1]
	v_pk_add_f32 v[30:31], v[30:31], v[0:1]
	v_pk_fma_f32 v[0:1], v[24:25], v[30:31], v[14:15] op_sel_hi:[0,1,1] neg_lo:[0,0,1] neg_hi:[0,0,1]
	v_cvt_pk_bf16_f32 v38, v0, v1
	v_lshlrev_b32_e32 v22, 16, v203
	v_and_b32_e32 v23, 0xffff0000, v203
	v_cndmask_b32_e32 v35, v171, v135, vcc
	v_lshlrev_b32_e32 v0, 16, v35
	v_and_b32_e32 v1, 0xffff0000, v35
	v_pk_add_f32 v[0:1], v[22:23], v[0:1] neg_lo:[0,1] neg_hi:[0,1]
	v_pk_add_f32 v[8:9], v[8:9], v[0:1]
	v_pk_fma_f32 v[0:1], v[24:25], v[8:9], v[22:23] op_sel_hi:[0,1,1] neg_lo:[0,0,1] neg_hi:[0,0,1]
	v_cvt_pk_bf16_f32 v39, v0, v1
	v_lshl_add_u64 v[6:7], v[6:7], 0, s[16:17]
	global_store_dwordx4 v[6:7], v[36:39], off offset:-4096 nt
	s_waitcnt vmcnt(31)
; __device__ __forceinline__ unsigned cvtpk(float lo, float hi) { return pg8::cvt_pk_bf16(lo, hi); }
; __device__ __forceinline__ float bflo(unsigned u) { return __uint_as_float(u << 16); }
; __device__ __forceinline__ float bfhi(unsigned u) { return __uint_as_float(u & 0xffff0000u); }
; __device__ __forceinline__ void pool_pass(const bf16* __restrict__ U, bf16* __restrict__ Y, int gtid, int gthreads) {
;     ...
;         for (int t = t0; t < t0 + 32; ++t) {
;             const v4u v = *(const v4u*)(up + (size_t)t * 1024);
;             const int tb = t - w; v4u vb = {0u, 0u, 0u, 0u};
;             if (t > t0 && tb >= 0) vb = *(const v4u*)(up + (size_t)tb * 1024);
;             const float rc = 1.0f / (float)((t + 1 < w) ? (t + 1) : w);
;             v4u o;
; #pragma unroll
;             for (int j = 0; j < 4; ++j) { const float c0 = bflo(v[j]), c1 = bfhi(v[j]);
;                 sum[2 * j] += c0 - bflo(vb[j]); sum[2 * j + 1] += c1 - bfhi(vb[j]);
;                 o[j] = cvtpk(sum[2 * j] * rc - c0, sum[2 * j + 1] * rc - c1); }
;             __builtin_nontemporal_store(o, (v4u*)(yp + (size_t)t * 1024));
	v_lshlrev_b32_e32 v10, 16, v204
	v_and_b32_e32 v11, 0xffff0000, v204
	v_cndmask_b32_e32 v35, v172, v136, vcc
	v_lshlrev_b32_e32 v0, 16, v35
	v_and_b32_e32 v1, 0xffff0000, v35
	v_pk_add_f32 v[0:1], v[10:11], v[0:1] neg_lo:[0,1] neg_hi:[0,1]
	v_pk_add_f32 v[26:27], v[26:27], v[0:1]
	v_pk_fma_f32 v[0:1], v[24:25], v[26:27], v[10:11] op_sel_hi:[0,1,1] neg_lo:[0,0,1] neg_hi:[0,0,1]
	v_cvt_pk_bf16_f32 v36, v0, v1
	v_lshlrev_b32_e32 v12, 16, v205
	v_and_b32_e32 v13, 0xffff0000, v205
	v_cndmask_b32_e32 v35, v173, v137, vcc
	v_lshlrev_b32_e32 v0, 16, v35
	v_and_b32_e32 v1, 0xffff0000, v35
	v_pk_add_f32 v[0:1], v[12:13], v[0:1] neg_lo:[0,1] neg_hi:[0,1]
	v_pk_add_f32 v[28:29], v[28:29], v[0:1]
	v_pk_fma_f32 v[0:1], v[24:25], v[28:29], v[12:13] op_sel_hi:[0,1,1] neg_lo:[0,0,1] neg_hi:[0,0,1]
	v_cvt_pk_bf16_f32 v37, v0, v1
	v_lshlrev_b32_e32 v14, 16, v206
	v_and_b32_e32 v15, 0xffff0000, v206
	v_cndmask_b32_e32 v35, v174, v138, vcc
	v_lshlrev_b32_e32 v0, 16, v35
	v_and_b32_e32 v1, 0xffff0000, v35
	v_pk_add_f32 v[0:1], v[14:15], v[0:1] neg_lo:[0,1] neg_hi:[0,1]
	v_pk_add_f32 v[30:31], v[30:31], v[0:1]
	v_pk_fma_f32 v[0:1], v[24:25], v[30:31], v[14:15] op_sel_hi:[0,1,1] neg_lo:[0,0,1] neg_hi:[0,0,1]
	v_cvt_pk_bf16_f32 v38, v0, v1
	v_lshlrev_b32_e32 v22, 16, v207
	v_and_b32_e32 v23, 0xffff0000, v207
	v_cndmask_b32_e32 v35, v175, v139, vcc
	v_lshlrev_b32_e32 v0, 16, v35
	v_and_b32_e32 v1, 0xffff0000, v35
	v_pk_add_f32 v[0:1], v[22:23], v[0:1] neg_lo:[0,1] neg_hi:[0,1]
	v_pk_add_f32 v[8:9], v[8:9], v[0:1]
	v_pk_fma_f32 v[0:1], v[24:25], v[8:9], v[22:23] op_sel_hi:[0,1,1] neg_lo:[0,0,1] neg_hi:[0,0,1]
	v_cvt_pk_bf16_f32 v39, v0, v1
	global_store_dwordx4 v[6:7], v[36:39], off offset:-2048 nt
	s_waitcnt vmcnt(31)
	v_lshlrev_b32_e32 v10, 16, v208
	v_and_b32_e32 v11, 0xffff0000, v208
	v_cndmask_b32_e32 v35, v176, v140, vcc
	v_lshlrev_b32_e32 v0, 16, v35
	v_and_b32_e32 v1, 0xffff0000, v35
	v_pk_add_f32 v[0:1], v[10:11], v[0:1] neg_lo:[0,1] neg_hi:[0,1]
	v_pk_add_f32 v[26:27], v[26:27], v[0:1]
	v_pk_fma_f32 v[0:1], v[24:25], v[26:27], v[10:11] op_sel_hi:[0,1,1] neg_lo:[0,0,1] neg_hi:[0,0,1]
	v_cvt_pk_bf16_f32 v36, v0, v1
	v_lshlrev_b32_e32 v12, 16, v209
	v_and_b32_e32 v13, 0xffff0000, v209
	v_cndmask_b32_e32 v35, v177, v141, vcc
	v_lshlrev_b32_e32 v0, 16, v35
	v_and_b32_e32 v1, 0xffff0000, v35
	v_pk_add_f32 v[0:1], v[12:13], v[0:1] neg_lo:[0,1] neg_hi:[0,1]
	v_pk_add_f32 v[28:29], v[28:29], v[0:1]
	v_pk_fma_f32 v[0:1], v[24:25], v[28:29], v[12:13] op_sel_hi:[0,1,1] neg_lo:[0,0,1] neg_hi:[0,0,1]
	v_cvt_pk_bf16_f32 v37, v0, v1
	v_lshlrev_b32_e32 v14, 16, v210
	v_and_b32_e32 v15, 0xffff0000, v210
	v_cndmask_b32_e32 v35, v178, v142, vcc
	v_lshlrev_b32_e32 v0, 16, v35
	v_and_b32_e32 v1, 0xffff0000, v35
	v_pk_add_f32 v[0:1], v[14:15], v[0:1] neg_lo:[0,1] neg_hi:[0,1]
	v_pk_add_f32 v[30:31], v[30:31], v[0:1]
	v_pk_fma_f32 v[0:1], v[24:25], v[30:31], v[14:15] op_sel_hi:[0,1,1] neg_lo:[0,0,1] neg_hi:[0,0,1]
	v_cvt_pk_bf16_f32 v38, v0, v1
	v_lshlrev_b32_e32 v22, 16, v211
	v_and_b32_e32 v23, 0xffff0000, v211
	v_cndmask_b32_e32 v35, v179, v143, vcc
	v_lshlrev_b32_e32 v0, 16, v35
	v_and_b32_e32 v1, 0xffff0000, v35
	v_pk_add_f32 v[0:1], v[22:23], v[0:1] neg_lo:[0,1] neg_hi:[0,1]
	v_pk_add_f32 v[8:9], v[8:9], v[0:1]
	v_pk_fma_f32 v[0:1], v[24:25], v[8:9], v[22:23] op_sel_hi:[0,1,1] neg_lo:[0,0,1] neg_hi:[0,0,1]
	v_cvt_pk_bf16_f32 v39, v0, v1
	global_store_dwordx4 v[6:7], v[36:39], off nt
	s_waitcnt vmcnt(31)
	v_lshlrev_b32_e32 v10, 16, v212
	v_and_b32_e32 v11, 0xffff0000, v212
	v_cndmask_b32_e32 v35, v180, v144, vcc
	v_lshlrev_b32_e32 v0, 16, v35
	v_and_b32_e32 v1, 0xffff0000, v35
	v_pk_add_f32 v[0:1], v[10:11], v[0:1] neg_lo:[0,1] neg_hi:[0,1]
	v_pk_add_f32 v[26:27], v[26:27], v[0:1]
	v_pk_fma_f32 v[0:1], v[24:25], v[26:27], v[10:11] op_sel_hi:[0,1,1] neg_lo:[0,0,1] neg_hi:[0,0,1]
	v_cvt_pk_bf16_f32 v36, v0, v1
	v_lshlrev_b32_e32 v12, 16, v213
	v_and_b32_e32 v13, 0xffff0000, v213
	v_cndmask_b32_e32 v35, v181, v145, vcc
	v_lshlrev_b32_e32 v0, 16, v35
	v_and_b32_e32 v1, 0xffff0000, v35
	v_pk_add_f32 v[0:1], v[12:13], v[0:1] neg_lo:[0,1] neg_hi:[0,1]
	v_pk_add_f32 v[28:29], v[28:29], v[0:1]
	v_pk_fma_f32 v[0:1], v[24:25], v[28:29], v[12:13] op_sel_hi:[0,1,1] neg_lo:[0,0,1] neg_hi:[0,0,1]
	v_cvt_pk_bf16_f32 v37, v0, v1
	v_lshlrev_b32_e32 v14, 16, v214
	v_and_b32_e32 v15, 0xffff0000, v214
	v_cndmask_b32_e32 v35, v182, v146, vcc
	v_lshlrev_b32_e32 v0, 16, v35
	v_and_b32_e32 v1, 0xffff0000, v35
	v_pk_add_f32 v[0:1], v[14:15], v[0:1] neg_lo:[0,1] neg_hi:[0,1]
	v_pk_add_f32 v[30:31], v[30:31], v[0:1]
	v_pk_fma_f32 v[0:1], v[24:25], v[30:31], v[14:15] op_sel_hi:[0,1,1] neg_lo:[0,0,1] neg_hi:[0,0,1]
	v_cvt_pk_bf16_f32 v38, v0, v1
	v_lshlrev_b32_e32 v22, 16, v215
	v_and_b32_e32 v23, 0xffff0000, v215
	v_cndmask_b32_e32 v35, v183, v147, vcc
	v_lshlrev_b32_e32 v0, 16, v35
	v_and_b32_e32 v1, 0xffff0000, v35
	v_pk_add_f32 v[0:1], v[22:23], v[0:1] neg_lo:[0,1] neg_hi:[0,1]
	v_pk_add_f32 v[8:9], v[8:9], v[0:1]
	v_pk_fma_f32 v[0:1], v[24:25], v[8:9], v[22:23] op_sel_hi:[0,1,1] neg_lo:[0,0,1] neg_hi:[0,0,1]
	v_cvt_pk_bf16_f32 v39, v0, v1
	global_store_dwordx4 v[6:7], v[36:39], off offset:2048 nt
	s_waitcnt vmcnt(31)
; __device__ __forceinline__ unsigned cvtpk(float lo, float hi) { return pg8::cvt_pk_bf16(lo, hi); }
; __device__ __forceinline__ float bflo(unsigned u) { return __uint_as_float(u << 16); }
; __device__ __forceinline__ float bfhi(unsigned u) { return __uint_as_float(u & 0xffff0000u); }
; __device__ __forceinline__ void pool_pass(const bf16* __restrict__ U, bf16* __restrict__ Y, int gtid, int gthreads) {
;     ...
;         for (int t = t0; t < t0 + 32; ++t) {
;             const v4u v = *(const v4u*)(up + (size_t)t * 1024);
;             const int tb = t - w; v4u vb = {0u, 0u, 0u, 0u};
;             if (t > t0 && tb >= 0) vb = *(const v4u*)(up + (size_t)tb * 1024);
;             const float rc = 1.0f / (float)((t + 1 < w) ? (t + 1) : w);
;             v4u o;
; #pragma unroll
;             for (int j = 0; j < 4; ++j) { const float c0 = bflo(v[j]), c1 = bfhi(v[j]);
;                 sum[2 * j] += c0 - bflo(vb[j]); sum[2 * j + 1] += c1 - bfhi(vb[j]);
;                 o[j] = cvtpk(sum[2 * j] * rc - c0, sum[2 * j + 1] * rc - c1); }
;             __builtin_nontemporal_store(o, (v4u*)(yp + (size_t)t * 1024));
	v_lshlrev_b32_e32 v10, 16, v216
	v_and_b32_e32 v11, 0xffff0000, v216
	v_cndmask_b32_e32 v35, v184, v148, vcc
	v_lshlrev_b32_e32 v0, 16, v35
	v_and_b32_e32 v1, 0xffff0000, v35
	v_pk_add_f32 v[0:1], v[10:11], v[0:1] neg_lo:[0,1] neg_hi:[0,1]
	v_pk_add_f32 v[26:27], v[26:27], v[0:1]
	v_pk_fma_f32 v[0:1], v[24:25], v[26:27], v[10:11] op_sel_hi:[0,1,1] neg_lo:[0,0,1] neg_hi:[0,0,1]
	v_cvt_pk_bf16_f32 v36, v0, v1
	v_lshlrev_b32_e32 v12, 16, v217
	v_and_b32_e32 v13, 0xffff0000, v217
	v_cndmask_b32_e32 v35, v185, v149, vcc
	v_lshlrev_b32_e32 v0, 16, v35
	v_and_b32_e32 v1, 0xffff0000, v35
	v_pk_add_f32 v[0:1], v[12:13], v[0:1] neg_lo:[0,1] neg_hi:[0,1]
	v_pk_add_f32 v[28:29], v[28:29], v[0:1]
	v_pk_fma_f32 v[0:1], v[24:25], v[28:29], v[12:13] op_sel_hi:[0,1,1] neg_lo:[0,0,1] neg_hi:[0,0,1]
	v_cvt_pk_bf16_f32 v37, v0, v1
	v_lshlrev_b32_e32 v14, 16, v218
	v_and_b32_e32 v15, 0xffff0000, v218
	v_cndmask_b32_e32 v35, v186, v150, vcc
	v_lshlrev_b32_e32 v0, 16, v35
	v_and_b32_e32 v1, 0xffff0000, v35
	v_pk_add_f32 v[0:1], v[14:15], v[0:1] neg_lo:[0,1] neg_hi:[0,1]
	v_pk_add_f32 v[30:31], v[30:31], v[0:1]
	v_pk_fma_f32 v[0:1], v[24:25], v[30:31], v[14:15] op_sel_hi:[0,1,1] neg_lo:[0,0,1] neg_hi:[0,0,1]
	v_cvt_pk_bf16_f32 v38, v0, v1
	v_lshlrev_b32_e32 v22, 16, v219
	v_and_b32_e32 v23, 0xffff0000, v219
	v_cndmask_b32_e32 v35, v187, v151, vcc
	v_lshlrev_b32_e32 v0, 16, v35
	v_and_b32_e32 v1, 0xffff0000, v35
	v_pk_add_f32 v[0:1], v[22:23], v[0:1] neg_lo:[0,1] neg_hi:[0,1]
	v_pk_add_f32 v[8:9], v[8:9], v[0:1]
	v_pk_fma_f32 v[0:1], v[24:25], v[8:9], v[22:23] op_sel_hi:[0,1,1] neg_lo:[0,0,1] neg_hi:[0,0,1]
	v_cvt_pk_bf16_f32 v39, v0, v1
	v_lshl_add_u64 v[6:7], v[6:7], 0, s[16:17]
	global_store_dwordx4 v[6:7], v[36:39], off offset:-4096 nt
	s_waitcnt vmcnt(31)
	v_lshlrev_b32_e32 v10, 16, v220
	v_and_b32_e32 v11, 0xffff0000, v220
	v_cndmask_b32_e32 v35, v188, v156, vcc
	v_lshlrev_b32_e32 v0, 16, v35
	v_and_b32_e32 v1, 0xffff0000, v35
	v_pk_add_f32 v[0:1], v[10:11], v[0:1] neg_lo:[0,1] neg_hi:[0,1]
	v_pk_add_f32 v[26:27], v[26:27], v[0:1]
	v_pk_fma_f32 v[0:1], v[24:25], v[26:27], v[10:11] op_sel_hi:[0,1,1] neg_lo:[0,0,1] neg_hi:[0,0,1]
	v_cvt_pk_bf16_f32 v36, v0, v1
	v_lshlrev_b32_e32 v12, 16, v221
	v_and_b32_e32 v13, 0xffff0000, v221
	v_cndmask_b32_e32 v35, v189, v157, vcc
	v_lshlrev_b32_e32 v0, 16, v35
	v_and_b32_e32 v1, 0xffff0000, v35
	v_pk_add_f32 v[0:1], v[12:13], v[0:1] neg_lo:[0,1] neg_hi:[0,1]
	v_pk_add_f32 v[28:29], v[28:29], v[0:1]
	v_pk_fma_f32 v[0:1], v[24:25], v[28:29], v[12:13] op_sel_hi:[0,1,1] neg_lo:[0,0,1] neg_hi:[0,0,1]
	v_cvt_pk_bf16_f32 v37, v0, v1
	v_lshlrev_b32_e32 v14, 16, v222
	v_and_b32_e32 v15, 0xffff0000, v222
	v_cndmask_b32_e32 v35, v190, v158, vcc
	v_lshlrev_b32_e32 v0, 16, v35
	v_and_b32_e32 v1, 0xffff0000, v35
	v_pk_add_f32 v[0:1], v[14:15], v[0:1] neg_lo:[0,1] neg_hi:[0,1]
	v_pk_add_f32 v[30:31], v[30:31], v[0:1]
	v_pk_fma_f32 v[0:1], v[24:25], v[30:31], v[14:15] op_sel_hi:[0,1,1] neg_lo:[0,0,1] neg_hi:[0,0,1]
	v_cvt_pk_bf16_f32 v38, v0, v1
	v_lshlrev_b32_e32 v22, 16, v223
	v_and_b32_e32 v23, 0xffff0000, v223
	v_cndmask_b32_e32 v35, v191, v159, vcc
	v_lshlrev_b32_e32 v0, 16, v35
	v_and_b32_e32 v1, 0xffff0000, v35
	v_pk_add_f32 v[0:1], v[22:23], v[0:1] neg_lo:[0,1] neg_hi:[0,1]
	v_pk_add_f32 v[8:9], v[8:9], v[0:1]
	v_pk_fma_f32 v[0:1], v[24:25], v[8:9], v[22:23] op_sel_hi:[0,1,1] neg_lo:[0,0,1] neg_hi:[0,0,1]
	v_cvt_pk_bf16_f32 v39, v0, v1
	global_store_dwordx4 v[6:7], v[36:39], off offset:-2048 nt
	s_waitcnt vmcnt(31)
	v_lshlrev_b32_e32 v10, 16, v224
	v_and_b32_e32 v11, 0xffff0000, v224
	v_cndmask_b32_e32 v35, v192, v160, vcc
	v_lshlrev_b32_e32 v0, 16, v35
	v_and_b32_e32 v1, 0xffff0000, v35
	v_pk_add_f32 v[0:1], v[10:11], v[0:1] neg_lo:[0,1] neg_hi:[0,1]
	v_pk_add_f32 v[26:27], v[26:27], v[0:1]
	v_pk_fma_f32 v[0:1], v[24:25], v[26:27], v[10:11] op_sel_hi:[0,1,1] neg_lo:[0,0,1] neg_hi:[0,0,1]
	v_cvt_pk_bf16_f32 v36, v0, v1
	v_lshlrev_b32_e32 v12, 16, v225
	v_and_b32_e32 v13, 0xffff0000, v225
	v_cndmask_b32_e32 v35, v193, v161, vcc
	v_lshlrev_b32_e32 v0, 16, v35
	v_and_b32_e32 v1, 0xffff0000, v35
	v_pk_add_f32 v[0:1], v[12:13], v[0:1] neg_lo:[0,1] neg_hi:[0,1]
	v_pk_add_f32 v[28:29], v[28:29], v[0:1]
	v_pk_fma_f32 v[0:1], v[24:25], v[28:29], v[12:13] op_sel_hi:[0,1,1] neg_lo:[0,0,1] neg_hi:[0,0,1]
	v_cvt_pk_bf16_f32 v37, v0, v1
	v_lshlrev_b32_e32 v14, 16, v226
	v_and_b32_e32 v15, 0xffff0000, v226
	v_cndmask_b32_e32 v35, v194, v162, vcc
	v_lshlrev_b32_e32 v0, 16, v35
	v_and_b32_e32 v1, 0xffff0000, v35
	v_pk_add_f32 v[0:1], v[14:15], v[0:1] neg_lo:[0,1] neg_hi:[0,1]
	v_pk_add_f32 v[30:31], v[30:31], v[0:1]
	v_pk_fma_f32 v[0:1], v[24:25], v[30:31], v[14:15] op_sel_hi:[0,1,1] neg_lo:[0,0,1] neg_hi:[0,0,1]
	v_cvt_pk_bf16_f32 v38, v0, v1
	v_lshlrev_b32_e32 v22, 16, v227
	v_and_b32_e32 v23, 0xffff0000, v227
	v_cndmask_b32_e32 v35, v195, v163, vcc
	v_lshlrev_b32_e32 v0, 16, v35
	v_and_b32_e32 v1, 0xffff0000, v35
	v_pk_add_f32 v[0:1], v[22:23], v[0:1] neg_lo:[0,1] neg_hi:[0,1]
	v_pk_add_f32 v[8:9], v[8:9], v[0:1]
	v_pk_fma_f32 v[0:1], v[24:25], v[8:9], v[22:23] op_sel_hi:[0,1,1] neg_lo:[0,0,1] neg_hi:[0,0,1]
	v_cvt_pk_bf16_f32 v39, v0, v1
	global_store_dwordx4 v[6:7], v[36:39], off nt
	s_waitcnt vmcnt(31)
	v_lshlrev_b32_e32 v10, 16, v228
	v_and_b32_e32 v11, 0xffff0000, v228
	v_cndmask_b32_e32 v35, v196, v164, vcc
	v_lshlrev_b32_e32 v0, 16, v35
	v_and_b32_e32 v1, 0xffff0000, v35
	v_pk_add_f32 v[0:1], v[10:11], v[0:1] neg_lo:[0,1] neg_hi:[0,1]
	v_pk_add_f32 v[26:27], v[26:27], v[0:1]
	v_pk_fma_f32 v[0:1], v[24:25], v[26:27], v[10:11] op_sel_hi:[0,1,1] neg_lo:[0,0,1] neg_hi:[0,0,1]
	v_cvt_pk_bf16_f32 v36, v0, v1
	v_lshlrev_b32_e32 v12, 16, v229
	v_and_b32_e32 v13, 0xffff0000, v229
	v_cndmask_b32_e32 v35, v197, v165, vcc
	v_lshlrev_b32_e32 v0, 16, v35
	v_and_b32_e32 v1, 0xffff0000, v35
	v_pk_add_f32 v[0:1], v[12:13], v[0:1] neg_lo:[0,1] neg_hi:[0,1]
	v_pk_add_f32 v[28:29], v[28:29], v[0:1]
	v_pk_fma_f32 v[0:1], v[24:25], v[28:29], v[12:13] op_sel_hi:[0,1,1] neg_lo:[0,0,1] neg_hi:[0,0,1]
	v_cvt_pk_bf16_f32 v37, v0, v1
	v_lshlrev_b32_e32 v14, 16, v230
	v_and_b32_e32 v15, 0xffff0000, v230
	v_cndmask_b32_e32 v35, v198, v166, vcc
	v_lshlrev_b32_e32 v0, 16, v35
	v_and_b32_e32 v1, 0xffff0000, v35
	v_pk_add_f32 v[0:1], v[14:15], v[0:1] neg_lo:[0,1] neg_hi:[0,1]
	v_pk_add_f32 v[30:31], v[30:31], v[0:1]
	v_pk_fma_f32 v[0:1], v[24:25], v[30:31], v[14:15] op_sel_hi:[0,1,1] neg_lo:[0,0,1] neg_hi:[0,0,1]
	v_cvt_pk_bf16_f32 v38, v0, v1
	v_lshlrev_b32_e32 v22, 16, v231
	v_and_b32_e32 v23, 0xffff0000, v231
	v_cndmask_b32_e32 v35, v199, v167, vcc
	v_lshlrev_b32_e32 v0, 16, v35
	v_and_b32_e32 v1, 0xffff0000, v35
	v_pk_add_f32 v[0:1], v[22:23], v[0:1] neg_lo:[0,1] neg_hi:[0,1]
	v_pk_add_f32 v[8:9], v[8:9], v[0:1]
	v_pk_fma_f32 v[0:1], v[24:25], v[8:9], v[22:23] op_sel_hi:[0,1,1] neg_lo:[0,0,1] neg_hi:[0,0,1]
	v_cvt_pk_bf16_f32 v39, v0, v1
	global_store_dwordx4 v[6:7], v[36:39], off offset:2048 nt
	s_branch .LBB0_930
